# P6 int8 operands (A8, WGU8) re-laid with 4224-byte padded row stride in d_out scratch (non power-of-2 stride)
# baseline (speedup 1.0000x reference)
; #define GAS __attribute__((address_space(1)))
; #define LAS __attribute__((address_space(3)))
; template <int MAP> __device__ __forceinline__ void quant_strip(const float* W, int N, unsigned char* W8, const float* gk, unsigned* cmax, LAS unsigned char* lds, int strip, int wave, int lane) {
;     LAS float* smax = (LAS float*)(lds + 8 * 16896);
;     const int n0 = 32 * strip, n4 = lane & 7, kr = lane >> 3;
;     f32x4 mx = (f32x4){0.f, 0.f, 0.f, 0.f};
; #pragma unroll 16
;     for (int i = 0; i < 64; ++i) { const int k = 512 * wave + 8 * i + kr; const f32x4 v = *(const GAS f32x4*)(W + (size_t)k * N + n0 + 4 * n4) * gk[k];
;         mx[0] = fmaxf(mx[0], fabsf(v[0])); mx[1] = fmaxf(mx[1], fabsf(v[1])); mx[2] = fmaxf(mx[2], fabsf(v[2])); mx[3] = fmaxf(mx[3], fabsf(v[3])); }
; #pragma unroll
;     for (int e = 0; e < 4; ++e) { mx[e] = fmaxf(mx[e], __shfl_xor(mx[e], 8)); mx[e] = fmaxf(mx[e], __shfl_xor(mx[e], 16)); mx[e] = fmaxf(mx[e], __shfl_xor(mx[e], 32)); }
;     if (kr == 0) *(LAS f32x4*)(smax + wave * 32 + 4 * n4) = mx;
;     __syncthreads();
;     if (wave == 0 && lane < 32) { float m = 0.f;
; #pragma unroll
;         for (int w = 0; w < 8; ++w) m = fmaxf(m, smax[w * 32 + lane]);
;         smax[256 + lane] = m; cmax[rowmap<MAP>(n0 + lane, 0)] = __float_as_uint(m); }
;     __syncthreads();
;     LAS float* qscr = (LAS float*)(lds + wave * 16896);
;     for (int kb = wave; kb < DM / 128; kb += 8) quant_item<MAP>(W, DM, N, W8, gk, cmax, qscr, kb * (N / 32) + strip, lane, smax + 256);
; __global__ void __launch_bounds__(NWAVES * 64, 2) fwd_kernel(Args args) {
;     ...
;     if (IN(3)) {
;         pg8::Gemm g{MIX, WOUT, DM, DM, DM, 1, 1 << 30, 0, 0, 0, 0, 0}; pg8::StaticOrder S; S.init(MTOK / 256, DM / 256, G, bx);
;         constexpr int I_Q8 = (DM / 128) * (FF / 32); const int hq = G >> 1;
;         if ((bx & 1) && hq > 0) { LAS float* qscr = (LAS float*)(lds + wave * 16896);
;             (void)qscr; for (int st = (bx >> 1); st < FF / 32; st += hq) quant_strip<2>(w_gate, FF, WGU8, g_ffn, cmaxU, lds, st, wave, lane);
.LBB0_762:
	v_readlane_b32 s36, v244, 2
	v_readlane_b32 s50, v244, 16
	v_readlane_b32 s51, v244, 17
	v_readlane_b32 s0, v244, 14
	v_readlane_b32 s1, v244, 15
	s_add_u32 s0, s0, 0x4800000
	s_addc_u32 s1, s1, 0
	s_add_u32 s52, s50, 0x2b500000
	v_readlane_b32 s37, v244, 3
	v_readlane_b32 s38, v244, 4
	v_readlane_b32 s39, v244, 5
	v_readlane_b32 s40, v244, 6
	v_readlane_b32 s41, v244, 7
	v_readlane_b32 s42, v244, 8
	v_readlane_b32 s43, v244, 9
	v_readlane_b32 s44, v244, 10
	v_readlane_b32 s45, v244, 11
	v_readlane_b32 s46, v244, 12
	v_readlane_b32 s47, v244, 13
	v_readlane_b32 s48, v244, 14
	v_readlane_b32 s49, v244, 15
	v_writelane_b32 v244, s0, 49
	s_addc_u32 s53, s51, 0
	s_nop 0
	v_writelane_b32 v244, s1, 50
	s_add_u32 s0, s50, 0x70000
	s_addc_u32 s1, s51, 0
	s_add_u32 s62, s50, 0x40000
	s_addc_u32 s63, s51, 0
	v_writelane_b32 v244, s0, 23
	s_cmp_lt_i32 s96, 4
	s_nop 0
	v_writelane_b32 v244, s1, 24
	s_cselect_b64 s[0:1], -1, 0
	s_cmp_gt_i32 s97, 3
	s_cselect_b64 s[2:3], -1, 0
	s_and_b64 s[0:1], s[0:1], s[2:3]
	s_andn2_b64 vcc, exec, s[0:1]
	s_cbranch_vccnz .LBB0_873
	s_ashr_i32 s23, s22, 1
	s_and_b32 s56, s16, 1
	s_cmp_eq_u32 s56, 0
	s_cselect_b64 s[0:1], -1, 0
	s_cmp_gt_i32 s23, 0
	s_cselect_b64 s[54:55], -1, 0
	s_cmp_lt_i32 s23, 1
	s_cselect_b64 s[2:3], -1, 0
	s_or_b64 s[0:1], s[0:1], s[2:3]
	s_and_b64 vcc, exec, s[0:1]
	s_cbranch_vccnz .LBB0_776
	s_ashr_i32 s14, s16, 1
	s_cmpk_gt_i32 s14, 0x157
	s_cbranch_scc1 .LBB0_775
	s_waitcnt vmcnt(47)
	v_lshlrev_b32_e32 v2, 4, v0
	v_readlane_b32 s36, v244, 2
	v_and_b32_e32 v2, 0x70, v2
	v_mov_b32_e32 v3, 0
	v_readlane_b32 s38, v244, 4
	v_readlane_b32 s39, v244, 5
	v_readlane_b32 s6, v244, 42
	s_lshl_b32 s0, s6, 7
	v_lshl_add_u64 v[4:5], s[38:39], 0, v[2:3]
	v_mbcnt_lo_u32_b32 v2, -1, 0
	v_mbcnt_hi_u32_b32 v2, -1, v2
	s_waitcnt vmcnt(46)
	v_and_b32_e32 v7, 64, v2
	v_xor_b32_e32 v6, 8, v2
	v_add_u32_e32 v7, 64, v7
	v_cmp_lt_i32_e32 vcc, v6, v7
	s_add_i32 s4, 0, 0x21000
	s_add_i32 s5, s4, s0
	v_cndmask_b32_e32 v6, v2, v6, vcc
	s_waitcnt vmcnt(41)
	v_lshlrev_b32_e32 v19, 2, v6
	v_xor_b32_e32 v6, 16, v2
	v_cmp_lt_i32_e32 vcc, v6, v7
	v_readlane_b32 s7, v244, 41
	v_and_b32_e32 v1, 63, v0
	v_cndmask_b32_e32 v6, v2, v6, vcc
	v_lshlrev_b32_e32 v20, 2, v6
	v_xor_b32_e32 v6, 32, v2
	v_cmp_lt_i32_e32 vcc, v6, v7
	s_cmp_lt_u32 s7, 64
	s_cselect_b64 s[0:1], -1, 0
	v_cndmask_b32_e32 v2, v2, v6, vcc
	v_cmp_gt_u32_e32 vcc, 32, v1
	s_and_b64 s[8:9], s[0:1], vcc
	s_cmpk_lt_u32 s7, 0x800
	s_mul_i32 s0, s6, 0x4200
	v_and_b32_e32 v8, 7, v0
	v_readlane_b32 s24, v244, 49
	v_bfe_u32 v18, v0, 3, 3
	v_lshlrev_b32_e32 v21, 2, v2
	s_cselect_b64 s[10:11], -1, 0
	s_add_i32 s0, s0, 0
	v_lshlrev_b32_e32 v2, 4, v8
	v_readlane_b32 s25, v244, 50
	v_lshl_add_u64 v[6:7], s[38:39], 0, v[2:3]
	v_add_u32_e32 v11, s0, v2
	v_mul_u32_u24_e32 v13, 0x840, v8
	v_lshl_add_u64 v[8:9], s[24:25], 0, v[2:3]
	v_lshlrev_b32_e32 v2, 2, v18
	v_lshlrev_b32_e32 v10, 4, v1
	v_mul_u32_u24_e32 v12, 0x84, v18
	s_waitcnt vmcnt(40)
	v_or_b32_e32 v23, 8, v18
	v_or_b32_e32 v24, 16, v18
	v_or_b32_e32 v25, 24, v18
	s_add_i32 s1, 0, 0x21400
	s_waitcnt vmcnt(39)
	v_add3_u32 v27, s0, v13, v2
	s_mul_i32 s0, s6, 0x158
	v_cmp_gt_u32_e64 s[2:3], 8, v1
	v_lshl_add_u32 v22, v1, 2, s4
	v_add_u32_e32 v26, s1, v2
	v_lshl_add_u32 v28, v23, 2, s1
	v_lshl_add_u32 v29, v24, 2, s1
	v_lshl_add_u32 v30, v25, 2, s1
	v_lshl_or_b32 v31, s6, 9, v18
	s_add_i32 s15, s6, -8
	s_add_i32 s17, s14, s0
	s_mov_b32 s19, 0xac00
	v_add_u32_e32 v32, s5, v10
	v_add_u32_e32 v33, v11, v12
	s_mov_b32 s24, 0x42fe0000
	s_mov_b32 s25, 0xc2fe0000
	s_mov_b32 s26, 0x40c0c00
	s_waitcnt vmcnt(38)
	v_mov_b32_e32 v34, 0x42fe0000
	v_readlane_b32 s37, v244, 3
	v_readlane_b32 s40, v244, 6
	v_readlane_b32 s41, v244, 7
	v_readlane_b32 s42, v244, 8
	v_readlane_b32 s43, v244, 9
	v_readlane_b32 s44, v244, 10
	v_readlane_b32 s45, v244, 11
	v_readlane_b32 s46, v244, 12
	v_readlane_b32 s47, v244, 13
	v_readlane_b32 s48, v244, 14
	v_readlane_b32 s49, v244, 15
	v_readlane_b32 s50, v244, 16
	v_readlane_b32 s51, v244, 17
	s_branch .LBB0_767

; #define GAS __attribute__((address_space(1)))
; #define LAS __attribute__((address_space(3)))
; #define LDS_WAIT() asm volatile("s_waitcnt lgkmcnt(0)" ::: "memory")
; __device__ __forceinline__ unsigned pack4_i8(int a, int b, int c, int d) { return (unsigned)(a & 0xff) | ((unsigned)(b & 0xff) << 8) | ((unsigned)(c & 0xff) << 16) | ((unsigned)d << 24); }
; __device__ __forceinline__ int quant_i8(float x, float inv) { return (int)fminf(fmaxf(__builtin_rintf(x * inv), -127.0f), 127.0f); }
; template <int MAP> __device__ __forceinline__ void quant_item(const float* W, int K, int N, unsigned char* W8, const float* gk, const unsigned* cmax, LAS float* scr, int item, int lane, const LAS float* lmax = nullptr) {
;     const int nblk = N / 32, kb = item / nblk, nb = item % nblk, k0 = 128 * kb, n0 = 32 * nb;
;     const int n4 = lane & 7, kr = lane >> 3;
;     f32x4 v[16];
; #pragma unroll
;     for (int i = 0; i < 16; ++i) v[i] = *(const GAS f32x4*)(W + (size_t)(k0 + 8 * i + kr) * N + n0 + 4 * n4);
; #pragma unroll
;     for (int i = 0; i < 16; ++i) v[i] = v[i] * (gk ? gk[k0 + 8 * i + kr] : 1.0f);
; #pragma unroll
;     for (int i = 0; i < 16; ++i) { LAS float* d = scr + (8 * i + kr) * 33 + 4 * n4; d[0] = v[i][0]; d[1] = v[i][1]; d[2] = v[i][2]; d[3] = v[i][3]; }
;     LDS_WAIT(); asm volatile("" ::: "memory");
;     const int c = lane & 7, nn = lane >> 3;
; #pragma unroll
;     for (int j = 0; j < 4; ++j) { const int n = nn + 8 * j, dr = rowmap<MAP>(n0 + n, 0); const float cm = lmax ? lmax[n] : __uint_as_float(__hip_atomic_load(cmax + dr, __ATOMIC_RELAXED, __HIP_MEMORY_SCOPE_AGENT)); const float inv = cm > 0.f ? 127.0f / cm : 0.f;
;         const LAS float* sp = scr + (16 * c) * 33 + n; int q[16];
; #pragma unroll
;         for (int t = 0; t < 16; ++t) q[t] = quant_i8(sp[t * 33], inv);
;         u32x4 o; o.x = pack4_i8(q[0], q[1], q[2], q[3]); o.y = pack4_i8(q[4], q[5], q[6], q[7]); o.z = pack4_i8(q[8], q[9], q[10], q[11]); o.w = pack4_i8(q[12], q[13], q[14], q[15]);
;         *(GAS u32x4*)(W8 + (size_t)dr * K + k0 + 16 * c) = o; }
.LBB0_774:
	s_mul_hi_i32 s0, s27, 0x2fa0be83
	s_lshr_b32 s1, s0, 31
	s_ashr_i32 s0, s0, 6
	s_add_i32 s0, s0, s1
	s_mul_i32 s1, s0, 0x158
	s_sub_i32 s5, s27, s1
	s_lshl_b32 s0, s0, 7
	s_lshl_b32 s4, s5, 5
	v_or_b32_e32 v10, s0, v18
	s_ashr_i32 s1, s0, 31
	s_lshl_b32 s6, s5, 6
	s_ashr_i32 s5, s4, 31
	v_ashrrev_i32_e32 v11, 31, v10
	v_or_b32_e32 v65, 24, v10
	v_or_b32_e32 v66, 32, v10
	v_or_b32_e32 v67, 40, v10
	v_or_b32_e32 v68, 48, v10
	v_or_b32_e32 v69, 56, v10
	v_or_b32_e32 v70, 64, v10
	v_or_b32_e32 v71, 0x48, v10
	v_or_b32_e32 v72, 0x50, v10
	v_or_b32_e32 v73, 0x58, v10
	v_or_b32_e32 v74, 0x60, v10
	v_or_b32_e32 v76, 0x68, v10
	v_or_b32_e32 v77, 0x70, v10
	v_lshl_add_u64 v[130:131], v[8:9], 0, s[0:1]
	s_and_b32 s0, s6, 0xffffff00
	s_and_b32 s1, s4, 0x60
	v_lshl_add_u64 v[14:15], s[4:5], 2, v[6:7]
	v_or_b32_e32 v16, 8, v10
	v_or_b32_e32 v17, 16, v10
	v_or_b32_e32 v80, 0x78, v10
	v_lshl_add_u64 v[12:13], v[10:11], 2, s[36:37]
	s_or_b32 s4, s1, s0
	v_mad_i64_i32 v[110:111], s[0:1], v65, s19, v[14:15]
	v_mad_i64_i32 v[106:107], s[0:1], v66, s19, v[14:15]
	v_mad_i64_i32 v[102:103], s[0:1], v67, s19, v[14:15]
	v_mad_i64_i32 v[98:99], s[0:1], v68, s19, v[14:15]
	v_mad_i64_i32 v[94:95], s[0:1], v69, s19, v[14:15]
	v_mad_i64_i32 v[90:91], s[0:1], v70, s19, v[14:15]
	v_mad_i64_i32 v[86:87], s[0:1], v71, s19, v[14:15]
	v_mad_i64_i32 v[82:83], s[0:1], v72, s19, v[14:15]
	v_mad_i64_i32 v[78:79], s[0:1], v73, s19, v[14:15]
	v_mad_i64_i32 v[74:75], s[0:1], v74, s19, v[14:15]
	v_mad_i64_i32 v[70:71], s[0:1], v76, s19, v[14:15]
	v_mad_i64_i32 v[66:67], s[0:1], v77, s19, v[14:15]
	global_load_dword v132, v[12:13], off
	global_load_dword v134, v[12:13], off offset:32
	global_load_dword v136, v[12:13], off offset:64
	global_load_dword v138, v[12:13], off offset:96
	global_load_dword v140, v[12:13], off offset:128
	global_load_dword v142, v[12:13], off offset:160
	global_load_dword v144, v[12:13], off offset:192
	global_load_dword v146, v[12:13], off offset:224
	global_load_dword v148, v[12:13], off offset:256
	global_load_dword v150, v[12:13], off offset:288
	global_load_dword v152, v[12:13], off offset:320
	global_load_dword v154, v[12:13], off offset:352
	global_load_dword v156, v[12:13], off offset:384
	global_load_dword v158, v[12:13], off offset:416
	global_load_dword v160, v[12:13], off offset:448
	global_load_dword v162, v[12:13], off offset:480
	v_mad_i64_i32 v[10:11], s[0:1], v10, s19, v[14:15]
	v_mad_i64_i32 v[12:13], s[0:1], v16, s19, v[14:15]
	v_mad_i64_i32 v[16:17], s[0:1], v17, s19, v[14:15]
	v_mad_i64_i32 v[14:15], s[0:1], v80, s19, v[14:15]
	global_load_dwordx4 v[66:69], v[66:67], off
	s_nop 0
	global_load_dwordx4 v[70:73], v[70:71], off
	s_nop 0
	global_load_dwordx4 v[74:77], v[74:75], off
	s_nop 0
	global_load_dwordx4 v[78:81], v[78:79], off
	s_nop 0
	global_load_dwordx4 v[82:85], v[82:83], off
	s_nop 0
	global_load_dwordx4 v[86:89], v[86:87], off
	s_nop 0
	global_load_dwordx4 v[90:93], v[90:91], off
	s_nop 0
	global_load_dwordx4 v[94:97], v[94:95], off
	s_nop 0
	global_load_dwordx4 v[98:101], v[98:99], off
	s_nop 0
	global_load_dwordx4 v[102:105], v[102:103], off
	s_nop 0
	global_load_dwordx4 v[106:109], v[106:107], off
	s_nop 0
	global_load_dwordx4 v[110:113], v[110:111], off
	s_nop 0
	global_load_dwordx4 v[114:117], v[16:17], off
	global_load_dwordx4 v[118:121], v[12:13], off
	global_load_dwordx4 v[122:125], v[10:11], off
	global_load_dwordx4 v[126:129], v[14:15], off
	v_add_u32_e32 v133, 0x600, v27
	v_add_u32_e32 v2, 0x420, v33
	v_add_u32_e32 v35, 0x428, v33
	v_add_u32_e32 v36, 0x840, v33
	v_add_u32_e32 v37, 0x848, v33
	v_add_u32_e32 v38, 0xc60, v33
	v_add_u32_e32 v39, 0xc68, v33
	v_add_u32_e32 v40, 0x1080, v33
	v_add_u32_e32 v41, 0x1088, v33
	v_add_u32_e32 v42, 0x14a0, v33
	v_add_u32_e32 v43, 0x14a8, v33
	v_add_u32_e32 v44, 0x18c0, v33
	v_add_u32_e32 v45, 0x18c8, v33
	v_add_u32_e32 v46, 0x1ce0, v33
	v_add_u32_e32 v47, 0x1ce8, v33
	v_add_u32_e32 v48, 0x2100, v33
	v_add_u32_e32 v49, 0x2108, v33
	v_add_u32_e32 v50, 0x2520, v33
	v_add_u32_e32 v51, 0x2528, v33
	v_add_u32_e32 v52, 0x2940, v33
	v_add_u32_e32 v53, 0x2948, v33
	v_add_u32_e32 v54, 0x2d60, v33
	v_add_u32_e32 v55, 0x2d68, v33
	v_add_u32_e32 v56, 0x3180, v33
	v_add_u32_e32 v57, 0x3188, v33
	v_add_u32_e32 v58, 0x35a0, v33
	v_add_u32_e32 v59, 0x35a8, v33
	v_add_u32_e32 v60, 0x39c0, v33
	v_add_u32_e32 v61, 0x39c8, v33
	v_add_u32_e32 v62, 0x3de0, v33
	v_add_u32_e32 v63, 0x3de8, v33
	v_add_u32_e32 v64, 0x400, v27
	v_or_b32_e32 v164, s4, v18
	v_or_b32_e32 v166, s4, v23
	v_or_b32_e32 v168, s4, v24
	v_or_b32_e32 v170, s4, v25
	v_ashrrev_i32_e32 v165, 31, v164
	v_ashrrev_i32_e32 v167, 31, v166
	v_mul_u32_u24_e32 v10, 0x1080, v164
	v_mov_b32_e32 v11, 0
	v_ashrrev_i32_e32 v169, 31, v168
	v_mul_u32_u24_e32 v12, 0x1080, v166
	v_mov_b32_e32 v13, 0
	v_lshl_add_u64 v[16:17], v[130:131], 0, v[10:11]
	v_ashrrev_i32_e32 v171, 31, v170
	v_mul_u32_u24_e32 v164, 0x1080, v168
	v_mov_b32_e32 v165, 0
	v_lshl_add_u64 v[14:15], v[130:131], 0, v[12:13]
	v_mul_u32_u24_e32 v166, 0x1080, v170
	v_mov_b32_e32 v167, 0
	v_lshl_add_u64 v[12:13], v[130:131], 0, v[164:165]
	v_lshl_add_u64 v[10:11], v[130:131], 0, v[166:167]
	s_add_i32 s28, s28, 8
	s_addk_i32 s27, 0xac0
	s_cmp_lt_u32 s28, 24
	s_waitcnt vmcnt(13)
	v_pk_mul_f32 v[76:77], v[76:77], v[156:157] op_sel_hi:[1,0]
	v_pk_mul_f32 v[72:73], v[72:73], v[158:159] op_sel_hi:[1,0]
	v_pk_mul_f32 v[68:69], v[68:69], v[160:161] op_sel_hi:[1,0]
	v_pk_mul_f32 v[66:67], v[66:67], v[160:161] op_sel_hi:[1,0]
	v_pk_mul_f32 v[70:71], v[70:71], v[158:159] op_sel_hi:[1,0]
	v_pk_mul_f32 v[74:75], v[74:75], v[156:157] op_sel_hi:[1,0]
	s_waitcnt vmcnt(12)
; #define LAS __attribute__((address_space(3)))
; #define LDS_WAIT() asm volatile("s_waitcnt lgkmcnt(0)" ::: "memory")
; template <int MAP> __device__ __forceinline__ void quant_item(const float* W, int K, int N, unsigned char* W8, const float* gk, const unsigned* cmax, LAS float* scr, int item, int lane, const LAS float* lmax = nullptr) {
;     ...
;     for (int i = 0; i < 16; ++i) v[i] = v[i] * (gk ? gk[k0 + 8 * i + kr] : 1.0f);
; #pragma unroll
;     for (int i = 0; i < 16; ++i) { LAS float* d = scr + (8 * i + kr) * 33 + 4 * n4; d[0] = v[i][0]; d[1] = v[i][1]; d[2] = v[i][2]; d[3] = v[i][3]; }
;     LDS_WAIT(); asm volatile("" ::: "memory");
;     const int c = lane & 7, nn = lane >> 3;
; #pragma unroll
;     for (int j = 0; j < 4; ++j) { const int n = nn + 8 * j, dr = rowmap<MAP>(n0 + n, 0); const float cm = lmax ? lmax[n] : __uint_as_float(__hip_atomic_load(cmax + dr, __ATOMIC_RELAXED, __HIP_MEMORY_SCOPE_AGENT)); const float inv = cm > 0.f ? 127.0f / cm : 0.f;
	v_pk_mul_f32 v[80:81], v[80:81], v[154:155] op_sel_hi:[1,0]
	v_pk_mul_f32 v[78:79], v[78:79], v[154:155] op_sel_hi:[1,0]
	s_waitcnt vmcnt(11)
	v_pk_mul_f32 v[84:85], v[84:85], v[152:153] op_sel_hi:[1,0]
	v_pk_mul_f32 v[82:83], v[82:83], v[152:153] op_sel_hi:[1,0]
	s_waitcnt vmcnt(10)
	v_pk_mul_f32 v[88:89], v[88:89], v[150:151] op_sel_hi:[1,0]
	s_waitcnt vmcnt(1)
	v_pk_mul_f32 v[122:123], v[122:123], v[132:133] op_sel_hi:[1,0]
	v_pk_mul_f32 v[86:87], v[86:87], v[150:151] op_sel_hi:[1,0]
	v_pk_mul_f32 v[92:93], v[92:93], v[148:149] op_sel_hi:[1,0]
	v_pk_mul_f32 v[90:91], v[90:91], v[148:149] op_sel_hi:[1,0]
	v_pk_mul_f32 v[96:97], v[96:97], v[146:147] op_sel_hi:[1,0]
	v_pk_mul_f32 v[94:95], v[94:95], v[146:147] op_sel_hi:[1,0]
	v_pk_mul_f32 v[100:101], v[100:101], v[144:145] op_sel_hi:[1,0]
	v_pk_mul_f32 v[98:99], v[98:99], v[144:145] op_sel_hi:[1,0]
	v_pk_mul_f32 v[104:105], v[104:105], v[142:143] op_sel_hi:[1,0]
	v_pk_mul_f32 v[102:103], v[102:103], v[142:143] op_sel_hi:[1,0]
	v_pk_mul_f32 v[108:109], v[108:109], v[140:141] op_sel_hi:[1,0]
	v_pk_mul_f32 v[106:107], v[106:107], v[140:141] op_sel_hi:[1,0]
	v_pk_mul_f32 v[112:113], v[112:113], v[138:139] op_sel_hi:[1,0]
	v_pk_mul_f32 v[110:111], v[110:111], v[138:139] op_sel_hi:[1,0]
	v_pk_mul_f32 v[116:117], v[116:117], v[136:137] op_sel_hi:[1,0]
	v_pk_mul_f32 v[114:115], v[114:115], v[136:137] op_sel_hi:[1,0]
	v_pk_mul_f32 v[120:121], v[120:121], v[134:135] op_sel_hi:[1,0]
	v_pk_mul_f32 v[118:119], v[118:119], v[134:135] op_sel_hi:[1,0]
	v_pk_mul_f32 v[124:125], v[124:125], v[132:133] op_sel_hi:[1,0]
	s_waitcnt vmcnt(0)
	v_pk_mul_f32 v[128:129], v[128:129], v[162:163] op_sel_hi:[1,0]
	v_pk_mul_f32 v[126:127], v[126:127], v[162:163] op_sel_hi:[1,0]
	ds_write2_b32 v33, v122, v123 offset1:1
	ds_write2_b32 v33, v124, v125 offset0:2 offset1:3
	ds_write2_b32 v2, v118, v119 offset1:1
	ds_write2_b32 v35, v120, v121 offset1:1
	ds_write2_b32 v36, v114, v115 offset1:1
	ds_write2_b32 v37, v116, v117 offset1:1
	ds_write2_b32 v38, v110, v111 offset1:1
	ds_write2_b32 v39, v112, v113 offset1:1
	ds_write2_b32 v40, v106, v107 offset1:1
	ds_write2_b32 v41, v108, v109 offset1:1
	ds_write2_b32 v42, v102, v103 offset1:1
	ds_write2_b32 v43, v104, v105 offset1:1
	ds_write2_b32 v44, v98, v99 offset1:1
	ds_write2_b32 v45, v100, v101 offset1:1
	ds_write2_b32 v46, v94, v95 offset1:1
	ds_write2_b32 v47, v96, v97 offset1:1
	ds_write2_b32 v48, v90, v91 offset1:1
	ds_write2_b32 v49, v92, v93 offset1:1
	ds_write2_b32 v50, v86, v87 offset1:1
	ds_write2_b32 v51, v88, v89 offset1:1
	ds_write2_b32 v52, v82, v83 offset1:1
	ds_write2_b32 v53, v84, v85 offset1:1
	ds_write2_b32 v54, v78, v79 offset1:1
	ds_write2_b32 v55, v80, v81 offset1:1
	ds_write2_b32 v56, v74, v75 offset1:1
	ds_write2_b32 v57, v76, v77 offset1:1
	ds_write2_b32 v58, v70, v71 offset1:1
	ds_write2_b32 v59, v72, v73 offset1:1
	ds_write2_b32 v60, v66, v67 offset1:1
	ds_write2_b32 v61, v68, v69 offset1:1
	ds_write2_b32 v62, v126, v127 offset1:1
	ds_write2_b32 v63, v128, v129 offset1:1
	s_waitcnt lgkmcnt(0)
	ds_read2_b32 v[36:37], v27 offset1:8
	ds_read2_b32 v[38:39], v27 offset0:33 offset1:41
	ds_read2_b32 v[40:41], v27 offset0:66 offset1:74
	ds_read2_b32 v[42:43], v27 offset0:99 offset1:107
	ds_read2_b32 v[44:45], v27 offset0:132 offset1:140
	ds_read2_b32 v[46:47], v27 offset0:165 offset1:173
	ds_read2_b32 v[48:49], v27 offset0:198 offset1:206
	ds_read2_b32 v[50:51], v27 offset0:231 offset1:239
	ds_read2_b32 v[52:53], v64 offset0:8 offset1:16
	ds_read2_b32 v[54:55], v64 offset0:41 offset1:49
	ds_read2_b32 v[56:57], v64 offset0:74 offset1:82
	ds_read2_b32 v[58:59], v64 offset0:107 offset1:115
	ds_read2_b32 v[60:61], v64 offset0:140 offset1:148
	ds_read2_b32 v[62:63], v64 offset0:173 offset1:181
	ds_read2_b32 v[66:67], v64 offset0:206 offset1:214
	ds_read2_b32 v[68:69], v64 offset0:239 offset1:247
	ds_read2_b32 v[70:71], v27 offset0:16 offset1:24
	ds_read2_b32 v[72:73], v27 offset0:49 offset1:57
	ds_read2_b32 v[74:75], v27 offset0:82 offset1:90
	ds_read2_b32 v[76:77], v27 offset0:115 offset1:123
	ds_read2_b32 v[78:79], v27 offset0:148 offset1:156
	ds_read2_b32 v[80:81], v27 offset0:181 offset1:189
	ds_read2_b32 v[82:83], v27 offset0:214 offset1:222
	ds_read2_b32 v[84:85], v27 offset0:247 offset1:255
	ds_read2_b32 v[86:87], v64 offset0:24 offset1:32
	ds_read2_b32 v[88:89], v64 offset0:57 offset1:65
	ds_read2_b32 v[90:91], v64 offset0:90 offset1:98
	ds_read2_b32 v[92:93], v64 offset0:123 offset1:131
	ds_read2_b32 v[94:95], v64 offset0:156 offset1:164
	ds_read2_b32 v[96:97], v64 offset0:189 offset1:197
	ds_read2_b32 v[64:65], v64 offset0:222 offset1:230
	ds_read2_b32 v[98:99], v133 offset0:127 offset1:135
	ds_read_b32 v2, v26
	ds_read_b32 v35, v28
	ds_read_b32 v100, v29
	ds_read_b32 v101, v30
	s_waitcnt lgkmcnt(3)
	v_div_scale_f32 v102, s[0:1], v2, v2, s24
	s_waitcnt lgkmcnt(2)
	v_div_scale_f32 v104, s[0:1], v35, v35, s24
	v_rcp_f32_e32 v110, v102
	v_rcp_f32_e32 v111, v104
	s_waitcnt lgkmcnt(1)
	v_div_scale_f32 v106, s[4:5], v100, v100, s24
	s_waitcnt lgkmcnt(0)
; #define LAS __attribute__((address_space(3)))
; __device__ __forceinline__ unsigned pack4_i8(int a, int b, int c, int d) { return (unsigned)(a & 0xff) | ((unsigned)(b & 0xff) << 8) | ((unsigned)(c & 0xff) << 16) | ((unsigned)d << 24); }
; __device__ __forceinline__ int quant_i8(float x, float inv) { return (int)fminf(fmaxf(__builtin_rintf(x * inv), -127.0f), 127.0f); }
; template <int MAP> __device__ __forceinline__ void quant_item(const float* W, int K, int N, unsigned char* W8, const float* gk, const unsigned* cmax, LAS float* scr, int item, int lane, const LAS float* lmax = nullptr) {
;     ...
;     for (int j = 0; j < 4; ++j) { const int n = nn + 8 * j, dr = rowmap<MAP>(n0 + n, 0); const float cm = lmax ? lmax[n] : __uint_as_float(__hip_atomic_load(cmax + dr, __ATOMIC_RELAXED, __HIP_MEMORY_SCOPE_AGENT)); const float inv = cm > 0.f ? 127.0f / cm : 0.f;
;         const LAS float* sp = scr + (16 * c) * 33 + n; int q[16];
; #pragma unroll
;         for (int t = 0; t < 16; ++t) q[t] = quant_i8(sp[t * 33], inv);
;         u32x4 o; o.x = pack4_i8(q[0], q[1], q[2], q[3]); o.y = pack4_i8(q[4], q[5], q[6], q[7]); o.z = pack4_i8(q[8], q[9], q[10], q[11]); o.w = pack4_i8(q[12], q[13], q[14], q[15]);
	v_div_scale_f32 v108, s[6:7], v101, v101, s24
	v_rcp_f32_e32 v112, v106
	v_rcp_f32_e32 v113, v108
	v_fma_f32 v114, -v102, v110, 1.0
	v_div_scale_f32 v103, vcc, s24, v2, s24
	v_fma_f32 v115, -v104, v111, 1.0
	v_fmac_f32_e32 v110, v114, v110
	v_div_scale_f32 v105, s[0:1], s24, v35, s24
	v_fmac_f32_e32 v111, v115, v111
	v_mul_f32_e32 v114, v103, v110
	v_fma_f32 v116, -v106, v112, 1.0
	v_mul_f32_e32 v115, v105, v111
	v_fma_f32 v118, -v102, v114, v103
	v_div_scale_f32 v107, s[4:5], s24, v100, s24
	v_fma_f32 v117, -v108, v113, 1.0
	v_fmac_f32_e32 v112, v116, v112
	v_fma_f32 v119, -v104, v115, v105
	v_fmac_f32_e32 v114, v118, v110
	v_div_scale_f32 v109, s[6:7], s24, v101, s24
	v_fmac_f32_e32 v113, v117, v113
	v_mul_f32_e32 v116, v107, v112
	v_fmac_f32_e32 v115, v119, v111
	v_fma_f32 v102, -v102, v114, v103
	v_mul_f32_e32 v117, v109, v113
	v_fma_f32 v120, -v106, v116, v107
	v_fma_f32 v103, -v104, v115, v105
	v_div_fmas_f32 v102, v102, v110, v114
	s_mov_b64 vcc, s[0:1]
	v_fma_f32 v121, -v108, v117, v109
	v_fmac_f32_e32 v116, v120, v112
	v_div_fixup_f32 v102, v102, v2, s24
	v_div_fmas_f32 v103, v103, v111, v115
	v_cmp_lt_f32_e32 vcc, 0, v2
	v_fmac_f32_e32 v117, v121, v113
	v_fma_f32 v104, -v106, v116, v107
	v_cndmask_b32_e32 v2, 0, v102, vcc
	s_mov_b64 vcc, s[4:5]
	v_fma_f32 v105, -v108, v117, v109
	v_div_fixup_f32 v102, v103, v35, s24
	v_cmp_lt_f32_e64 s[0:1], 0, v35
	v_div_fmas_f32 v35, v104, v112, v116
	s_mov_b64 vcc, s[6:7]
	v_mul_f32_e32 v36, v36, v2
	v_mul_f32_e32 v38, v2, v38
	v_mul_f32_e32 v40, v2, v40
	v_mul_f32_e32 v42, v2, v42
	v_mul_f32_e32 v44, v2, v44
	v_mul_f32_e32 v46, v2, v46
	v_mul_f32_e32 v48, v2, v48
	v_mul_f32_e32 v50, v2, v50
	v_mul_f32_e32 v52, v2, v52
	v_mul_f32_e32 v54, v2, v54
	v_mul_f32_e32 v56, v2, v56
	v_mul_f32_e32 v58, v2, v58
	v_mul_f32_e32 v60, v2, v60
	v_mul_f32_e32 v62, v2, v62
	v_mul_f32_e32 v66, v2, v66
	v_mul_f32_e32 v2, v2, v68
	v_cndmask_b32_e64 v68, 0, v102, s[0:1]
	v_div_fixup_f32 v35, v35, v100, s24
	v_cmp_lt_f32_e64 s[0:1], 0, v100
	v_div_fmas_f32 v100, v105, v113, v117
	v_rndne_f32_e32 v36, v36
	v_rndne_f32_e32 v38, v38
	v_rndne_f32_e32 v42, v42
	v_rndne_f32_e32 v46, v46
	v_rndne_f32_e32 v48, v48
	v_rndne_f32_e32 v54, v54
	v_rndne_f32_e32 v62, v62
	v_mul_f32_e32 v37, v37, v68
	v_mul_f32_e32 v39, v68, v39
	v_mul_f32_e32 v41, v68, v41
	v_mul_f32_e32 v43, v68, v43
	v_mul_f32_e32 v45, v68, v45
	v_mul_f32_e32 v47, v68, v47
	v_mul_f32_e32 v49, v68, v49
	v_mul_f32_e32 v51, v68, v51
	v_mul_f32_e32 v53, v68, v53
	v_mul_f32_e32 v55, v68, v55
	v_mul_f32_e32 v57, v68, v57
	v_mul_f32_e32 v59, v68, v59
	v_mul_f32_e32 v61, v68, v61
	v_mul_f32_e32 v63, v68, v63
	v_mul_f32_e32 v67, v68, v67
	v_mul_f32_e32 v68, v68, v69
	v_cndmask_b32_e64 v35, 0, v35, s[0:1]
	v_div_fixup_f32 v69, v100, v101, s24
	v_cmp_lt_f32_e32 vcc, 0, v101
	v_rndne_f32_e32 v40, v40
	v_rndne_f32_e32 v44, v44
	v_rndne_f32_e32 v50, v50
	v_rndne_f32_e32 v52, v52
	v_rndne_f32_e32 v56, v56
	v_rndne_f32_e32 v58, v58
	v_rndne_f32_e32 v60, v60
	v_rndne_f32_e32 v66, v66
	v_rndne_f32_e32 v2, v2
	v_med3_f32 v36, v36, s25, v34
	v_med3_f32 v38, v38, s25, v34
	v_med3_f32 v42, v42, s25, v34
	v_med3_f32 v46, v46, s25, v34
	v_med3_f32 v48, v48, s25, v34
	v_med3_f32 v54, v54, s25, v34
	v_med3_f32 v62, v62, s25, v34
	v_rndne_f32_e32 v39, v39
	v_rndne_f32_e32 v45, v45
	v_rndne_f32_e32 v47, v47
	v_rndne_f32_e32 v51, v51
	v_rndne_f32_e32 v55, v55
	v_rndne_f32_e32 v57, v57
	v_rndne_f32_e32 v63, v63
	v_mul_f32_e32 v72, v35, v72
	v_mul_f32_e32 v80, v35, v80
	v_mul_f32_e32 v88, v35, v88
	v_mul_f32_e32 v96, v35, v96
	v_cndmask_b32_e32 v69, 0, v69, vcc
	v_med3_f32 v40, v40, s25, v34
	v_med3_f32 v44, v44, s25, v34
	v_med3_f32 v50, v50, s25, v34
	v_med3_f32 v52, v52, s25, v34
	v_med3_f32 v56, v56, s25, v34
	v_med3_f32 v58, v58, s25, v34
	v_med3_f32 v60, v60, s25, v34
	v_med3_f32 v66, v66, s25, v34
	v_med3_f32 v2, v2, s25, v34
	v_rndne_f32_e32 v37, v37
	v_rndne_f32_e32 v41, v41
	v_rndne_f32_e32 v43, v43
	v_rndne_f32_e32 v49, v49
	v_rndne_f32_e32 v53, v53
	v_rndne_f32_e32 v59, v59
	v_rndne_f32_e32 v61, v61
	v_rndne_f32_e32 v67, v67
	v_rndne_f32_e32 v68, v68
	v_mul_f32_e32 v70, v70, v35
	v_mul_f32_e32 v74, v35, v74
	v_mul_f32_e32 v76, v35, v76
	v_mul_f32_e32 v78, v35, v78
	v_mul_f32_e32 v82, v35, v82
	v_mul_f32_e32 v84, v35, v84
	v_mul_f32_e32 v86, v35, v86
	v_mul_f32_e32 v90, v35, v90
	v_mul_f32_e32 v92, v35, v92
	v_mul_f32_e32 v94, v35, v94
	v_mul_f32_e32 v64, v35, v64
	v_mul_f32_e32 v35, v35, v98
	v_cvt_i32_f32_e32 v36, v36
	v_cvt_i32_f32_e32 v38, v38
	v_cvt_i32_f32_e32 v42, v42
	v_cvt_i32_f32_e32 v46, v46
	v_cvt_i32_f32_sdwa v48, v48 dst_sel:WORD_1 dst_unused:UNUSED_PAD src0_sel:DWORD
	v_cvt_i32_f32_e32 v54, v54
	v_cvt_i32_f32_e32 v62, v62
	v_med3_f32 v39, v39, s25, v34
	v_med3_f32 v45, v45, s25, v34
	v_med3_f32 v47, v47, s25, v34
	v_med3_f32 v51, v51, s25, v34
	v_med3_f32 v55, v55, s25, v34
	v_med3_f32 v57, v57, s25, v34
	v_med3_f32 v63, v63, s25, v34
	v_rndne_f32_e32 v72, v72
	v_rndne_f32_e32 v80, v80
	v_rndne_f32_e32 v88, v88
	v_rndne_f32_e32 v96, v96
	v_mul_f32_e32 v73, v69, v73
	v_mul_f32_e32 v81, v69, v81
	v_mul_f32_e32 v89, v69, v89
	v_mul_f32_e32 v97, v69, v97
	v_cvt_i32_f32_sdwa v40, v40 dst_sel:WORD_1 dst_unused:UNUSED_PAD src0_sel:DWORD
	v_cvt_i32_f32_e32 v44, v44
	v_cvt_i32_f32_e32 v50, v50
	v_cvt_i32_f32_e32 v52, v52
	v_cvt_i32_f32_sdwa v56, v56 dst_sel:WORD_1 dst_unused:UNUSED_PAD src0_sel:DWORD
	v_cvt_i32_f32_e32 v58, v58
	v_cvt_i32_f32_e32 v60, v60
	v_cvt_i32_f32_sdwa v66, v66 dst_sel:WORD_1 dst_unused:UNUSED_PAD src0_sel:DWORD
	v_cvt_i32_f32_e32 v2, v2
	v_med3_f32 v37, v37, s25, v34
	v_med3_f32 v41, v41, s25, v34
	v_med3_f32 v43, v43, s25, v34
	v_med3_f32 v49, v49, s25, v34
; #define GAS __attribute__((address_space(1)))
; __device__ __forceinline__ unsigned pack4_i8(int a, int b, int c, int d) { return (unsigned)(a & 0xff) | ((unsigned)(b & 0xff) << 8) | ((unsigned)(c & 0xff) << 16) | ((unsigned)d << 24); }
; __device__ __forceinline__ int quant_i8(float x, float inv) { return (int)fminf(fmaxf(__builtin_rintf(x * inv), -127.0f), 127.0f); }
; template <int MAP> __device__ __forceinline__ void quant_item(const float* W, int K, int N, unsigned char* W8, const float* gk, const unsigned* cmax, LAS float* scr, int item, int lane, const LAS float* lmax = nullptr) {
;     ...
;         for (int t = 0; t < 16; ++t) q[t] = quant_i8(sp[t * 33], inv);
;         u32x4 o; o.x = pack4_i8(q[0], q[1], q[2], q[3]); o.y = pack4_i8(q[4], q[5], q[6], q[7]); o.z = pack4_i8(q[8], q[9], q[10], q[11]); o.w = pack4_i8(q[12], q[13], q[14], q[15]);
;         *(GAS u32x4*)(W8 + (size_t)dr * K + k0 + 16 * c) = o; }
	v_med3_f32 v53, v53, s25, v34
	v_med3_f32 v59, v59, s25, v34
	v_med3_f32 v61, v61, s25, v34
	v_med3_f32 v67, v67, s25, v34
	v_med3_f32 v68, v68, s25, v34
	v_rndne_f32_e32 v70, v70
	v_rndne_f32_e32 v74, v74
	v_rndne_f32_e32 v76, v76
	v_rndne_f32_e32 v78, v78
	v_rndne_f32_e32 v82, v82
	v_rndne_f32_e32 v84, v84
	v_rndne_f32_e32 v86, v86
	v_rndne_f32_e32 v90, v90
	v_rndne_f32_e32 v92, v92
	v_rndne_f32_e32 v94, v94
	v_rndne_f32_e32 v64, v64
	v_rndne_f32_e32 v35, v35
	v_mul_f32_e32 v71, v71, v69
	v_mul_f32_e32 v75, v69, v75
	v_mul_f32_e32 v77, v69, v77
	v_mul_f32_e32 v79, v69, v79
	v_mul_f32_e32 v83, v69, v83
	v_mul_f32_e32 v85, v69, v85
	v_mul_f32_e32 v87, v69, v87
	v_mul_f32_e32 v91, v69, v91
	v_mul_f32_e32 v93, v69, v93
	v_mul_f32_e32 v95, v69, v95
	v_mul_f32_e32 v65, v69, v65
	v_mul_f32_e32 v69, v69, v99
	v_cvt_i32_f32_e32 v39, v39
	v_cvt_i32_f32_e32 v45, v45
	v_cvt_i32_f32_e32 v47, v47
	v_cvt_i32_f32_e32 v51, v51
	v_cvt_i32_f32_e32 v55, v55
	v_cvt_i32_f32_sdwa v57, v57 dst_sel:WORD_1 dst_unused:UNUSED_PAD src0_sel:DWORD
	v_cvt_i32_f32_e32 v63, v63
	v_med3_f32 v72, v72, s25, v34
	v_med3_f32 v80, v80, s25, v34
	v_med3_f32 v88, v88, s25, v34
	v_med3_f32 v96, v96, s25, v34
	v_rndne_f32_e32 v73, v73
	v_rndne_f32_e32 v81, v81
	v_rndne_f32_e32 v89, v89
	v_rndne_f32_e32 v97, v97
	v_cvt_i32_f32_e32 v37, v37
	v_cvt_i32_f32_sdwa v41, v41 dst_sel:WORD_1 dst_unused:UNUSED_PAD src0_sel:DWORD
	v_cvt_i32_f32_e32 v43, v43
	v_cvt_i32_f32_sdwa v49, v49 dst_sel:WORD_1 dst_unused:UNUSED_PAD src0_sel:DWORD
	v_cvt_i32_f32_e32 v53, v53
	v_cvt_i32_f32_e32 v59, v59
	v_cvt_i32_f32_e32 v61, v61
	v_cvt_i32_f32_sdwa v67, v67 dst_sel:WORD_1 dst_unused:UNUSED_PAD src0_sel:DWORD
	v_cvt_i32_f32_e32 v68, v68
	v_med3_f32 v70, v70, s25, v34
	v_med3_f32 v74, v74, s25, v34
	v_med3_f32 v76, v76, s25, v34
	v_med3_f32 v78, v78, s25, v34
	v_med3_f32 v82, v82, s25, v34
	v_med3_f32 v84, v84, s25, v34
	v_med3_f32 v86, v86, s25, v34
	v_med3_f32 v90, v90, s25, v34
	v_med3_f32 v92, v92, s25, v34
	v_med3_f32 v94, v94, s25, v34
	v_med3_f32 v64, v64, s25, v34
	v_med3_f32 v35, v35, s25, v34
	v_rndne_f32_e32 v71, v71
	v_rndne_f32_e32 v75, v75
	v_rndne_f32_e32 v77, v77
	v_rndne_f32_e32 v79, v79
	v_rndne_f32_e32 v83, v83
	v_rndne_f32_e32 v85, v85
	v_rndne_f32_e32 v87, v87
	v_rndne_f32_e32 v91, v91
	v_rndne_f32_e32 v93, v93
	v_rndne_f32_e32 v95, v95
	v_rndne_f32_e32 v65, v65
	v_rndne_f32_e32 v69, v69
	v_cvt_i32_f32_e32 v72, v72
	v_cvt_i32_f32_e32 v80, v80
	v_cvt_i32_f32_e32 v88, v88
	v_cvt_i32_f32_e32 v96, v96
	v_med3_f32 v73, v73, s25, v34
	v_med3_f32 v81, v81, s25, v34
	v_med3_f32 v89, v89, s25, v34
	v_med3_f32 v97, v97, s25, v34
	v_cvt_i32_f32_e32 v70, v70
	v_cvt_i32_f32_sdwa v74, v74 dst_sel:WORD_1 dst_unused:UNUSED_PAD src0_sel:DWORD
	v_cvt_i32_f32_e32 v76, v76
	v_cvt_i32_f32_e32 v78, v78
	v_cvt_i32_f32_sdwa v82, v82 dst_sel:WORD_1 dst_unused:UNUSED_PAD src0_sel:DWORD
	v_cvt_i32_f32_e32 v84, v84
	v_cvt_i32_f32_e32 v86, v86
	v_cvt_i32_f32_sdwa v90, v90 dst_sel:WORD_1 dst_unused:UNUSED_PAD src0_sel:DWORD
	v_cvt_i32_f32_e32 v92, v92
	v_cvt_i32_f32_e32 v94, v94
	v_cvt_i32_f32_sdwa v64, v64 dst_sel:WORD_1 dst_unused:UNUSED_PAD src0_sel:DWORD
	v_cvt_i32_f32_e32 v35, v35
	v_med3_f32 v71, v71, s25, v34
	v_med3_f32 v75, v75, s25, v34
	v_med3_f32 v77, v77, s25, v34
	v_med3_f32 v79, v79, s25, v34
	v_med3_f32 v83, v83, s25, v34
	v_med3_f32 v85, v85, s25, v34
	v_med3_f32 v87, v87, s25, v34
	v_med3_f32 v91, v91, s25, v34
	v_med3_f32 v93, v93, s25, v34
	v_med3_f32 v95, v95, s25, v34
	v_med3_f32 v65, v65, s25, v34
	v_med3_f32 v69, v69, s25, v34
	v_cvt_i32_f32_e32 v73, v73
	v_cvt_i32_f32_e32 v81, v81
	v_cvt_i32_f32_e32 v89, v89
	v_cvt_i32_f32_e32 v97, v97
	v_cvt_i32_f32_e32 v71, v71
	v_cvt_i32_f32_sdwa v75, v75 dst_sel:WORD_1 dst_unused:UNUSED_PAD src0_sel:DWORD
	v_cvt_i32_f32_e32 v77, v77
	v_cvt_i32_f32_e32 v79, v79
	v_cvt_i32_f32_sdwa v83, v83 dst_sel:WORD_1 dst_unused:UNUSED_PAD src0_sel:DWORD
	v_cvt_i32_f32_e32 v85, v85
	v_cvt_i32_f32_e32 v87, v87
	v_cvt_i32_f32_sdwa v91, v91 dst_sel:WORD_1 dst_unused:UNUSED_PAD src0_sel:DWORD
	v_cvt_i32_f32_e32 v93, v93
	v_cvt_i32_f32_e32 v95, v95
	v_cvt_i32_f32_sdwa v65, v65 dst_sel:WORD_1 dst_unused:UNUSED_PAD src0_sel:DWORD
	v_cvt_i32_f32_e32 v69, v69
	v_lshlrev_b32_e32 v38, 8, v38
	v_perm_b32 v36, v42, v36, s26
	v_lshlrev_b32_e32 v42, 8, v46
	v_and_b32_e32 v46, 0xff0000, v48
	v_lshlrev_b32_e32 v48, 8, v54
	v_lshlrev_b32_e32 v54, 8, v62
	v_and_b32_e32 v40, 0xff0000, v40
	v_perm_b32 v44, v50, v44, s26
	v_and_b32_e32 v50, 0xff0000, v56
	v_perm_b32 v52, v58, v52, s26
	v_and_b32_e32 v56, 0xff0000, v66
	v_perm_b32 v2, v2, v60, s26
	v_and_b32_e32 v38, 0xff00, v38
	v_and_b32_e32 v42, 0xff00, v42
	v_and_b32_e32 v48, 0xff00, v48
	v_and_b32_e32 v54, 0xff00, v54
	v_lshlrev_b32_e32 v58, 8, v39
	v_lshlrev_b32_e32 v47, 8, v47
	v_perm_b32 v45, v51, v45, s26
	v_lshlrev_b32_e32 v51, 8, v55
	v_and_b32_e32 v55, 0xff0000, v57
	v_lshlrev_b32_e32 v57, 8, v63
	v_and_b32_e32 v41, 0xff0000, v41
	v_perm_b32 v43, v43, v37, s26
	v_and_b32_e32 v49, 0xff0000, v49
	v_perm_b32 v53, v59, v53, s26
	v_and_b32_e32 v59, 0xff0000, v67
	v_perm_b32 v60, v68, v61, s26
	v_or3_b32 v36, v36, v38, v40
	v_or3_b32 v37, v44, v42, v46
	v_or3_b32 v38, v52, v48, v50
	v_or3_b32 v39, v2, v54, v56
	v_and_b32_e32 v2, 0xff00, v58
	v_and_b32_e32 v40, 0xff00, v47
	v_and_b32_e32 v42, 0xff00, v51
	v_and_b32_e32 v44, 0xff00, v57
	v_lshlrev_b32_e32 v46, 8, v72
	v_lshlrev_b32_e32 v50, 8, v80
	v_lshlrev_b32_e32 v54, 8, v88
	v_lshlrev_b32_e32 v58, 8, v96
	v_and_b32_e32 v47, 0xff0000, v74
	v_perm_b32 v48, v76, v70, s26
	v_and_b32_e32 v51, 0xff0000, v82
	v_perm_b32 v52, v84, v78, s26
	v_and_b32_e32 v56, 0xff0000, v90
	v_perm_b32 v57, v92, v86, s26
	v_and_b32_e32 v61, 0xff0000, v64
	v_perm_b32 v35, v35, v94, s26
	global_store_dwordx4 v[16:17], v[36:39], off
	v_and_b32_e32 v16, 0xff00, v50
	v_and_b32_e32 v17, 0xff00, v54
	v_or3_b32 v36, v43, v2, v41
	v_or3_b32 v37, v45, v40, v49
	v_or3_b32 v38, v53, v42, v55
	v_or3_b32 v39, v60, v44, v59
	v_and_b32_e32 v2, 0xff00, v46
	v_and_b32_e32 v40, 0xff00, v58
	v_lshlrev_b32_e32 v41, 8, v73
	v_lshlrev_b32_e32 v44, 8, v81
	v_lshlrev_b32_e32 v49, 8, v89
	v_lshlrev_b32_e32 v54, 8, v97
	v_and_b32_e32 v42, 0xff0000, v75
	v_perm_b32 v43, v77, v71, s26
	v_and_b32_e32 v45, 0xff0000, v83
	v_perm_b32 v46, v85, v79, s26
	v_and_b32_e32 v50, 0xff0000, v91
	v_perm_b32 v53, v93, v87, s26
	v_and_b32_e32 v55, 0xff0000, v65
	v_perm_b32 v58, v69, v95, s26
	global_store_dwordx4 v[14:15], v[36:39], off
	v_or3_b32 v14, v48, v2, v47
	v_or3_b32 v15, v52, v16, v51
	v_or3_b32 v16, v57, v17, v56
	v_or3_b32 v17, v35, v40, v61
	v_and_b32_e32 v2, 0xff00, v41
	v_and_b32_e32 v35, 0xff00, v44
	v_and_b32_e32 v36, 0xff00, v49
	v_and_b32_e32 v37, 0xff00, v54
	global_store_dwordx4 v[12:13], v[14:17], off
	v_or3_b32 v12, v43, v2, v42
	v_or3_b32 v13, v46, v35, v45
	v_or3_b32 v14, v53, v36, v50
	v_or3_b32 v15, v58, v37, v55
	global_store_dwordx4 v[10:11], v[12:15], off
	s_waitcnt lgkmcnt(0)
	s_cbranch_scc1 .LBB0_774
	s_branch .LBB0_766

; #define GAS __attribute__((address_space(1)))
; #define LAS __attribute__((address_space(3)))
; #define LDS_WAIT() asm volatile("s_waitcnt lgkmcnt(0)" ::: "memory")
; template <int MAP> __device__ __forceinline__ int rowmap(int n, int row_off) {
;     ...
;     if (MAP == 3) return 256 * (n >> 7) + 128 + (n & 127);
; template <int MAP> __device__ __forceinline__ void quant_item(const float* W, int K, int N, unsigned char* W8, const float* gk, const unsigned* cmax, LAS float* scr, int item, int lane, const LAS float* lmax = nullptr) {
;     const int nblk = N / 32, kb = item / nblk, nb = item % nblk, k0 = 128 * kb, n0 = 32 * nb;
;     const int n4 = lane & 7, kr = lane >> 3;
;     f32x4 v[16];
; #pragma unroll
;     for (int i = 0; i < 16; ++i) v[i] = *(const GAS f32x4*)(W + (size_t)(k0 + 8 * i + kr) * N + n0 + 4 * n4);
; #pragma unroll
;     for (int i = 0; i < 16; ++i) v[i] = v[i] * (gk ? gk[k0 + 8 * i + kr] : 1.0f);
; #pragma unroll
;     for (int i = 0; i < 16; ++i) { LAS float* d = scr + (8 * i + kr) * 33 + 4 * n4; d[0] = v[i][0]; d[1] = v[i][1]; d[2] = v[i][2]; d[3] = v[i][3]; }
;     LDS_WAIT(); asm volatile("" ::: "memory");
;     const int c = lane & 7, nn = lane >> 3;
; #pragma unroll
;     for (int j = 0; j < 4; ++j) { const int n = nn + 8 * j, dr = rowmap<MAP>(n0 + n, 0); const float cm = lmax ? lmax[n] : __uint_as_float(__hip_atomic_load(cmax + dr, __ATOMIC_RELAXED, __HIP_MEMORY_SCOPE_AGENT)); const float inv = cm > 0.f ? 127.0f / cm : 0.f;
.LBB0_807:
	s_mul_hi_i32 s0, s30, 0x2fa0be83
	s_lshr_b32 s1, s0, 31
	s_ashr_i32 s0, s0, 6
	s_add_i32 s0, s0, s1
	s_mul_i32 s1, s0, 0x158
	s_sub_i32 s5, s30, s1
	s_lshl_b32 s0, s0, 7
	s_lshl_b32 s4, s5, 5
	v_or_b32_e32 v10, s0, v20
	s_ashr_i32 s1, s0, 31
	s_lshl_b32 s6, s5, 6
	s_ashr_i32 s5, s4, 31
	v_ashrrev_i32_e32 v11, 31, v10
	v_or_b32_e32 v64, 24, v10
	v_or_b32_e32 v65, 32, v10
	v_or_b32_e32 v66, 40, v10
	v_or_b32_e32 v67, 48, v10
	v_or_b32_e32 v68, 56, v10
	v_or_b32_e32 v69, 64, v10
	v_or_b32_e32 v70, 0x48, v10
	v_or_b32_e32 v71, 0x50, v10
	v_or_b32_e32 v72, 0x58, v10
	v_or_b32_e32 v73, 0x60, v10
	v_or_b32_e32 v74, 0x68, v10
	v_or_b32_e32 v75, 0x70, v10
	v_lshl_add_u64 v[128:129], v[8:9], 0, s[0:1]
	s_and_b32 s0, s6, 0xffffff00
	s_and_b32 s1, s4, 0x60
	v_lshl_add_u64 v[14:15], s[4:5], 2, v[6:7]
	v_or_b32_e32 v16, 8, v10
	v_or_b32_e32 v17, 16, v10
	v_or_b32_e32 v78, 0x78, v10
	v_lshl_add_u64 v[12:13], v[10:11], 2, s[36:37]
	s_or_b32 s4, s0, s1
	v_mad_i64_i32 v[108:109], s[0:1], v64, s25, v[14:15]
	v_mad_i64_i32 v[104:105], s[0:1], v65, s25, v[14:15]
	v_mad_i64_i32 v[100:101], s[0:1], v66, s25, v[14:15]
	v_mad_i64_i32 v[96:97], s[0:1], v67, s25, v[14:15]
	v_mad_i64_i32 v[92:93], s[0:1], v68, s25, v[14:15]
	v_mad_i64_i32 v[88:89], s[0:1], v69, s25, v[14:15]
	v_mad_i64_i32 v[84:85], s[0:1], v70, s25, v[14:15]
	v_mad_i64_i32 v[80:81], s[0:1], v71, s25, v[14:15]
	v_mad_i64_i32 v[76:77], s[0:1], v72, s25, v[14:15]
	v_mad_i64_i32 v[72:73], s[0:1], v73, s25, v[14:15]
	v_mad_i64_i32 v[68:69], s[0:1], v74, s25, v[14:15]
	v_mad_i64_i32 v[64:65], s[0:1], v75, s25, v[14:15]
	global_load_dword v130, v[12:13], off
	global_load_dword v132, v[12:13], off offset:32
	global_load_dword v134, v[12:13], off offset:64
	global_load_dword v136, v[12:13], off offset:96
	global_load_dword v138, v[12:13], off offset:128
	global_load_dword v140, v[12:13], off offset:160
	global_load_dword v142, v[12:13], off offset:192
	global_load_dword v144, v[12:13], off offset:224
	global_load_dword v146, v[12:13], off offset:256
	global_load_dword v148, v[12:13], off offset:288
	global_load_dword v150, v[12:13], off offset:320
	global_load_dword v152, v[12:13], off offset:352
	global_load_dword v154, v[12:13], off offset:384
	global_load_dword v156, v[12:13], off offset:416
	global_load_dword v158, v[12:13], off offset:448
	global_load_dword v160, v[12:13], off offset:480
	v_mad_i64_i32 v[10:11], s[0:1], v10, s25, v[14:15]
	v_mad_i64_i32 v[12:13], s[0:1], v16, s25, v[14:15]
	v_mad_i64_i32 v[16:17], s[0:1], v17, s25, v[14:15]
	v_mad_i64_i32 v[14:15], s[0:1], v78, s25, v[14:15]
	global_load_dwordx4 v[64:67], v[64:65], off
	s_nop 0
	global_load_dwordx4 v[68:71], v[68:69], off
	s_nop 0
	global_load_dwordx4 v[72:75], v[72:73], off
	s_nop 0
	global_load_dwordx4 v[76:79], v[76:77], off
	s_nop 0
	global_load_dwordx4 v[80:83], v[80:81], off
	s_nop 0
	global_load_dwordx4 v[84:87], v[84:85], off
	s_nop 0
	global_load_dwordx4 v[88:91], v[88:89], off
	s_nop 0
	global_load_dwordx4 v[92:95], v[92:93], off
	s_nop 0
	global_load_dwordx4 v[96:99], v[96:97], off
	s_nop 0
	global_load_dwordx4 v[100:103], v[100:101], off
	s_nop 0
	global_load_dwordx4 v[104:107], v[104:105], off
	s_nop 0
	global_load_dwordx4 v[108:111], v[108:109], off
	s_nop 0
	global_load_dwordx4 v[112:115], v[16:17], off
	global_load_dwordx4 v[116:119], v[12:13], off
	global_load_dwordx4 v[120:123], v[10:11], off
	global_load_dwordx4 v[124:127], v[14:15], off
	v_add_u32_e32 v131, 0x600, v26
	v_or_b32_e32 v133, s4, v20
	v_add_u32_e32 v2, 0x420, v32
	v_add_u32_e32 v34, 0x428, v32
	v_add_u32_e32 v35, 0x840, v32
	v_add_u32_e32 v36, 0x848, v32
	v_add_u32_e32 v37, 0xc60, v32
	v_add_u32_e32 v38, 0xc68, v32
	v_add_u32_e32 v39, 0x1080, v32
	v_add_u32_e32 v40, 0x1088, v32
	v_add_u32_e32 v41, 0x14a0, v32
	v_add_u32_e32 v42, 0x14a8, v32
	v_add_u32_e32 v43, 0x18c0, v32
	v_add_u32_e32 v44, 0x18c8, v32
	v_add_u32_e32 v45, 0x1ce0, v32
	v_add_u32_e32 v46, 0x1ce8, v32
	v_add_u32_e32 v47, 0x2100, v32
	v_add_u32_e32 v48, 0x2108, v32
	v_add_u32_e32 v49, 0x2520, v32
	v_add_u32_e32 v50, 0x2528, v32
	v_add_u32_e32 v51, 0x2940, v32
	v_add_u32_e32 v52, 0x2948, v32
	v_add_u32_e32 v53, 0x2d60, v32
	v_add_u32_e32 v54, 0x2d68, v32
	v_add_u32_e32 v55, 0x3180, v32
	v_add_u32_e32 v56, 0x3188, v32
	v_add_u32_e32 v57, 0x35a0, v32
	v_add_u32_e32 v58, 0x35a8, v32
	v_add_u32_e32 v59, 0x39c0, v32
	v_add_u32_e32 v60, 0x39c8, v32
	v_add_u32_e32 v61, 0x3de0, v32
	v_add_u32_e32 v62, 0x3de8, v32
	v_add_u32_e32 v63, 0x400, v26
	v_or_b32_e32 v10, 0x80, v133
	v_or_b32_e32 v12, 0x88, v133
	v_or_b32_e32 v16, 0x98, v133
	v_ashrrev_i32_e32 v11, 31, v10
	v_or_b32_e32 v14, 0x90, v133
	v_ashrrev_i32_e32 v13, 31, v12
	v_ashrrev_i32_e32 v17, 31, v16
	v_mul_u32_u24_e32 v10, 0x1080, v10
	v_mov_b32_e32 v11, 0
	v_ashrrev_i32_e32 v15, 31, v14
	v_mul_u32_u24_e32 v12, 0x1080, v12
	v_mov_b32_e32 v13, 0
	v_mul_u32_u24_e32 v164, 0x1080, v16
	v_mov_b32_e32 v165, 0
	v_lshl_add_u64 v[16:17], v[128:129], 0, v[10:11]
	v_mul_u32_u24_e32 v162, 0x1080, v14
	v_mov_b32_e32 v163, 0
	v_lshl_add_u64 v[14:15], v[128:129], 0, v[12:13]
	v_lshl_add_u64 v[12:13], v[128:129], 0, v[162:163]
	v_lshl_add_u64 v[10:11], v[128:129], 0, v[164:165]
	s_add_i32 s31, s31, 8
	s_addk_i32 s30, 0xac0
	s_cmp_lt_u32 s31, 24
	s_waitcnt vmcnt(13)
	v_pk_mul_f32 v[74:75], v[74:75], v[154:155] op_sel_hi:[1,0]
	v_pk_mul_f32 v[70:71], v[70:71], v[156:157] op_sel_hi:[1,0]
	v_pk_mul_f32 v[66:67], v[66:67], v[158:159] op_sel_hi:[1,0]
	v_pk_mul_f32 v[64:65], v[64:65], v[158:159] op_sel_hi:[1,0]
	v_pk_mul_f32 v[68:69], v[68:69], v[156:157] op_sel_hi:[1,0]
	v_pk_mul_f32 v[72:73], v[72:73], v[154:155] op_sel_hi:[1,0]
	s_waitcnt vmcnt(12)
; #define GAS __attribute__((address_space(1)))
; #define LAS __attribute__((address_space(3)))
; #define LDS_WAIT() asm volatile("s_waitcnt lgkmcnt(0)" ::: "memory")
; __device__ __forceinline__ unsigned pack4_i8(int a, int b, int c, int d) { return (unsigned)(a & 0xff) | ((unsigned)(b & 0xff) << 8) | ((unsigned)(c & 0xff) << 16) | ((unsigned)d << 24); }
; __device__ __forceinline__ int quant_i8(float x, float inv) { return (int)fminf(fmaxf(__builtin_rintf(x * inv), -127.0f), 127.0f); }
; template <int MAP> __device__ __forceinline__ void quant_item(const float* W, int K, int N, unsigned char* W8, const float* gk, const unsigned* cmax, LAS float* scr, int item, int lane, const LAS float* lmax = nullptr) {
;     ...
;     for (int i = 0; i < 16; ++i) v[i] = v[i] * (gk ? gk[k0 + 8 * i + kr] : 1.0f);
; #pragma unroll
;     for (int i = 0; i < 16; ++i) { LAS float* d = scr + (8 * i + kr) * 33 + 4 * n4; d[0] = v[i][0]; d[1] = v[i][1]; d[2] = v[i][2]; d[3] = v[i][3]; }
;     LDS_WAIT(); asm volatile("" ::: "memory");
;     const int c = lane & 7, nn = lane >> 3;
; #pragma unroll
;     for (int j = 0; j < 4; ++j) { const int n = nn + 8 * j, dr = rowmap<MAP>(n0 + n, 0); const float cm = lmax ? lmax[n] : __uint_as_float(__hip_atomic_load(cmax + dr, __ATOMIC_RELAXED, __HIP_MEMORY_SCOPE_AGENT)); const float inv = cm > 0.f ? 127.0f / cm : 0.f;
;         const LAS float* sp = scr + (16 * c) * 33 + n; int q[16];
; #pragma unroll
;         for (int t = 0; t < 16; ++t) q[t] = quant_i8(sp[t * 33], inv);
;         u32x4 o; o.x = pack4_i8(q[0], q[1], q[2], q[3]); o.y = pack4_i8(q[4], q[5], q[6], q[7]); o.z = pack4_i8(q[8], q[9], q[10], q[11]); o.w = pack4_i8(q[12], q[13], q[14], q[15]);
;         *(GAS u32x4*)(W8 + (size_t)dr * K + k0 + 16 * c) = o; }
	v_pk_mul_f32 v[78:79], v[78:79], v[152:153] op_sel_hi:[1,0]
	v_pk_mul_f32 v[76:77], v[76:77], v[152:153] op_sel_hi:[1,0]
	s_waitcnt vmcnt(11)
	v_pk_mul_f32 v[82:83], v[82:83], v[150:151] op_sel_hi:[1,0]
	v_pk_mul_f32 v[80:81], v[80:81], v[150:151] op_sel_hi:[1,0]
	s_waitcnt vmcnt(10)
	v_pk_mul_f32 v[86:87], v[86:87], v[148:149] op_sel_hi:[1,0]
	s_waitcnt vmcnt(1)
	v_pk_mul_f32 v[120:121], v[120:121], v[130:131] op_sel_hi:[1,0]
	v_pk_mul_f32 v[84:85], v[84:85], v[148:149] op_sel_hi:[1,0]
	v_pk_mul_f32 v[90:91], v[90:91], v[146:147] op_sel_hi:[1,0]
	v_pk_mul_f32 v[88:89], v[88:89], v[146:147] op_sel_hi:[1,0]
	v_pk_mul_f32 v[94:95], v[94:95], v[144:145] op_sel_hi:[1,0]
	v_pk_mul_f32 v[92:93], v[92:93], v[144:145] op_sel_hi:[1,0]
	v_pk_mul_f32 v[98:99], v[98:99], v[142:143] op_sel_hi:[1,0]
	v_pk_mul_f32 v[96:97], v[96:97], v[142:143] op_sel_hi:[1,0]
	v_pk_mul_f32 v[102:103], v[102:103], v[140:141] op_sel_hi:[1,0]
	v_pk_mul_f32 v[100:101], v[100:101], v[140:141] op_sel_hi:[1,0]
	v_pk_mul_f32 v[106:107], v[106:107], v[138:139] op_sel_hi:[1,0]
	v_pk_mul_f32 v[104:105], v[104:105], v[138:139] op_sel_hi:[1,0]
	v_pk_mul_f32 v[110:111], v[110:111], v[136:137] op_sel_hi:[1,0]
	v_pk_mul_f32 v[108:109], v[108:109], v[136:137] op_sel_hi:[1,0]
	v_pk_mul_f32 v[114:115], v[114:115], v[134:135] op_sel_hi:[1,0]
	v_pk_mul_f32 v[112:113], v[112:113], v[134:135] op_sel_hi:[1,0]
	v_pk_mul_f32 v[118:119], v[118:119], v[132:133] op_sel_hi:[1,0]
	v_pk_mul_f32 v[116:117], v[116:117], v[132:133] op_sel_hi:[1,0]
	v_pk_mul_f32 v[122:123], v[122:123], v[130:131] op_sel_hi:[1,0]
	s_waitcnt vmcnt(0)
	v_pk_mul_f32 v[126:127], v[126:127], v[160:161] op_sel_hi:[1,0]
	v_pk_mul_f32 v[124:125], v[124:125], v[160:161] op_sel_hi:[1,0]
	ds_write2_b32 v32, v120, v121 offset1:1
	ds_write2_b32 v32, v122, v123 offset0:2 offset1:3
	ds_write2_b32 v2, v116, v117 offset1:1
	ds_write2_b32 v34, v118, v119 offset1:1
	ds_write2_b32 v35, v112, v113 offset1:1
	ds_write2_b32 v36, v114, v115 offset1:1
	ds_write2_b32 v37, v108, v109 offset1:1
	ds_write2_b32 v38, v110, v111 offset1:1
	ds_write2_b32 v39, v104, v105 offset1:1
	ds_write2_b32 v40, v106, v107 offset1:1
	ds_write2_b32 v41, v100, v101 offset1:1
	ds_write2_b32 v42, v102, v103 offset1:1
	ds_write2_b32 v43, v96, v97 offset1:1
	ds_write2_b32 v44, v98, v99 offset1:1
	ds_write2_b32 v45, v92, v93 offset1:1
	ds_write2_b32 v46, v94, v95 offset1:1
	ds_write2_b32 v47, v88, v89 offset1:1
	ds_write2_b32 v48, v90, v91 offset1:1
	ds_write2_b32 v49, v84, v85 offset1:1
	ds_write2_b32 v50, v86, v87 offset1:1
	ds_write2_b32 v51, v80, v81 offset1:1
	ds_write2_b32 v52, v82, v83 offset1:1
	ds_write2_b32 v53, v76, v77 offset1:1
	ds_write2_b32 v54, v78, v79 offset1:1
	ds_write2_b32 v55, v72, v73 offset1:1
	ds_write2_b32 v56, v74, v75 offset1:1
	ds_write2_b32 v57, v68, v69 offset1:1
	ds_write2_b32 v58, v70, v71 offset1:1
	ds_write2_b32 v59, v64, v65 offset1:1
	ds_write2_b32 v60, v66, v67 offset1:1
	ds_write2_b32 v61, v124, v125 offset1:1
	ds_write2_b32 v62, v126, v127 offset1:1
	s_waitcnt lgkmcnt(0)
	ds_read2_b32 v[34:35], v26 offset1:8
	ds_read2_b32 v[36:37], v26 offset0:33 offset1:41
	ds_read2_b32 v[38:39], v26 offset0:66 offset1:74
	ds_read2_b32 v[40:41], v26 offset0:99 offset1:107
	ds_read2_b32 v[42:43], v26 offset0:132 offset1:140
	ds_read2_b32 v[44:45], v26 offset0:165 offset1:173
	ds_read2_b32 v[46:47], v26 offset0:198 offset1:206
	ds_read2_b32 v[48:49], v26 offset0:231 offset1:239
	ds_read2_b32 v[50:51], v63 offset0:8 offset1:16
	ds_read2_b32 v[52:53], v63 offset0:41 offset1:49
	ds_read2_b32 v[54:55], v63 offset0:74 offset1:82
	ds_read2_b32 v[56:57], v63 offset0:107 offset1:115
	ds_read2_b32 v[58:59], v63 offset0:140 offset1:148
	ds_read2_b32 v[60:61], v63 offset0:173 offset1:181
	ds_read2_b32 v[64:65], v63 offset0:206 offset1:214
	ds_read2_b32 v[66:67], v63 offset0:239 offset1:247
	ds_read2_b32 v[68:69], v26 offset0:16 offset1:24
	ds_read2_b32 v[70:71], v26 offset0:49 offset1:57
	ds_read2_b32 v[72:73], v26 offset0:82 offset1:90
	ds_read2_b32 v[74:75], v26 offset0:115 offset1:123
	ds_read2_b32 v[76:77], v26 offset0:148 offset1:156
	ds_read2_b32 v[78:79], v26 offset0:181 offset1:189
	ds_read2_b32 v[80:81], v26 offset0:214 offset1:222
	ds_read2_b32 v[82:83], v26 offset0:247 offset1:255
	ds_read2_b32 v[84:85], v63 offset0:24 offset1:32
	ds_read2_b32 v[86:87], v63 offset0:57 offset1:65
	ds_read2_b32 v[88:89], v63 offset0:90 offset1:98
	ds_read2_b32 v[90:91], v63 offset0:123 offset1:131
	ds_read2_b32 v[92:93], v63 offset0:156 offset1:164
	ds_read2_b32 v[94:95], v63 offset0:189 offset1:197
	ds_read2_b32 v[62:63], v63 offset0:222 offset1:230
	ds_read2_b32 v[96:97], v131 offset0:127 offset1:135
	ds_read_b32 v2, v25
	ds_read_b32 v98, v27
	ds_read_b32 v99, v28
	ds_read_b32 v100, v29
	s_waitcnt lgkmcnt(3)
	v_div_scale_f32 v101, s[0:1], v2, v2, s26
	s_waitcnt lgkmcnt(2)
	v_div_scale_f32 v103, s[0:1], v98, v98, s26
	v_rcp_f32_e32 v109, v101
	v_rcp_f32_e32 v110, v103
	s_waitcnt lgkmcnt(1)
	v_div_scale_f32 v105, s[4:5], v99, v99, s26
	s_waitcnt lgkmcnt(0)
; #define LAS __attribute__((address_space(3)))
; __device__ __forceinline__ unsigned pack4_i8(int a, int b, int c, int d) { return (unsigned)(a & 0xff) | ((unsigned)(b & 0xff) << 8) | ((unsigned)(c & 0xff) << 16) | ((unsigned)d << 24); }
; __device__ __forceinline__ int quant_i8(float x, float inv) { return (int)fminf(fmaxf(__builtin_rintf(x * inv), -127.0f), 127.0f); }
; template <int MAP> __device__ __forceinline__ void quant_item(const float* W, int K, int N, unsigned char* W8, const float* gk, const unsigned* cmax, LAS float* scr, int item, int lane, const LAS float* lmax = nullptr) {
;     ...
;     for (int j = 0; j < 4; ++j) { const int n = nn + 8 * j, dr = rowmap<MAP>(n0 + n, 0); const float cm = lmax ? lmax[n] : __uint_as_float(__hip_atomic_load(cmax + dr, __ATOMIC_RELAXED, __HIP_MEMORY_SCOPE_AGENT)); const float inv = cm > 0.f ? 127.0f / cm : 0.f;
;         const LAS float* sp = scr + (16 * c) * 33 + n; int q[16];
; #pragma unroll
;         for (int t = 0; t < 16; ++t) q[t] = quant_i8(sp[t * 33], inv);
;         u32x4 o; o.x = pack4_i8(q[0], q[1], q[2], q[3]); o.y = pack4_i8(q[4], q[5], q[6], q[7]); o.z = pack4_i8(q[8], q[9], q[10], q[11]); o.w = pack4_i8(q[12], q[13], q[14], q[15]);
	v_div_scale_f32 v107, s[6:7], v100, v100, s26
	v_rcp_f32_e32 v111, v105
	v_rcp_f32_e32 v112, v107
	v_fma_f32 v113, -v101, v109, 1.0
	v_div_scale_f32 v102, vcc, s26, v2, s26
	v_fma_f32 v114, -v103, v110, 1.0
	v_fmac_f32_e32 v109, v113, v109
	v_div_scale_f32 v104, s[0:1], s26, v98, s26
	v_fmac_f32_e32 v110, v114, v110
	v_mul_f32_e32 v113, v102, v109
	v_fma_f32 v115, -v105, v111, 1.0
	v_mul_f32_e32 v114, v104, v110
	v_fma_f32 v117, -v101, v113, v102
	v_div_scale_f32 v106, s[4:5], s26, v99, s26
	v_fma_f32 v116, -v107, v112, 1.0
	v_fmac_f32_e32 v111, v115, v111
	v_fma_f32 v118, -v103, v114, v104
	v_fmac_f32_e32 v113, v117, v109
	v_div_scale_f32 v108, s[6:7], s26, v100, s26
	v_fmac_f32_e32 v112, v116, v112
	v_mul_f32_e32 v115, v106, v111
	v_fmac_f32_e32 v114, v118, v110
	v_fma_f32 v101, -v101, v113, v102
	v_mul_f32_e32 v116, v108, v112
	v_fma_f32 v119, -v105, v115, v106
	v_fma_f32 v102, -v103, v114, v104
	v_div_fmas_f32 v101, v101, v109, v113
	s_mov_b64 vcc, s[0:1]
	v_fma_f32 v120, -v107, v116, v108
	v_fmac_f32_e32 v115, v119, v111
	v_div_fixup_f32 v101, v101, v2, s26
	v_div_fmas_f32 v102, v102, v110, v114
	v_cmp_lt_f32_e32 vcc, 0, v2
	v_fmac_f32_e32 v116, v120, v112
	v_fma_f32 v103, -v105, v115, v106
	v_cndmask_b32_e32 v2, 0, v101, vcc
	s_mov_b64 vcc, s[4:5]
	v_fma_f32 v104, -v107, v116, v108
	v_div_fixup_f32 v101, v102, v98, s26
	v_cmp_lt_f32_e64 s[0:1], 0, v98
	v_div_fmas_f32 v98, v103, v111, v115
	s_mov_b64 vcc, s[6:7]
	v_mul_f32_e32 v34, v34, v2
	v_mul_f32_e32 v36, v2, v36
	v_mul_f32_e32 v38, v2, v38
	v_mul_f32_e32 v40, v2, v40
	v_mul_f32_e32 v42, v2, v42
	v_mul_f32_e32 v44, v2, v44
	v_mul_f32_e32 v46, v2, v46
	v_mul_f32_e32 v48, v2, v48
	v_mul_f32_e32 v50, v2, v50
	v_mul_f32_e32 v52, v2, v52
	v_mul_f32_e32 v54, v2, v54
	v_mul_f32_e32 v56, v2, v56
	v_mul_f32_e32 v58, v2, v58
	v_mul_f32_e32 v60, v2, v60
	v_mul_f32_e32 v64, v2, v64
	v_mul_f32_e32 v2, v2, v66
	v_cndmask_b32_e64 v66, 0, v101, s[0:1]
	v_div_fixup_f32 v98, v98, v99, s26
	v_cmp_lt_f32_e64 s[0:1], 0, v99
	v_div_fmas_f32 v99, v104, v112, v116
	v_rndne_f32_e32 v34, v34
	v_rndne_f32_e32 v36, v36
	v_rndne_f32_e32 v40, v40
	v_rndne_f32_e32 v44, v44
	v_rndne_f32_e32 v46, v46
	v_rndne_f32_e32 v52, v52
	v_rndne_f32_e32 v60, v60
	v_mul_f32_e32 v35, v35, v66
	v_mul_f32_e32 v37, v66, v37
	v_mul_f32_e32 v39, v66, v39
	v_mul_f32_e32 v41, v66, v41
	v_mul_f32_e32 v43, v66, v43
	v_mul_f32_e32 v45, v66, v45
	v_mul_f32_e32 v47, v66, v47
	v_mul_f32_e32 v49, v66, v49
	v_mul_f32_e32 v51, v66, v51
	v_mul_f32_e32 v53, v66, v53
	v_mul_f32_e32 v55, v66, v55
	v_mul_f32_e32 v57, v66, v57
	v_mul_f32_e32 v59, v66, v59
	v_mul_f32_e32 v61, v66, v61
	v_mul_f32_e32 v65, v66, v65
	v_mul_f32_e32 v66, v66, v67
	v_cndmask_b32_e64 v67, 0, v98, s[0:1]
	v_div_fixup_f32 v98, v99, v100, s26
	v_cmp_lt_f32_e32 vcc, 0, v100
	v_rndne_f32_e32 v38, v38
	v_rndne_f32_e32 v42, v42
	v_rndne_f32_e32 v48, v48
	v_rndne_f32_e32 v50, v50
	v_rndne_f32_e32 v54, v54
	v_rndne_f32_e32 v56, v56
	v_rndne_f32_e32 v58, v58
	v_rndne_f32_e32 v64, v64
	v_rndne_f32_e32 v2, v2
	v_med3_f32 v34, v34, s27, v33
	v_med3_f32 v36, v36, s27, v33
	v_med3_f32 v40, v40, s27, v33
	v_med3_f32 v44, v44, s27, v33
	v_med3_f32 v46, v46, s27, v33
	v_med3_f32 v52, v52, s27, v33
	v_med3_f32 v60, v60, s27, v33
	v_rndne_f32_e32 v37, v37
	v_rndne_f32_e32 v43, v43
	v_rndne_f32_e32 v45, v45
	v_rndne_f32_e32 v49, v49
	v_rndne_f32_e32 v53, v53
	v_rndne_f32_e32 v55, v55
	v_rndne_f32_e32 v61, v61
	v_mul_f32_e32 v68, v68, v67
	v_mul_f32_e32 v70, v67, v70
	v_mul_f32_e32 v72, v67, v72
	v_mul_f32_e32 v74, v67, v74
	v_mul_f32_e32 v76, v67, v76
	v_mul_f32_e32 v78, v67, v78
	v_mul_f32_e32 v80, v67, v80
	v_mul_f32_e32 v82, v67, v82
	v_mul_f32_e32 v84, v67, v84
	v_mul_f32_e32 v86, v67, v86
	v_mul_f32_e32 v88, v67, v88
	v_mul_f32_e32 v90, v67, v90
	v_mul_f32_e32 v92, v67, v92
	v_mul_f32_e32 v94, v67, v94
	v_mul_f32_e32 v62, v67, v62
	v_mul_f32_e32 v67, v67, v96
	v_cndmask_b32_e32 v96, 0, v98, vcc
	v_med3_f32 v38, v38, s27, v33
	v_med3_f32 v42, v42, s27, v33
	v_med3_f32 v48, v48, s27, v33
	v_med3_f32 v50, v50, s27, v33
	v_med3_f32 v54, v54, s27, v33
	v_med3_f32 v56, v56, s27, v33
	v_med3_f32 v58, v58, s27, v33
	v_med3_f32 v64, v64, s27, v33
	v_med3_f32 v2, v2, s27, v33
	v_rndne_f32_e32 v35, v35
	v_rndne_f32_e32 v39, v39
	v_rndne_f32_e32 v41, v41
	v_rndne_f32_e32 v47, v47
	v_rndne_f32_e32 v51, v51
	v_rndne_f32_e32 v57, v57
	v_rndne_f32_e32 v59, v59
	v_rndne_f32_e32 v65, v65
	v_rndne_f32_e32 v66, v66
	v_cvt_i32_f32_e32 v34, v34
	v_cvt_i32_f32_e32 v36, v36
	v_cvt_i32_f32_e32 v40, v40
	v_cvt_i32_f32_e32 v44, v44
	v_cvt_i32_f32_sdwa v46, v46 dst_sel:WORD_1 dst_unused:UNUSED_PAD src0_sel:DWORD
	v_cvt_i32_f32_e32 v52, v52
	v_cvt_i32_f32_e32 v60, v60
	v_med3_f32 v37, v37, s27, v33
	v_med3_f32 v43, v43, s27, v33
	v_med3_f32 v45, v45, s27, v33
	v_med3_f32 v49, v49, s27, v33
	v_med3_f32 v53, v53, s27, v33
	v_med3_f32 v55, v55, s27, v33
	v_med3_f32 v61, v61, s27, v33
	v_rndne_f32_e32 v70, v70
	v_rndne_f32_e32 v78, v78
	v_rndne_f32_e32 v86, v86
	v_rndne_f32_e32 v94, v94
	v_mul_f32_e32 v71, v96, v71
	v_mul_f32_e32 v79, v96, v79
	v_mul_f32_e32 v87, v96, v87
	v_mul_f32_e32 v95, v96, v95
	v_cvt_i32_f32_sdwa v38, v38 dst_sel:WORD_1 dst_unused:UNUSED_PAD src0_sel:DWORD
	v_cvt_i32_f32_e32 v42, v42
	v_cvt_i32_f32_e32 v48, v48
	v_cvt_i32_f32_e32 v50, v50
	v_cvt_i32_f32_sdwa v54, v54 dst_sel:WORD_1 dst_unused:UNUSED_PAD src0_sel:DWORD
	v_cvt_i32_f32_e32 v56, v56
	v_cvt_i32_f32_e32 v58, v58
	v_cvt_i32_f32_sdwa v64, v64 dst_sel:WORD_1 dst_unused:UNUSED_PAD src0_sel:DWORD
	v_cvt_i32_f32_e32 v2, v2
	v_med3_f32 v35, v35, s27, v33
	v_med3_f32 v39, v39, s27, v33
	v_med3_f32 v41, v41, s27, v33
	v_med3_f32 v47, v47, s27, v33
; #define GAS __attribute__((address_space(1)))
; #define LAS __attribute__((address_space(3)))
; __device__ __forceinline__ unsigned pack4_i8(int a, int b, int c, int d) { return (unsigned)(a & 0xff) | ((unsigned)(b & 0xff) << 8) | ((unsigned)(c & 0xff) << 16) | ((unsigned)d << 24); }
; __device__ __forceinline__ int quant_i8(float x, float inv) { return (int)fminf(fmaxf(__builtin_rintf(x * inv), -127.0f), 127.0f); }
; template <int MAP> __device__ __forceinline__ void quant_item(const float* W, int K, int N, unsigned char* W8, const float* gk, const unsigned* cmax, LAS float* scr, int item, int lane, const LAS float* lmax = nullptr) {
;     ...
;     for (int j = 0; j < 4; ++j) { const int n = nn + 8 * j, dr = rowmap<MAP>(n0 + n, 0); const float cm = lmax ? lmax[n] : __uint_as_float(__hip_atomic_load(cmax + dr, __ATOMIC_RELAXED, __HIP_MEMORY_SCOPE_AGENT)); const float inv = cm > 0.f ? 127.0f / cm : 0.f;
;         const LAS float* sp = scr + (16 * c) * 33 + n; int q[16];
; #pragma unroll
;         for (int t = 0; t < 16; ++t) q[t] = quant_i8(sp[t * 33], inv);
;         u32x4 o; o.x = pack4_i8(q[0], q[1], q[2], q[3]); o.y = pack4_i8(q[4], q[5], q[6], q[7]); o.z = pack4_i8(q[8], q[9], q[10], q[11]); o.w = pack4_i8(q[12], q[13], q[14], q[15]);
;         *(GAS u32x4*)(W8 + (size_t)dr * K + k0 + 16 * c) = o; }
; template <int MAP> __device__ __forceinline__ void quant_strip(const float* W, int N, unsigned char* W8, const float* gk, unsigned* cmax, LAS unsigned char* lds, int strip, int wave, int lane) {
;     ...
;     for (int kb = wave; kb < DM / 128; kb += 8) quant_item<MAP>(W, DM, N, W8, gk, cmax, qscr, kb * (N / 32) + strip, lane, smax + 256);
	v_med3_f32 v51, v51, s27, v33
	v_med3_f32 v57, v57, s27, v33
	v_med3_f32 v59, v59, s27, v33
	v_med3_f32 v65, v65, s27, v33
	v_med3_f32 v66, v66, s27, v33
	v_rndne_f32_e32 v68, v68
	v_rndne_f32_e32 v72, v72
	v_rndne_f32_e32 v74, v74
	v_rndne_f32_e32 v76, v76
	v_rndne_f32_e32 v80, v80
	v_rndne_f32_e32 v82, v82
	v_rndne_f32_e32 v84, v84
	v_rndne_f32_e32 v88, v88
	v_rndne_f32_e32 v90, v90
	v_rndne_f32_e32 v92, v92
	v_rndne_f32_e32 v62, v62
	v_rndne_f32_e32 v67, v67
	v_mul_f32_e32 v69, v69, v96
	v_mul_f32_e32 v73, v96, v73
	v_mul_f32_e32 v75, v96, v75
	v_mul_f32_e32 v77, v96, v77
	v_mul_f32_e32 v81, v96, v81
	v_mul_f32_e32 v83, v96, v83
	v_mul_f32_e32 v85, v96, v85
	v_mul_f32_e32 v89, v96, v89
	v_mul_f32_e32 v91, v96, v91
	v_mul_f32_e32 v93, v96, v93
	v_mul_f32_e32 v63, v96, v63
	v_mul_f32_e32 v96, v96, v97
	v_cvt_i32_f32_e32 v37, v37
	v_cvt_i32_f32_e32 v43, v43
	v_cvt_i32_f32_e32 v45, v45
	v_cvt_i32_f32_e32 v49, v49
	v_cvt_i32_f32_e32 v53, v53
	v_cvt_i32_f32_sdwa v55, v55 dst_sel:WORD_1 dst_unused:UNUSED_PAD src0_sel:DWORD
	v_cvt_i32_f32_e32 v61, v61
	v_med3_f32 v70, v70, s27, v33
	v_med3_f32 v78, v78, s27, v33
	v_med3_f32 v86, v86, s27, v33
	v_med3_f32 v94, v94, s27, v33
	v_rndne_f32_e32 v71, v71
	v_rndne_f32_e32 v79, v79
	v_rndne_f32_e32 v87, v87
	v_rndne_f32_e32 v95, v95
	v_cvt_i32_f32_e32 v35, v35
	v_cvt_i32_f32_sdwa v39, v39 dst_sel:WORD_1 dst_unused:UNUSED_PAD src0_sel:DWORD
	v_cvt_i32_f32_e32 v41, v41
	v_cvt_i32_f32_sdwa v47, v47 dst_sel:WORD_1 dst_unused:UNUSED_PAD src0_sel:DWORD
	v_cvt_i32_f32_e32 v51, v51
	v_cvt_i32_f32_e32 v57, v57
	v_cvt_i32_f32_e32 v59, v59
	v_cvt_i32_f32_sdwa v65, v65 dst_sel:WORD_1 dst_unused:UNUSED_PAD src0_sel:DWORD
	v_cvt_i32_f32_e32 v66, v66
	v_med3_f32 v68, v68, s27, v33
	v_med3_f32 v72, v72, s27, v33
	v_med3_f32 v74, v74, s27, v33
	v_med3_f32 v76, v76, s27, v33
	v_med3_f32 v80, v80, s27, v33
	v_med3_f32 v82, v82, s27, v33
	v_med3_f32 v84, v84, s27, v33
	v_med3_f32 v88, v88, s27, v33
	v_med3_f32 v90, v90, s27, v33
	v_med3_f32 v92, v92, s27, v33
	v_med3_f32 v62, v62, s27, v33
	v_med3_f32 v67, v67, s27, v33
	v_rndne_f32_e32 v69, v69
	v_rndne_f32_e32 v73, v73
	v_rndne_f32_e32 v75, v75
	v_rndne_f32_e32 v77, v77
	v_rndne_f32_e32 v81, v81
	v_rndne_f32_e32 v83, v83
	v_rndne_f32_e32 v85, v85
	v_rndne_f32_e32 v89, v89
	v_rndne_f32_e32 v91, v91
	v_rndne_f32_e32 v93, v93
	v_rndne_f32_e32 v63, v63
	v_rndne_f32_e32 v96, v96
	v_cvt_i32_f32_e32 v70, v70
	v_cvt_i32_f32_e32 v78, v78
	v_cvt_i32_f32_e32 v86, v86
	v_cvt_i32_f32_e32 v94, v94
	v_med3_f32 v71, v71, s27, v33
	v_med3_f32 v79, v79, s27, v33
	v_med3_f32 v87, v87, s27, v33
	v_med3_f32 v95, v95, s27, v33
	v_cvt_i32_f32_e32 v68, v68
	v_cvt_i32_f32_sdwa v72, v72 dst_sel:WORD_1 dst_unused:UNUSED_PAD src0_sel:DWORD
	v_cvt_i32_f32_e32 v74, v74
	v_cvt_i32_f32_e32 v76, v76
	v_cvt_i32_f32_sdwa v80, v80 dst_sel:WORD_1 dst_unused:UNUSED_PAD src0_sel:DWORD
	v_cvt_i32_f32_e32 v82, v82
	v_cvt_i32_f32_e32 v84, v84
	v_cvt_i32_f32_sdwa v88, v88 dst_sel:WORD_1 dst_unused:UNUSED_PAD src0_sel:DWORD
	v_cvt_i32_f32_e32 v90, v90
	v_cvt_i32_f32_e32 v92, v92
	v_cvt_i32_f32_sdwa v62, v62 dst_sel:WORD_1 dst_unused:UNUSED_PAD src0_sel:DWORD
	v_cvt_i32_f32_e32 v67, v67
	v_med3_f32 v69, v69, s27, v33
	v_med3_f32 v73, v73, s27, v33
	v_med3_f32 v75, v75, s27, v33
	v_med3_f32 v77, v77, s27, v33
	v_med3_f32 v81, v81, s27, v33
	v_med3_f32 v83, v83, s27, v33
	v_med3_f32 v85, v85, s27, v33
	v_med3_f32 v89, v89, s27, v33
	v_med3_f32 v91, v91, s27, v33
	v_med3_f32 v93, v93, s27, v33
	v_med3_f32 v63, v63, s27, v33
	v_med3_f32 v96, v96, s27, v33
	v_cvt_i32_f32_e32 v71, v71
	v_cvt_i32_f32_e32 v79, v79
	v_cvt_i32_f32_e32 v87, v87
	v_cvt_i32_f32_e32 v95, v95
	v_cvt_i32_f32_e32 v69, v69
	v_cvt_i32_f32_sdwa v73, v73 dst_sel:WORD_1 dst_unused:UNUSED_PAD src0_sel:DWORD
	v_cvt_i32_f32_e32 v75, v75
	v_cvt_i32_f32_e32 v77, v77
	v_cvt_i32_f32_sdwa v81, v81 dst_sel:WORD_1 dst_unused:UNUSED_PAD src0_sel:DWORD
	v_cvt_i32_f32_e32 v83, v83
	v_cvt_i32_f32_e32 v85, v85
	v_cvt_i32_f32_sdwa v89, v89 dst_sel:WORD_1 dst_unused:UNUSED_PAD src0_sel:DWORD
	v_cvt_i32_f32_e32 v91, v91
	v_cvt_i32_f32_e32 v93, v93
	v_cvt_i32_f32_sdwa v63, v63 dst_sel:WORD_1 dst_unused:UNUSED_PAD src0_sel:DWORD
	v_cvt_i32_f32_e32 v96, v96
	v_lshlrev_b32_e32 v36, 8, v36
	v_perm_b32 v34, v40, v34, s28
	v_lshlrev_b32_e32 v40, 8, v44
	v_and_b32_e32 v44, 0xff0000, v46
	v_lshlrev_b32_e32 v46, 8, v52
	v_lshlrev_b32_e32 v52, 8, v60
	v_and_b32_e32 v38, 0xff0000, v38
	v_perm_b32 v42, v48, v42, s28
	v_and_b32_e32 v48, 0xff0000, v54
	v_perm_b32 v50, v56, v50, s28
	v_and_b32_e32 v54, 0xff0000, v64
	v_perm_b32 v2, v2, v58, s28
	v_and_b32_e32 v36, 0xff00, v36
	v_and_b32_e32 v40, 0xff00, v40
	v_and_b32_e32 v46, 0xff00, v46
	v_and_b32_e32 v52, 0xff00, v52
	v_lshlrev_b32_e32 v56, 8, v37
	v_lshlrev_b32_e32 v45, 8, v45
	v_perm_b32 v43, v49, v43, s28
	v_lshlrev_b32_e32 v49, 8, v53
	v_and_b32_e32 v53, 0xff0000, v55
	v_lshlrev_b32_e32 v55, 8, v61
	v_and_b32_e32 v39, 0xff0000, v39
	v_perm_b32 v41, v41, v35, s28
	v_and_b32_e32 v47, 0xff0000, v47
	v_perm_b32 v51, v57, v51, s28
	v_and_b32_e32 v57, 0xff0000, v65
	v_perm_b32 v58, v66, v59, s28
	v_or3_b32 v34, v34, v36, v38
	v_or3_b32 v35, v42, v40, v44
	v_or3_b32 v36, v50, v46, v48
	v_or3_b32 v37, v2, v52, v54
	v_and_b32_e32 v2, 0xff00, v56
	v_and_b32_e32 v38, 0xff00, v45
	v_and_b32_e32 v40, 0xff00, v49
	v_and_b32_e32 v42, 0xff00, v55
	v_lshlrev_b32_e32 v44, 8, v70
	v_lshlrev_b32_e32 v48, 8, v78
	v_lshlrev_b32_e32 v52, 8, v86
	v_lshlrev_b32_e32 v56, 8, v94
	v_and_b32_e32 v45, 0xff0000, v72
	v_perm_b32 v46, v74, v68, s28
	v_and_b32_e32 v49, 0xff0000, v80
	v_perm_b32 v50, v82, v76, s28
	v_and_b32_e32 v54, 0xff0000, v88
	v_perm_b32 v55, v90, v84, s28
	v_and_b32_e32 v59, 0xff0000, v62
	v_perm_b32 v60, v67, v92, s28
	global_store_dwordx4 v[16:17], v[34:37], off
	v_and_b32_e32 v16, 0xff00, v48
	v_and_b32_e32 v17, 0xff00, v52
	v_or3_b32 v34, v41, v2, v39
	v_or3_b32 v35, v43, v38, v47
	v_or3_b32 v36, v51, v40, v53
	v_or3_b32 v37, v58, v42, v57
	v_and_b32_e32 v2, 0xff00, v44
	v_and_b32_e32 v38, 0xff00, v56
	v_lshlrev_b32_e32 v39, 8, v71
	v_lshlrev_b32_e32 v42, 8, v79
	v_lshlrev_b32_e32 v47, 8, v87
	v_lshlrev_b32_e32 v52, 8, v95
	v_and_b32_e32 v40, 0xff0000, v73
	v_perm_b32 v41, v75, v69, s28
	v_and_b32_e32 v43, 0xff0000, v81
	v_perm_b32 v44, v83, v77, s28
	v_and_b32_e32 v48, 0xff0000, v89
	v_perm_b32 v51, v91, v85, s28
	v_and_b32_e32 v53, 0xff0000, v63
	v_perm_b32 v56, v96, v93, s28
	global_store_dwordx4 v[14:15], v[34:37], off
	v_or3_b32 v14, v46, v2, v45
	v_or3_b32 v15, v50, v16, v49
	v_or3_b32 v16, v55, v17, v54
	v_or3_b32 v17, v60, v38, v59
	v_and_b32_e32 v2, 0xff00, v39
	v_and_b32_e32 v34, 0xff00, v42
	v_and_b32_e32 v35, 0xff00, v47
	v_and_b32_e32 v36, 0xff00, v52
	global_store_dwordx4 v[12:13], v[14:17], off
	v_or3_b32 v12, v41, v2, v40
	v_or3_b32 v13, v44, v34, v43
	v_or3_b32 v14, v51, v35, v48
	v_or3_b32 v15, v56, v36, v53
	global_store_dwordx4 v[10:11], v[12:15], off
	s_waitcnt lgkmcnt(0)
	s_cbranch_scc1 .LBB0_807
	s_branch .LBB0_799

; #define GAS __attribute__((address_space(1)))
; #define LAS __attribute__((address_space(3)))
; #define LDS_WAIT() asm volatile("s_waitcnt lgkmcnt(0)" ::: "memory")
; __device__ __forceinline__ unsigned pack4_i8(int a, int b, int c, int d) { return (unsigned)(a & 0xff) | ((unsigned)(b & 0xff) << 8) | ((unsigned)(c & 0xff) << 16) | ((unsigned)d << 24); }
; __device__ __forceinline__ int quant_i8(float x, float inv) { return (int)fminf(fmaxf(__builtin_rintf(x * inv), -127.0f), 127.0f); }
; template <int MAP> __device__ __forceinline__ void quant_item(const float* W, int K, int N, unsigned char* W8, const float* gk, const unsigned* cmax, LAS float* scr, int item, int lane, const LAS float* lmax = nullptr) {
;     const int nblk = N / 32, kb = item / nblk, nb = item % nblk, k0 = 128 * kb, n0 = 32 * nb;
;     const int n4 = lane & 7, kr = lane >> 3;
;     f32x4 v[16];
; #pragma unroll
;     for (int i = 0; i < 16; ++i) v[i] = *(const GAS f32x4*)(W + (size_t)(k0 + 8 * i + kr) * N + n0 + 4 * n4);
; #pragma unroll
;     for (int i = 0; i < 16; ++i) v[i] = v[i] * (gk ? gk[k0 + 8 * i + kr] : 1.0f);
; #pragma unroll
;     for (int i = 0; i < 16; ++i) { LAS float* d = scr + (8 * i + kr) * 33 + 4 * n4; d[0] = v[i][0]; d[1] = v[i][1]; d[2] = v[i][2]; d[3] = v[i][3]; }
;     LDS_WAIT(); asm volatile("" ::: "memory");
;     const int c = lane & 7, nn = lane >> 3;
; #pragma unroll
;     for (int j = 0; j < 4; ++j) { const int n = nn + 8 * j, dr = rowmap<MAP>(n0 + n, 0); const float cm = lmax ? lmax[n] : __uint_as_float(__hip_atomic_load(cmax + dr, __ATOMIC_RELAXED, __HIP_MEMORY_SCOPE_AGENT)); const float inv = cm > 0.f ? 127.0f / cm : 0.f;
;         const LAS float* sp = scr + (16 * c) * 33 + n; int q[16];
; #pragma unroll
;         for (int t = 0; t < 16; ++t) q[t] = quant_i8(sp[t * 33], inv);
;         u32x4 o; o.x = pack4_i8(q[0], q[1], q[2], q[3]); o.y = pack4_i8(q[4], q[5], q[6], q[7]); o.z = pack4_i8(q[8], q[9], q[10], q[11]); o.w = pack4_i8(q[12], q[13], q[14], q[15]);
;         *(GAS u32x4*)(W8 + (size_t)dr * K + k0 + 16 * c) = o; }
.LBB0_818:
	s_mul_hi_i32 s0, s25, 0x2fa0be83
	s_lshr_b32 s1, s0, 31
	s_ashr_i32 s0, s0, 6
	s_add_i32 s0, s0, s1
	s_mul_i32 s1, s0, 0x158
	s_sub_i32 s5, s25, s1
	s_lshl_b32 s0, s0, 7
	s_lshl_b32 s4, s5, 5
	v_or_b32_e32 v10, s0, v20
	s_ashr_i32 s1, s0, 31
	s_lshl_b32 s6, s5, 6
	s_ashr_i32 s5, s4, 31
	v_ashrrev_i32_e32 v11, 31, v10
	v_or_b32_e32 v65, 24, v10
	v_or_b32_e32 v66, 32, v10
	v_or_b32_e32 v67, 40, v10
	v_or_b32_e32 v68, 48, v10
	v_or_b32_e32 v69, 56, v10
	v_or_b32_e32 v70, 64, v10
	v_or_b32_e32 v71, 0x48, v10
	v_or_b32_e32 v72, 0x50, v10
	v_or_b32_e32 v73, 0x58, v10
	v_or_b32_e32 v74, 0x60, v10
	v_or_b32_e32 v76, 0x68, v10
	v_or_b32_e32 v77, 0x70, v10
	v_lshl_add_u64 v[130:131], v[8:9], 0, s[0:1]
	s_and_b32 s0, s6, 0xffffff00
	s_and_b32 s1, s4, 0x60
	v_lshl_add_u64 v[14:15], s[4:5], 2, v[6:7]
	v_or_b32_e32 v16, 8, v10
	v_or_b32_e32 v17, 16, v10
	v_or_b32_e32 v80, 0x78, v10
	v_lshl_add_u64 v[12:13], v[10:11], 2, s[36:37]
	s_or_b32 s4, s1, s0
	v_mad_i64_i32 v[110:111], s[0:1], v65, s17, v[14:15]
	v_mad_i64_i32 v[106:107], s[0:1], v66, s17, v[14:15]
	v_mad_i64_i32 v[102:103], s[0:1], v67, s17, v[14:15]
	v_mad_i64_i32 v[98:99], s[0:1], v68, s17, v[14:15]
	v_mad_i64_i32 v[94:95], s[0:1], v69, s17, v[14:15]
	v_mad_i64_i32 v[90:91], s[0:1], v70, s17, v[14:15]
	v_mad_i64_i32 v[86:87], s[0:1], v71, s17, v[14:15]
	v_mad_i64_i32 v[82:83], s[0:1], v72, s17, v[14:15]
	v_mad_i64_i32 v[78:79], s[0:1], v73, s17, v[14:15]
	v_mad_i64_i32 v[74:75], s[0:1], v74, s17, v[14:15]
	v_mad_i64_i32 v[70:71], s[0:1], v76, s17, v[14:15]
	v_mad_i64_i32 v[66:67], s[0:1], v77, s17, v[14:15]
	global_load_dword v132, v[12:13], off
	global_load_dword v134, v[12:13], off offset:32
	global_load_dword v136, v[12:13], off offset:64
	global_load_dword v138, v[12:13], off offset:96
	global_load_dword v140, v[12:13], off offset:128
	global_load_dword v142, v[12:13], off offset:160
	global_load_dword v144, v[12:13], off offset:192
	global_load_dword v146, v[12:13], off offset:224
	global_load_dword v148, v[12:13], off offset:256
	global_load_dword v150, v[12:13], off offset:288
	global_load_dword v152, v[12:13], off offset:320
	global_load_dword v154, v[12:13], off offset:352
	global_load_dword v156, v[12:13], off offset:384
	global_load_dword v158, v[12:13], off offset:416
	global_load_dword v160, v[12:13], off offset:448
	global_load_dword v162, v[12:13], off offset:480
	v_mad_i64_i32 v[10:11], s[0:1], v10, s17, v[14:15]
	v_mad_i64_i32 v[12:13], s[0:1], v16, s17, v[14:15]
	v_mad_i64_i32 v[16:17], s[0:1], v17, s17, v[14:15]
	v_mad_i64_i32 v[14:15], s[0:1], v80, s17, v[14:15]
	global_load_dwordx4 v[66:69], v[66:67], off
	s_nop 0
	global_load_dwordx4 v[70:73], v[70:71], off
	s_nop 0
	global_load_dwordx4 v[74:77], v[74:75], off
	s_nop 0
	global_load_dwordx4 v[78:81], v[78:79], off
	s_nop 0
	global_load_dwordx4 v[82:85], v[82:83], off
	s_nop 0
	global_load_dwordx4 v[86:89], v[86:87], off
	s_nop 0
	global_load_dwordx4 v[90:93], v[90:91], off
	s_nop 0
	global_load_dwordx4 v[94:97], v[94:95], off
	s_nop 0
	global_load_dwordx4 v[98:101], v[98:99], off
	s_nop 0
	global_load_dwordx4 v[102:105], v[102:103], off
	s_nop 0
	global_load_dwordx4 v[106:109], v[106:107], off
	s_nop 0
	global_load_dwordx4 v[110:113], v[110:111], off
	s_nop 0
	global_load_dwordx4 v[114:117], v[16:17], off
	global_load_dwordx4 v[118:121], v[12:13], off
	global_load_dwordx4 v[122:125], v[10:11], off
	global_load_dwordx4 v[126:129], v[14:15], off
	v_add_u32_e32 v133, 0x600, v27
	v_add_u32_e32 v2, 0x420, v33
	v_add_u32_e32 v35, 0x428, v33
	v_add_u32_e32 v36, 0x840, v33
	v_add_u32_e32 v37, 0x848, v33
	v_add_u32_e32 v38, 0xc60, v33
	v_add_u32_e32 v39, 0xc68, v33
	v_add_u32_e32 v40, 0x1080, v33
	v_add_u32_e32 v41, 0x1088, v33
	v_add_u32_e32 v42, 0x14a0, v33
	v_add_u32_e32 v43, 0x14a8, v33
	v_add_u32_e32 v44, 0x18c0, v33
	v_add_u32_e32 v45, 0x18c8, v33
	v_add_u32_e32 v46, 0x1ce0, v33
	v_add_u32_e32 v47, 0x1ce8, v33
	v_add_u32_e32 v48, 0x2100, v33
	v_add_u32_e32 v49, 0x2108, v33
	v_add_u32_e32 v50, 0x2520, v33
	v_add_u32_e32 v51, 0x2528, v33
	v_add_u32_e32 v52, 0x2940, v33
	v_add_u32_e32 v53, 0x2948, v33
	v_add_u32_e32 v54, 0x2d60, v33
	v_add_u32_e32 v55, 0x2d68, v33
	v_add_u32_e32 v56, 0x3180, v33
	v_add_u32_e32 v57, 0x3188, v33
	v_add_u32_e32 v58, 0x35a0, v33
	v_add_u32_e32 v59, 0x35a8, v33
	v_add_u32_e32 v60, 0x39c0, v33
	v_add_u32_e32 v61, 0x39c8, v33
	v_add_u32_e32 v62, 0x3de0, v33
	v_add_u32_e32 v63, 0x3de8, v33
	v_add_u32_e32 v64, 0x400, v27
	v_or_b32_e32 v164, s4, v20
	v_or_b32_e32 v166, s4, v24
	v_or_b32_e32 v168, s4, v25
	v_or_b32_e32 v170, s4, v26
	v_ashrrev_i32_e32 v165, 31, v164
	v_ashrrev_i32_e32 v167, 31, v166
	v_mul_u32_u24_e32 v10, 0x1080, v164
	v_mov_b32_e32 v11, 0
	v_ashrrev_i32_e32 v169, 31, v168
	v_mul_u32_u24_e32 v12, 0x1080, v166
	v_mov_b32_e32 v13, 0
	v_lshl_add_u64 v[16:17], v[130:131], 0, v[10:11]
	v_ashrrev_i32_e32 v171, 31, v170
	v_mul_u32_u24_e32 v164, 0x1080, v168
	v_mov_b32_e32 v165, 0
	v_lshl_add_u64 v[14:15], v[130:131], 0, v[12:13]
	v_mul_u32_u24_e32 v166, 0x1080, v170
	v_mov_b32_e32 v167, 0
	v_lshl_add_u64 v[12:13], v[130:131], 0, v[164:165]
	v_lshl_add_u64 v[10:11], v[130:131], 0, v[166:167]
	s_add_i32 s26, s26, 8
	s_addk_i32 s25, 0xac0
	s_cmp_lt_u32 s26, 24
	s_waitcnt vmcnt(13)
	v_pk_mul_f32 v[76:77], v[76:77], v[156:157] op_sel_hi:[1,0]
	v_pk_mul_f32 v[72:73], v[72:73], v[158:159] op_sel_hi:[1,0]
	v_pk_mul_f32 v[68:69], v[68:69], v[160:161] op_sel_hi:[1,0]
	v_pk_mul_f32 v[66:67], v[66:67], v[160:161] op_sel_hi:[1,0]
	v_pk_mul_f32 v[70:71], v[70:71], v[158:159] op_sel_hi:[1,0]
	v_pk_mul_f32 v[74:75], v[74:75], v[156:157] op_sel_hi:[1,0]
	s_waitcnt vmcnt(12)
; #define LAS __attribute__((address_space(3)))
; #define LDS_WAIT() asm volatile("s_waitcnt lgkmcnt(0)" ::: "memory")
; __device__ __forceinline__ int quant_i8(float x, float inv) { return (int)fminf(fmaxf(__builtin_rintf(x * inv), -127.0f), 127.0f); }
; template <int MAP> __device__ __forceinline__ void quant_item(const float* W, int K, int N, unsigned char* W8, const float* gk, const unsigned* cmax, LAS float* scr, int item, int lane, const LAS float* lmax = nullptr) {
;     ...
;     for (int i = 0; i < 16; ++i) v[i] = v[i] * (gk ? gk[k0 + 8 * i + kr] : 1.0f);
; #pragma unroll
;     for (int i = 0; i < 16; ++i) { LAS float* d = scr + (8 * i + kr) * 33 + 4 * n4; d[0] = v[i][0]; d[1] = v[i][1]; d[2] = v[i][2]; d[3] = v[i][3]; }
;     LDS_WAIT(); asm volatile("" ::: "memory");
;     const int c = lane & 7, nn = lane >> 3;
; #pragma unroll
;     for (int j = 0; j < 4; ++j) { const int n = nn + 8 * j, dr = rowmap<MAP>(n0 + n, 0); const float cm = lmax ? lmax[n] : __uint_as_float(__hip_atomic_load(cmax + dr, __ATOMIC_RELAXED, __HIP_MEMORY_SCOPE_AGENT)); const float inv = cm > 0.f ? 127.0f / cm : 0.f;
;         const LAS float* sp = scr + (16 * c) * 33 + n; int q[16];
; #pragma unroll
;         for (int t = 0; t < 16; ++t) q[t] = quant_i8(sp[t * 33], inv);
	v_pk_mul_f32 v[80:81], v[80:81], v[154:155] op_sel_hi:[1,0]
	v_pk_mul_f32 v[78:79], v[78:79], v[154:155] op_sel_hi:[1,0]
	s_waitcnt vmcnt(11)
	v_pk_mul_f32 v[84:85], v[84:85], v[152:153] op_sel_hi:[1,0]
	v_pk_mul_f32 v[82:83], v[82:83], v[152:153] op_sel_hi:[1,0]
	s_waitcnt vmcnt(10)
	v_pk_mul_f32 v[88:89], v[88:89], v[150:151] op_sel_hi:[1,0]
	s_waitcnt vmcnt(1)
	v_pk_mul_f32 v[122:123], v[122:123], v[132:133] op_sel_hi:[1,0]
	v_pk_mul_f32 v[86:87], v[86:87], v[150:151] op_sel_hi:[1,0]
	v_pk_mul_f32 v[92:93], v[92:93], v[148:149] op_sel_hi:[1,0]
	v_pk_mul_f32 v[90:91], v[90:91], v[148:149] op_sel_hi:[1,0]
	v_pk_mul_f32 v[96:97], v[96:97], v[146:147] op_sel_hi:[1,0]
	v_pk_mul_f32 v[94:95], v[94:95], v[146:147] op_sel_hi:[1,0]
	v_pk_mul_f32 v[100:101], v[100:101], v[144:145] op_sel_hi:[1,0]
	v_pk_mul_f32 v[98:99], v[98:99], v[144:145] op_sel_hi:[1,0]
	v_pk_mul_f32 v[104:105], v[104:105], v[142:143] op_sel_hi:[1,0]
	v_pk_mul_f32 v[102:103], v[102:103], v[142:143] op_sel_hi:[1,0]
	v_pk_mul_f32 v[108:109], v[108:109], v[140:141] op_sel_hi:[1,0]
	v_pk_mul_f32 v[106:107], v[106:107], v[140:141] op_sel_hi:[1,0]
	v_pk_mul_f32 v[112:113], v[112:113], v[138:139] op_sel_hi:[1,0]
	v_pk_mul_f32 v[110:111], v[110:111], v[138:139] op_sel_hi:[1,0]
	v_pk_mul_f32 v[116:117], v[116:117], v[136:137] op_sel_hi:[1,0]
	v_pk_mul_f32 v[114:115], v[114:115], v[136:137] op_sel_hi:[1,0]
	v_pk_mul_f32 v[120:121], v[120:121], v[134:135] op_sel_hi:[1,0]
	v_pk_mul_f32 v[118:119], v[118:119], v[134:135] op_sel_hi:[1,0]
	v_pk_mul_f32 v[124:125], v[124:125], v[132:133] op_sel_hi:[1,0]
	s_waitcnt vmcnt(0)
	v_pk_mul_f32 v[128:129], v[128:129], v[162:163] op_sel_hi:[1,0]
	v_pk_mul_f32 v[126:127], v[126:127], v[162:163] op_sel_hi:[1,0]
	ds_write2_b32 v33, v122, v123 offset1:1
	ds_write2_b32 v33, v124, v125 offset0:2 offset1:3
	ds_write2_b32 v2, v118, v119 offset1:1
	ds_write2_b32 v35, v120, v121 offset1:1
	ds_write2_b32 v36, v114, v115 offset1:1
	ds_write2_b32 v37, v116, v117 offset1:1
	ds_write2_b32 v38, v110, v111 offset1:1
	ds_write2_b32 v39, v112, v113 offset1:1
	ds_write2_b32 v40, v106, v107 offset1:1
	ds_write2_b32 v41, v108, v109 offset1:1
	ds_write2_b32 v42, v102, v103 offset1:1
	ds_write2_b32 v43, v104, v105 offset1:1
	ds_write2_b32 v44, v98, v99 offset1:1
	ds_write2_b32 v45, v100, v101 offset1:1
	ds_write2_b32 v46, v94, v95 offset1:1
	ds_write2_b32 v47, v96, v97 offset1:1
	ds_write2_b32 v48, v90, v91 offset1:1
	ds_write2_b32 v49, v92, v93 offset1:1
	ds_write2_b32 v50, v86, v87 offset1:1
	ds_write2_b32 v51, v88, v89 offset1:1
	ds_write2_b32 v52, v82, v83 offset1:1
	ds_write2_b32 v53, v84, v85 offset1:1
	ds_write2_b32 v54, v78, v79 offset1:1
	ds_write2_b32 v55, v80, v81 offset1:1
	ds_write2_b32 v56, v74, v75 offset1:1
	ds_write2_b32 v57, v76, v77 offset1:1
	ds_write2_b32 v58, v70, v71 offset1:1
	ds_write2_b32 v59, v72, v73 offset1:1
	ds_write2_b32 v60, v66, v67 offset1:1
	ds_write2_b32 v61, v68, v69 offset1:1
	ds_write2_b32 v62, v126, v127 offset1:1
	ds_write2_b32 v63, v128, v129 offset1:1
	s_waitcnt lgkmcnt(0)
	ds_read2_b32 v[36:37], v27 offset1:8
	ds_read2_b32 v[38:39], v27 offset0:33 offset1:41
	ds_read2_b32 v[40:41], v27 offset0:66 offset1:74
	ds_read2_b32 v[42:43], v27 offset0:99 offset1:107
	ds_read2_b32 v[44:45], v27 offset0:132 offset1:140
	ds_read2_b32 v[46:47], v27 offset0:165 offset1:173
	ds_read2_b32 v[48:49], v27 offset0:198 offset1:206
	ds_read2_b32 v[50:51], v27 offset0:231 offset1:239
	ds_read2_b32 v[52:53], v64 offset0:8 offset1:16
	ds_read2_b32 v[54:55], v64 offset0:41 offset1:49
	ds_read2_b32 v[56:57], v64 offset0:74 offset1:82
	ds_read2_b32 v[58:59], v64 offset0:107 offset1:115
	ds_read2_b32 v[60:61], v64 offset0:140 offset1:148
	ds_read2_b32 v[62:63], v64 offset0:173 offset1:181
	ds_read2_b32 v[66:67], v64 offset0:206 offset1:214
	ds_read2_b32 v[68:69], v64 offset0:239 offset1:247
	ds_read2_b32 v[70:71], v27 offset0:16 offset1:24
	ds_read2_b32 v[72:73], v27 offset0:49 offset1:57
	ds_read2_b32 v[74:75], v27 offset0:82 offset1:90
	ds_read2_b32 v[76:77], v27 offset0:115 offset1:123
	ds_read2_b32 v[78:79], v27 offset0:148 offset1:156
	ds_read2_b32 v[80:81], v27 offset0:181 offset1:189
	ds_read2_b32 v[82:83], v27 offset0:214 offset1:222
	ds_read2_b32 v[84:85], v27 offset0:247 offset1:255
	ds_read2_b32 v[86:87], v64 offset0:24 offset1:32
	ds_read2_b32 v[88:89], v64 offset0:57 offset1:65
	ds_read2_b32 v[90:91], v64 offset0:90 offset1:98
	ds_read2_b32 v[92:93], v64 offset0:123 offset1:131
	ds_read2_b32 v[94:95], v64 offset0:156 offset1:164
	ds_read2_b32 v[96:97], v64 offset0:189 offset1:197
	ds_read2_b32 v[64:65], v64 offset0:222 offset1:230
	ds_read2_b32 v[98:99], v133 offset0:127 offset1:135
	ds_read_b32 v2, v1
	ds_read_b32 v35, v28
	ds_read_b32 v100, v29
	ds_read_b32 v101, v30
	s_waitcnt lgkmcnt(3)
	v_div_scale_f32 v102, s[0:1], v2, v2, s19
	s_waitcnt lgkmcnt(2)
	v_div_scale_f32 v104, s[0:1], v35, v35, s19
	v_rcp_f32_e32 v110, v102
	v_rcp_f32_e32 v111, v104
	s_waitcnt lgkmcnt(1)
	v_div_scale_f32 v106, s[4:5], v100, v100, s19
	s_waitcnt lgkmcnt(0)
; #define LAS __attribute__((address_space(3)))
; __device__ __forceinline__ unsigned pack4_i8(int a, int b, int c, int d) { return (unsigned)(a & 0xff) | ((unsigned)(b & 0xff) << 8) | ((unsigned)(c & 0xff) << 16) | ((unsigned)d << 24); }
; __device__ __forceinline__ int quant_i8(float x, float inv) { return (int)fminf(fmaxf(__builtin_rintf(x * inv), -127.0f), 127.0f); }
; template <int MAP> __device__ __forceinline__ void quant_item(const float* W, int K, int N, unsigned char* W8, const float* gk, const unsigned* cmax, LAS float* scr, int item, int lane, const LAS float* lmax = nullptr) {
;     ...
;     for (int j = 0; j < 4; ++j) { const int n = nn + 8 * j, dr = rowmap<MAP>(n0 + n, 0); const float cm = lmax ? lmax[n] : __uint_as_float(__hip_atomic_load(cmax + dr, __ATOMIC_RELAXED, __HIP_MEMORY_SCOPE_AGENT)); const float inv = cm > 0.f ? 127.0f / cm : 0.f;
;         const LAS float* sp = scr + (16 * c) * 33 + n; int q[16];
; #pragma unroll
;         for (int t = 0; t < 16; ++t) q[t] = quant_i8(sp[t * 33], inv);
;         u32x4 o; o.x = pack4_i8(q[0], q[1], q[2], q[3]); o.y = pack4_i8(q[4], q[5], q[6], q[7]); o.z = pack4_i8(q[8], q[9], q[10], q[11]); o.w = pack4_i8(q[12], q[13], q[14], q[15]);
	v_div_scale_f32 v108, s[6:7], v101, v101, s19
	v_rcp_f32_e32 v112, v106
	v_rcp_f32_e32 v113, v108
	v_fma_f32 v114, -v102, v110, 1.0
	v_div_scale_f32 v103, vcc, s19, v2, s19
	v_fma_f32 v115, -v104, v111, 1.0
	v_fmac_f32_e32 v110, v114, v110
	v_div_scale_f32 v105, s[0:1], s19, v35, s19
	v_fmac_f32_e32 v111, v115, v111
	v_mul_f32_e32 v114, v103, v110
	v_fma_f32 v116, -v106, v112, 1.0
	v_mul_f32_e32 v115, v105, v111
	v_fma_f32 v118, -v102, v114, v103
	v_div_scale_f32 v107, s[4:5], s19, v100, s19
	v_fma_f32 v117, -v108, v113, 1.0
	v_fmac_f32_e32 v112, v116, v112
	v_fma_f32 v119, -v104, v115, v105
	v_fmac_f32_e32 v114, v118, v110
	v_div_scale_f32 v109, s[6:7], s19, v101, s19
	v_fmac_f32_e32 v113, v117, v113
	v_mul_f32_e32 v116, v107, v112
	v_fmac_f32_e32 v115, v119, v111
	v_fma_f32 v102, -v102, v114, v103
	v_mul_f32_e32 v117, v109, v113
	v_fma_f32 v120, -v106, v116, v107
	v_fma_f32 v103, -v104, v115, v105
	v_div_fmas_f32 v102, v102, v110, v114
	s_mov_b64 vcc, s[0:1]
	v_fma_f32 v121, -v108, v117, v109
	v_fmac_f32_e32 v116, v120, v112
	v_div_fixup_f32 v102, v102, v2, s19
	v_div_fmas_f32 v103, v103, v111, v115
	v_cmp_lt_f32_e32 vcc, 0, v2
	v_fmac_f32_e32 v117, v121, v113
	v_fma_f32 v104, -v106, v116, v107
	v_cndmask_b32_e32 v2, 0, v102, vcc
	s_mov_b64 vcc, s[4:5]
	v_fma_f32 v105, -v108, v117, v109
	v_div_fixup_f32 v102, v103, v35, s19
	v_cmp_lt_f32_e64 s[0:1], 0, v35
	v_div_fmas_f32 v35, v104, v112, v116
	s_mov_b64 vcc, s[6:7]
	v_mul_f32_e32 v36, v36, v2
	v_mul_f32_e32 v38, v2, v38
	v_mul_f32_e32 v40, v2, v40
	v_mul_f32_e32 v42, v2, v42
	v_mul_f32_e32 v44, v2, v44
	v_mul_f32_e32 v46, v2, v46
	v_mul_f32_e32 v48, v2, v48
	v_mul_f32_e32 v50, v2, v50
	v_mul_f32_e32 v52, v2, v52
	v_mul_f32_e32 v54, v2, v54
	v_mul_f32_e32 v56, v2, v56
	v_mul_f32_e32 v58, v2, v58
	v_mul_f32_e32 v60, v2, v60
	v_mul_f32_e32 v62, v2, v62
	v_mul_f32_e32 v66, v2, v66
	v_mul_f32_e32 v2, v2, v68
	v_cndmask_b32_e64 v68, 0, v102, s[0:1]
	v_div_fixup_f32 v35, v35, v100, s19
	v_cmp_lt_f32_e64 s[0:1], 0, v100
	v_div_fmas_f32 v100, v105, v113, v117
	v_rndne_f32_e32 v36, v36
	v_rndne_f32_e32 v38, v38
	v_rndne_f32_e32 v42, v42
	v_rndne_f32_e32 v46, v46
	v_rndne_f32_e32 v48, v48
	v_rndne_f32_e32 v54, v54
	v_rndne_f32_e32 v62, v62
	v_mul_f32_e32 v37, v37, v68
	v_mul_f32_e32 v39, v68, v39
	v_mul_f32_e32 v41, v68, v41
	v_mul_f32_e32 v43, v68, v43
	v_mul_f32_e32 v45, v68, v45
	v_mul_f32_e32 v47, v68, v47
	v_mul_f32_e32 v49, v68, v49
	v_mul_f32_e32 v51, v68, v51
	v_mul_f32_e32 v53, v68, v53
	v_mul_f32_e32 v55, v68, v55
	v_mul_f32_e32 v57, v68, v57
	v_mul_f32_e32 v59, v68, v59
	v_mul_f32_e32 v61, v68, v61
	v_mul_f32_e32 v63, v68, v63
	v_mul_f32_e32 v67, v68, v67
	v_mul_f32_e32 v68, v68, v69
	v_cndmask_b32_e64 v35, 0, v35, s[0:1]
	v_div_fixup_f32 v69, v100, v101, s19
	v_cmp_lt_f32_e32 vcc, 0, v101
	v_rndne_f32_e32 v40, v40
	v_rndne_f32_e32 v44, v44
	v_rndne_f32_e32 v50, v50
	v_rndne_f32_e32 v52, v52
	v_rndne_f32_e32 v56, v56
	v_rndne_f32_e32 v58, v58
	v_rndne_f32_e32 v60, v60
	v_rndne_f32_e32 v66, v66
	v_rndne_f32_e32 v2, v2
	v_med3_f32 v36, v36, s23, v34
	v_med3_f32 v38, v38, s23, v34
	v_med3_f32 v42, v42, s23, v34
	v_med3_f32 v46, v46, s23, v34
	v_med3_f32 v48, v48, s23, v34
	v_med3_f32 v54, v54, s23, v34
	v_med3_f32 v62, v62, s23, v34
	v_rndne_f32_e32 v39, v39
	v_rndne_f32_e32 v45, v45
	v_rndne_f32_e32 v47, v47
	v_rndne_f32_e32 v51, v51
	v_rndne_f32_e32 v55, v55
	v_rndne_f32_e32 v57, v57
	v_rndne_f32_e32 v63, v63
	v_mul_f32_e32 v72, v35, v72
	v_mul_f32_e32 v80, v35, v80
	v_mul_f32_e32 v88, v35, v88
	v_mul_f32_e32 v96, v35, v96
	v_cndmask_b32_e32 v69, 0, v69, vcc
	v_med3_f32 v40, v40, s23, v34
	v_med3_f32 v44, v44, s23, v34
	v_med3_f32 v50, v50, s23, v34
	v_med3_f32 v52, v52, s23, v34
	v_med3_f32 v56, v56, s23, v34
	v_med3_f32 v58, v58, s23, v34
	v_med3_f32 v60, v60, s23, v34
	v_med3_f32 v66, v66, s23, v34
	v_med3_f32 v2, v2, s23, v34
	v_rndne_f32_e32 v37, v37
	v_rndne_f32_e32 v41, v41
	v_rndne_f32_e32 v43, v43
	v_rndne_f32_e32 v49, v49
	v_rndne_f32_e32 v53, v53
	v_rndne_f32_e32 v59, v59
	v_rndne_f32_e32 v61, v61
	v_rndne_f32_e32 v67, v67
	v_rndne_f32_e32 v68, v68
	v_mul_f32_e32 v70, v70, v35
	v_mul_f32_e32 v74, v35, v74
	v_mul_f32_e32 v76, v35, v76
	v_mul_f32_e32 v78, v35, v78
	v_mul_f32_e32 v82, v35, v82
	v_mul_f32_e32 v84, v35, v84
	v_mul_f32_e32 v86, v35, v86
	v_mul_f32_e32 v90, v35, v90
	v_mul_f32_e32 v92, v35, v92
	v_mul_f32_e32 v94, v35, v94
	v_mul_f32_e32 v64, v35, v64
	v_mul_f32_e32 v35, v35, v98
	v_cvt_i32_f32_e32 v36, v36
	v_cvt_i32_f32_e32 v38, v38
	v_cvt_i32_f32_e32 v42, v42
	v_cvt_i32_f32_e32 v46, v46
	v_cvt_i32_f32_sdwa v48, v48 dst_sel:WORD_1 dst_unused:UNUSED_PAD src0_sel:DWORD
	v_cvt_i32_f32_e32 v54, v54
	v_cvt_i32_f32_e32 v62, v62
	v_med3_f32 v39, v39, s23, v34
	v_med3_f32 v45, v45, s23, v34
	v_med3_f32 v47, v47, s23, v34
	v_med3_f32 v51, v51, s23, v34
	v_med3_f32 v55, v55, s23, v34
	v_med3_f32 v57, v57, s23, v34
	v_med3_f32 v63, v63, s23, v34
	v_rndne_f32_e32 v72, v72
	v_rndne_f32_e32 v80, v80
	v_rndne_f32_e32 v88, v88
	v_rndne_f32_e32 v96, v96
	v_mul_f32_e32 v73, v69, v73
	v_mul_f32_e32 v81, v69, v81
	v_mul_f32_e32 v89, v69, v89
	v_mul_f32_e32 v97, v69, v97
	v_cvt_i32_f32_sdwa v40, v40 dst_sel:WORD_1 dst_unused:UNUSED_PAD src0_sel:DWORD
	v_cvt_i32_f32_e32 v44, v44
	v_cvt_i32_f32_e32 v50, v50
	v_cvt_i32_f32_e32 v52, v52
	v_cvt_i32_f32_sdwa v56, v56 dst_sel:WORD_1 dst_unused:UNUSED_PAD src0_sel:DWORD
	v_cvt_i32_f32_e32 v58, v58
	v_cvt_i32_f32_e32 v60, v60
	v_cvt_i32_f32_sdwa v66, v66 dst_sel:WORD_1 dst_unused:UNUSED_PAD src0_sel:DWORD
	v_cvt_i32_f32_e32 v2, v2
	v_med3_f32 v37, v37, s23, v34
	v_med3_f32 v41, v41, s23, v34
	v_med3_f32 v43, v43, s23, v34
	v_med3_f32 v49, v49, s23, v34
; #define GAS __attribute__((address_space(1)))
; #define LAS __attribute__((address_space(3)))
; __device__ __forceinline__ unsigned pack4_i8(int a, int b, int c, int d) { return (unsigned)(a & 0xff) | ((unsigned)(b & 0xff) << 8) | ((unsigned)(c & 0xff) << 16) | ((unsigned)d << 24); }
; __device__ __forceinline__ int quant_i8(float x, float inv) { return (int)fminf(fmaxf(__builtin_rintf(x * inv), -127.0f), 127.0f); }
; template <int MAP> __device__ __forceinline__ void quant_item(const float* W, int K, int N, unsigned char* W8, const float* gk, const unsigned* cmax, LAS float* scr, int item, int lane, const LAS float* lmax = nullptr) {
;     ...
;     for (int j = 0; j < 4; ++j) { const int n = nn + 8 * j, dr = rowmap<MAP>(n0 + n, 0); const float cm = lmax ? lmax[n] : __uint_as_float(__hip_atomic_load(cmax + dr, __ATOMIC_RELAXED, __HIP_MEMORY_SCOPE_AGENT)); const float inv = cm > 0.f ? 127.0f / cm : 0.f;
;         const LAS float* sp = scr + (16 * c) * 33 + n; int q[16];
; #pragma unroll
;         for (int t = 0; t < 16; ++t) q[t] = quant_i8(sp[t * 33], inv);
;         u32x4 o; o.x = pack4_i8(q[0], q[1], q[2], q[3]); o.y = pack4_i8(q[4], q[5], q[6], q[7]); o.z = pack4_i8(q[8], q[9], q[10], q[11]); o.w = pack4_i8(q[12], q[13], q[14], q[15]);
;         *(GAS u32x4*)(W8 + (size_t)dr * K + k0 + 16 * c) = o; }
; template <int MAP> __device__ __forceinline__ void quant_strip(const float* W, int N, unsigned char* W8, const float* gk, unsigned* cmax, LAS unsigned char* lds, int strip, int wave, int lane) {
;     ...
;     for (int kb = wave; kb < DM / 128; kb += 8) quant_item<MAP>(W, DM, N, W8, gk, cmax, qscr, kb * (N / 32) + strip, lane, smax + 256);
	v_med3_f32 v53, v53, s23, v34
	v_med3_f32 v59, v59, s23, v34
	v_med3_f32 v61, v61, s23, v34
	v_med3_f32 v67, v67, s23, v34
	v_med3_f32 v68, v68, s23, v34
	v_rndne_f32_e32 v70, v70
	v_rndne_f32_e32 v74, v74
	v_rndne_f32_e32 v76, v76
	v_rndne_f32_e32 v78, v78
	v_rndne_f32_e32 v82, v82
	v_rndne_f32_e32 v84, v84
	v_rndne_f32_e32 v86, v86
	v_rndne_f32_e32 v90, v90
	v_rndne_f32_e32 v92, v92
	v_rndne_f32_e32 v94, v94
	v_rndne_f32_e32 v64, v64
	v_rndne_f32_e32 v35, v35
	v_mul_f32_e32 v71, v71, v69
	v_mul_f32_e32 v75, v69, v75
	v_mul_f32_e32 v77, v69, v77
	v_mul_f32_e32 v79, v69, v79
	v_mul_f32_e32 v83, v69, v83
	v_mul_f32_e32 v85, v69, v85
	v_mul_f32_e32 v87, v69, v87
	v_mul_f32_e32 v91, v69, v91
	v_mul_f32_e32 v93, v69, v93
	v_mul_f32_e32 v95, v69, v95
	v_mul_f32_e32 v65, v69, v65
	v_mul_f32_e32 v69, v69, v99
	v_cvt_i32_f32_e32 v39, v39
	v_cvt_i32_f32_e32 v45, v45
	v_cvt_i32_f32_e32 v47, v47
	v_cvt_i32_f32_e32 v51, v51
	v_cvt_i32_f32_e32 v55, v55
	v_cvt_i32_f32_sdwa v57, v57 dst_sel:WORD_1 dst_unused:UNUSED_PAD src0_sel:DWORD
	v_cvt_i32_f32_e32 v63, v63
	v_med3_f32 v72, v72, s23, v34
	v_med3_f32 v80, v80, s23, v34
	v_med3_f32 v88, v88, s23, v34
	v_med3_f32 v96, v96, s23, v34
	v_rndne_f32_e32 v73, v73
	v_rndne_f32_e32 v81, v81
	v_rndne_f32_e32 v89, v89
	v_rndne_f32_e32 v97, v97
	v_cvt_i32_f32_e32 v37, v37
	v_cvt_i32_f32_sdwa v41, v41 dst_sel:WORD_1 dst_unused:UNUSED_PAD src0_sel:DWORD
	v_cvt_i32_f32_e32 v43, v43
	v_cvt_i32_f32_sdwa v49, v49 dst_sel:WORD_1 dst_unused:UNUSED_PAD src0_sel:DWORD
	v_cvt_i32_f32_e32 v53, v53
	v_cvt_i32_f32_e32 v59, v59
	v_cvt_i32_f32_e32 v61, v61
	v_cvt_i32_f32_sdwa v67, v67 dst_sel:WORD_1 dst_unused:UNUSED_PAD src0_sel:DWORD
	v_cvt_i32_f32_e32 v68, v68
	v_med3_f32 v70, v70, s23, v34
	v_med3_f32 v74, v74, s23, v34
	v_med3_f32 v76, v76, s23, v34
	v_med3_f32 v78, v78, s23, v34
	v_med3_f32 v82, v82, s23, v34
	v_med3_f32 v84, v84, s23, v34
	v_med3_f32 v86, v86, s23, v34
	v_med3_f32 v90, v90, s23, v34
	v_med3_f32 v92, v92, s23, v34
	v_med3_f32 v94, v94, s23, v34
	v_med3_f32 v64, v64, s23, v34
	v_med3_f32 v35, v35, s23, v34
	v_rndne_f32_e32 v71, v71
	v_rndne_f32_e32 v75, v75
	v_rndne_f32_e32 v77, v77
	v_rndne_f32_e32 v79, v79
	v_rndne_f32_e32 v83, v83
	v_rndne_f32_e32 v85, v85
	v_rndne_f32_e32 v87, v87
	v_rndne_f32_e32 v91, v91
	v_rndne_f32_e32 v93, v93
	v_rndne_f32_e32 v95, v95
	v_rndne_f32_e32 v65, v65
	v_rndne_f32_e32 v69, v69
	v_cvt_i32_f32_e32 v72, v72
	v_cvt_i32_f32_e32 v80, v80
	v_cvt_i32_f32_e32 v88, v88
	v_cvt_i32_f32_e32 v96, v96
	v_med3_f32 v73, v73, s23, v34
	v_med3_f32 v81, v81, s23, v34
	v_med3_f32 v89, v89, s23, v34
	v_med3_f32 v97, v97, s23, v34
	v_cvt_i32_f32_e32 v70, v70
	v_cvt_i32_f32_sdwa v74, v74 dst_sel:WORD_1 dst_unused:UNUSED_PAD src0_sel:DWORD
	v_cvt_i32_f32_e32 v76, v76
	v_cvt_i32_f32_e32 v78, v78
	v_cvt_i32_f32_sdwa v82, v82 dst_sel:WORD_1 dst_unused:UNUSED_PAD src0_sel:DWORD
	v_cvt_i32_f32_e32 v84, v84
	v_cvt_i32_f32_e32 v86, v86
	v_cvt_i32_f32_sdwa v90, v90 dst_sel:WORD_1 dst_unused:UNUSED_PAD src0_sel:DWORD
	v_cvt_i32_f32_e32 v92, v92
	v_cvt_i32_f32_e32 v94, v94
	v_cvt_i32_f32_sdwa v64, v64 dst_sel:WORD_1 dst_unused:UNUSED_PAD src0_sel:DWORD
	v_cvt_i32_f32_e32 v35, v35
	v_med3_f32 v71, v71, s23, v34
	v_med3_f32 v75, v75, s23, v34
	v_med3_f32 v77, v77, s23, v34
	v_med3_f32 v79, v79, s23, v34
	v_med3_f32 v83, v83, s23, v34
	v_med3_f32 v85, v85, s23, v34
	v_med3_f32 v87, v87, s23, v34
	v_med3_f32 v91, v91, s23, v34
	v_med3_f32 v93, v93, s23, v34
	v_med3_f32 v95, v95, s23, v34
	v_med3_f32 v65, v65, s23, v34
	v_med3_f32 v69, v69, s23, v34
	v_cvt_i32_f32_e32 v73, v73
	v_cvt_i32_f32_e32 v81, v81
	v_cvt_i32_f32_e32 v89, v89
	v_cvt_i32_f32_e32 v97, v97
	v_cvt_i32_f32_e32 v71, v71
	v_cvt_i32_f32_sdwa v75, v75 dst_sel:WORD_1 dst_unused:UNUSED_PAD src0_sel:DWORD
	v_cvt_i32_f32_e32 v77, v77
	v_cvt_i32_f32_e32 v79, v79
	v_cvt_i32_f32_sdwa v83, v83 dst_sel:WORD_1 dst_unused:UNUSED_PAD src0_sel:DWORD
	v_cvt_i32_f32_e32 v85, v85
	v_cvt_i32_f32_e32 v87, v87
	v_cvt_i32_f32_sdwa v91, v91 dst_sel:WORD_1 dst_unused:UNUSED_PAD src0_sel:DWORD
	v_cvt_i32_f32_e32 v93, v93
	v_cvt_i32_f32_e32 v95, v95
	v_cvt_i32_f32_sdwa v65, v65 dst_sel:WORD_1 dst_unused:UNUSED_PAD src0_sel:DWORD
	v_cvt_i32_f32_e32 v69, v69
	v_lshlrev_b32_e32 v38, 8, v38
	v_perm_b32 v36, v42, v36, s24
	v_lshlrev_b32_e32 v42, 8, v46
	v_and_b32_e32 v46, 0xff0000, v48
	v_lshlrev_b32_e32 v48, 8, v54
	v_lshlrev_b32_e32 v54, 8, v62
	v_and_b32_e32 v40, 0xff0000, v40
	v_perm_b32 v44, v50, v44, s24
	v_and_b32_e32 v50, 0xff0000, v56
	v_perm_b32 v52, v58, v52, s24
	v_and_b32_e32 v56, 0xff0000, v66
	v_perm_b32 v2, v2, v60, s24
	v_and_b32_e32 v38, 0xff00, v38
	v_and_b32_e32 v42, 0xff00, v42
	v_and_b32_e32 v48, 0xff00, v48
	v_and_b32_e32 v54, 0xff00, v54
	v_lshlrev_b32_e32 v58, 8, v39
	v_lshlrev_b32_e32 v47, 8, v47
	v_perm_b32 v45, v51, v45, s24
	v_lshlrev_b32_e32 v51, 8, v55
	v_and_b32_e32 v55, 0xff0000, v57
	v_lshlrev_b32_e32 v57, 8, v63
	v_and_b32_e32 v41, 0xff0000, v41
	v_perm_b32 v43, v43, v37, s24
	v_and_b32_e32 v49, 0xff0000, v49
	v_perm_b32 v53, v59, v53, s24
	v_and_b32_e32 v59, 0xff0000, v67
	v_perm_b32 v60, v68, v61, s24
	v_or3_b32 v36, v36, v38, v40
	v_or3_b32 v37, v44, v42, v46
	v_or3_b32 v38, v52, v48, v50
	v_or3_b32 v39, v2, v54, v56
	v_and_b32_e32 v2, 0xff00, v58
	v_and_b32_e32 v40, 0xff00, v47
	v_and_b32_e32 v42, 0xff00, v51
	v_and_b32_e32 v44, 0xff00, v57
	v_lshlrev_b32_e32 v46, 8, v72
	v_lshlrev_b32_e32 v50, 8, v80
	v_lshlrev_b32_e32 v54, 8, v88
	v_lshlrev_b32_e32 v58, 8, v96
	v_and_b32_e32 v47, 0xff0000, v74
	v_perm_b32 v48, v76, v70, s24
	v_and_b32_e32 v51, 0xff0000, v82
	v_perm_b32 v52, v84, v78, s24
	v_and_b32_e32 v56, 0xff0000, v90
	v_perm_b32 v57, v92, v86, s24
	v_and_b32_e32 v61, 0xff0000, v64
	v_perm_b32 v35, v35, v94, s24
	global_store_dwordx4 v[16:17], v[36:39], off
	v_and_b32_e32 v16, 0xff00, v50
	v_and_b32_e32 v17, 0xff00, v54
	v_or3_b32 v36, v43, v2, v41
	v_or3_b32 v37, v45, v40, v49
	v_or3_b32 v38, v53, v42, v55
	v_or3_b32 v39, v60, v44, v59
	v_and_b32_e32 v2, 0xff00, v46
	v_and_b32_e32 v40, 0xff00, v58
	v_lshlrev_b32_e32 v41, 8, v73
	v_lshlrev_b32_e32 v44, 8, v81
	v_lshlrev_b32_e32 v49, 8, v89
	v_lshlrev_b32_e32 v54, 8, v97
	v_and_b32_e32 v42, 0xff0000, v75
	v_perm_b32 v43, v77, v71, s24
	v_and_b32_e32 v45, 0xff0000, v83
	v_perm_b32 v46, v85, v79, s24
	v_and_b32_e32 v50, 0xff0000, v91
	v_perm_b32 v53, v93, v87, s24
	v_and_b32_e32 v55, 0xff0000, v65
	v_perm_b32 v58, v69, v95, s24
	global_store_dwordx4 v[14:15], v[36:39], off
	v_or3_b32 v14, v48, v2, v47
	v_or3_b32 v15, v52, v16, v51
	v_or3_b32 v16, v57, v17, v56
	v_or3_b32 v17, v35, v40, v61
	v_and_b32_e32 v2, 0xff00, v41
	v_and_b32_e32 v35, 0xff00, v44
	v_and_b32_e32 v36, 0xff00, v49
	v_and_b32_e32 v37, 0xff00, v54
	global_store_dwordx4 v[12:13], v[14:17], off
	v_or3_b32 v12, v43, v2, v42
	v_or3_b32 v13, v46, v35, v45
	v_or3_b32 v14, v53, v36, v50
	v_or3_b32 v15, v58, v37, v55
	global_store_dwordx4 v[10:11], v[12:15], off
	s_waitcnt lgkmcnt(0)
	s_cbranch_scc1 .LBB0_818
	s_branch .LBB0_810

; #define GAS __attribute__((address_space(1)))
; __device__ __forceinline__ float bf_lo(unsigned w) { return __uint_as_float(w << 16); }
; __device__ __forceinline__ float bf_hi(unsigned w) { return __uint_as_float(w & 0xffff0000u); }
; __device__ __forceinline__ unsigned pack4_i8(int a, int b, int c, int d) { return (unsigned)(a & 0xff) | ((unsigned)(b & 0xff) << 8) | ((unsigned)(c & 0xff) << 16) | ((unsigned)d << 24); }
; __device__ __forceinline__ int quant_i8(float x, float inv) { return (int)fminf(fmaxf(__builtin_rintf(x * inv), -127.0f), 127.0f); }
; __device__ __forceinline__ void quant_row_i8(const bf16* hrow, unsigned char* qrow, float amax, int lane) {
;     const float inv = amax > 0.f ? 127.0f / amax : 0.f;
; #pragma unroll
;     for (int it = 0; it < 4; ++it) { const GAS u32x4* src = (const GAS u32x4*)(hrow + it * 1024 + lane * 16); const u32x4 a = src[0], b = src[1];
;         u32x4 o;
;         o.x = pack4_i8(quant_i8(bf_lo(a.x), inv), quant_i8(bf_hi(a.x), inv), quant_i8(bf_lo(a.y), inv), quant_i8(bf_hi(a.y), inv));
;         o.y = pack4_i8(quant_i8(bf_lo(a.z), inv), quant_i8(bf_hi(a.z), inv), quant_i8(bf_lo(a.w), inv), quant_i8(bf_hi(a.w), inv));
;         o.z = pack4_i8(quant_i8(bf_lo(b.x), inv), quant_i8(bf_hi(b.x), inv), quant_i8(bf_lo(b.y), inv), quant_i8(bf_hi(b.y), inv));
;         o.w = pack4_i8(quant_i8(bf_lo(b.z), inv), quant_i8(bf_hi(b.z), inv), quant_i8(bf_lo(b.w), inv), quant_i8(bf_hi(b.w), inv));
;         *(GAS u32x4*)(qrow + it * 1024 + lane * 16) = o; }
; __global__ void __launch_bounds__(NWAVES * 64, 2) fwd_kernel(Args args) {
;     ...
;         for (int m = gw; m < MTOK; m += NGW) quant_row_i8(HB + (size_t)m * DM, A8 + (size_t)m * DM, __uint_as_float(__hip_atomic_load(rmaxU + m, __ATOMIC_RELAXED, __HIP_MEMORY_SCOPE_AGENT)), lane);
.LBB0_1120:
	s_or_b64 exec, exec, s[0:1]
	v_readlane_b32 s36, v244, 2
	s_cmpk_gt_i32 s18, 0x3fff
	v_readlane_b32 s50, v244, 16
	v_readlane_b32 s51, v244, 17
	s_waitcnt lgkmcnt(0)
	s_barrier
	v_readlane_b32 s37, v244, 3
	v_readlane_b32 s38, v244, 4
	v_readlane_b32 s39, v244, 5
	v_readlane_b32 s40, v244, 6
	v_readlane_b32 s41, v244, 7
	v_readlane_b32 s42, v244, 8
	v_readlane_b32 s43, v244, 9
	v_readlane_b32 s44, v244, 10
	v_readlane_b32 s45, v244, 11
	v_readlane_b32 s46, v244, 12
	v_readlane_b32 s47, v244, 13
	v_readlane_b32 s48, v244, 14
	v_readlane_b32 s49, v244, 15
	s_cbranch_scc1 .LBB0_1123
	s_ashr_i32 s19, s18, 31
	s_lshl_b64 s[0:1], s[18:19], 2
	s_add_u32 s14, s0, 0x85800
	v_and_b32_e32 v1, 0x3f0, v1
	s_addc_u32 s15, s1, 0
	s_mul_i32 s2, s18, 0x1080
	s_mov_b32 s3, 0
	v_readlane_b32 s98, v244, 14
	v_readlane_b32 s99, v244, 15
	s_ashr_i32 s21, s20, 31
	s_waitcnt vmcnt(47)
	v_add_u32_e32 v2, s2, v1
	s_lshl_b64 s[4:5], s[18:19], 13
	v_and_b32_e32 v1, 63, v0
	s_lshl_b64 s[0:1], s[20:21], 2
	v_mov_b32_e32 v3, s3
	s_mul_i32 s2, s20, 0x1080
	s_mov_b32 s3, 0
	v_lshl_or_b32 v4, v1, 5, s4
	v_mov_b32_e32 v5, s5
	s_lshl_b64 s[4:5], s[20:21], 13
	v_mov_b32_e32 v1, 0
	s_mov_b32 s17, 0x42fe0000
	s_mov_b64 s[6:7], 0x2b500000
	s_mov_b32 s19, 0x2b500000
	s_mov_b32 s21, 0xc2fe0000
	s_waitcnt vmcnt(45)
	v_mov_b32_e32 v12, 0x42fe0000
	s_mov_b32 s23, 0x40c0c00
	s_mov_b32 s24, 0
	s_mov_b64 s[8:9], 0x2b500800
	s_mov_b64 s[10:11], 0x2b501000
	s_mov_b32 s25, 0x2b501000
	s_mov_b64 s[12:13], 0x2b501800
	s_mov_b32 s26, s18
.LBB0_1122:
	v_lshl_add_u64 v[6:7], s[50:51], 0, v[4:5]
	s_waitcnt vmcnt(40)
	v_add_co_u32_e32 v22, vcc, s19, v6
	s_add_u32 s40, s50, s14
	s_nop 0
	v_addc_co_u32_e32 v23, vcc, 0, v7, vcc
	s_addc_u32 s41, s51, s15
	v_lshl_add_u64 v[18:19], v[6:7], 0, s[6:7]
	v_add_co_u32_e32 v10, vcc, s25, v6
	v_lshl_add_u64 v[8:9], s[98:99], 0, v[2:3]
	s_nop 0
	v_addc_co_u32_e32 v11, vcc, 0, v7, vcc
	global_load_dword v13, v1, s[40:41] sc1
	global_load_dwordx4 v[14:17], v[10:11], off offset:-4096
	s_nop 0
	global_load_dwordx4 v[18:21], v[18:19], off offset:16
	v_add_co_u32_e32 v8, vcc, s24, v8
	v_lshl_add_u64 v[24:25], v[6:7], 0, s[8:9]
	s_nop 0
	v_addc_co_u32_e32 v9, vcc, 0, v9, vcc
	s_waitcnt vmcnt(42)
	v_lshl_add_u64 v[26:27], v[6:7], 0, s[10:11]
	v_lshl_add_u64 v[6:7], v[6:7], 0, s[12:13]
	s_add_i32 s26, s26, s20
	s_add_u32 s14, s14, s0
	s_addc_u32 s15, s15, s1
	v_lshl_add_u64 v[2:3], v[2:3], 0, s[2:3]
	v_lshl_add_u64 v[4:5], v[4:5], 0, s[4:5]
	s_cmpk_gt_i32 s26, 0x3fff
	s_waitcnt vmcnt(2)
	v_div_scale_f32 v28, s[28:29], v13, v13, s17
	v_rcp_f32_e32 v38, v28
	v_div_scale_f32 v29, vcc, s17, v13, s17
	s_waitcnt vmcnt(1)
	v_lshlrev_b32_e32 v30, 16, v14
	v_fma_f32 v39, -v28, v38, 1.0
	v_fmac_f32_e32 v38, v39, v38
	v_mul_f32_e32 v39, v29, v38
	v_fma_f32 v40, -v28, v39, v29
	v_fmac_f32_e32 v39, v40, v38
	v_fma_f32 v28, -v28, v39, v29
	v_div_fmas_f32 v28, v28, v38, v39
	v_div_fixup_f32 v28, v28, v13, s17
	v_cmp_lt_f32_e32 vcc, 0, v13
	v_and_b32_e32 v14, 0xffff0000, v14
	v_lshlrev_b32_e32 v32, 16, v16
	v_and_b32_e32 v16, 0xffff0000, v16
	s_waitcnt vmcnt(0)
	v_lshlrev_b32_e32 v34, 16, v18
	v_and_b32_e32 v18, 0xffff0000, v18
	v_lshlrev_b32_e32 v36, 16, v20
	v_and_b32_e32 v20, 0xffff0000, v20
	v_cndmask_b32_e32 v13, 0, v28, vcc
	v_lshlrev_b32_e32 v31, 16, v15
	v_and_b32_e32 v15, 0xffff0000, v15
	v_lshlrev_b32_e32 v33, 16, v17
	v_and_b32_e32 v17, 0xffff0000, v17
	v_lshlrev_b32_e32 v35, 16, v19
	v_and_b32_e32 v19, 0xffff0000, v19
	v_lshlrev_b32_e32 v37, 16, v21
	v_and_b32_e32 v21, 0xffff0000, v21
	v_mul_f32_e32 v14, v13, v14
	v_mul_f32_e32 v16, v13, v16
	v_mul_f32_e32 v18, v13, v18
	v_mul_f32_e32 v20, v13, v20
	v_mul_f32_e32 v28, v13, v30
	v_mul_f32_e32 v29, v13, v31
	v_mul_f32_e32 v15, v13, v15
	v_mul_f32_e32 v30, v13, v32
	v_mul_f32_e32 v31, v13, v33
	v_mul_f32_e32 v17, v13, v17
	v_mul_f32_e32 v32, v13, v34
	v_mul_f32_e32 v33, v13, v35
	v_mul_f32_e32 v19, v13, v19
	v_mul_f32_e32 v34, v13, v36
	v_mul_f32_e32 v35, v13, v37
	v_mul_f32_e32 v21, v13, v21
	v_rndne_f32_e32 v14, v14
	v_rndne_f32_e32 v16, v16
	v_rndne_f32_e32 v18, v18
	v_rndne_f32_e32 v20, v20
	v_rndne_f32_e32 v28, v28
	v_rndne_f32_e32 v29, v29
	v_rndne_f32_e32 v15, v15
	v_rndne_f32_e32 v30, v30
	v_rndne_f32_e32 v31, v31
	v_rndne_f32_e32 v17, v17
	v_rndne_f32_e32 v32, v32
	v_rndne_f32_e32 v33, v33
	v_rndne_f32_e32 v19, v19
	v_rndne_f32_e32 v34, v34
	v_rndne_f32_e32 v35, v35
	v_rndne_f32_e32 v21, v21
	v_med3_f32 v14, v14, s21, v12
	v_med3_f32 v16, v16, s21, v12
	v_med3_f32 v18, v18, s21, v12
	v_med3_f32 v20, v20, s21, v12
	v_med3_f32 v28, v28, s21, v12
	v_med3_f32 v29, v29, s21, v12
	v_med3_f32 v15, v15, s21, v12
	v_med3_f32 v30, v30, s21, v12
	v_med3_f32 v31, v31, s21, v12
	v_med3_f32 v17, v17, s21, v12
	v_med3_f32 v32, v32, s21, v12
	v_med3_f32 v33, v33, s21, v12
	v_med3_f32 v19, v19, s21, v12
	v_med3_f32 v34, v34, s21, v12
	v_med3_f32 v35, v35, s21, v12
	v_med3_f32 v21, v21, s21, v12
	v_cvt_i32_f32_e32 v14, v14
	v_cvt_i32_f32_e32 v16, v16
	v_cvt_i32_f32_e32 v18, v18
	v_cvt_i32_f32_e32 v20, v20
	v_cvt_i32_f32_e32 v28, v28
	v_cvt_i32_f32_sdwa v29, v29 dst_sel:WORD_1 dst_unused:UNUSED_PAD src0_sel:DWORD
	v_cvt_i32_f32_e32 v15, v15
	v_cvt_i32_f32_e32 v30, v30
	v_cvt_i32_f32_sdwa v31, v31 dst_sel:WORD_1 dst_unused:UNUSED_PAD src0_sel:DWORD
	v_cvt_i32_f32_e32 v17, v17
	v_cvt_i32_f32_e32 v32, v32
	v_cvt_i32_f32_sdwa v33, v33 dst_sel:WORD_1 dst_unused:UNUSED_PAD src0_sel:DWORD
	v_cvt_i32_f32_e32 v19, v19
	v_cvt_i32_f32_e32 v34, v34
	v_cvt_i32_f32_sdwa v35, v35 dst_sel:WORD_1 dst_unused:UNUSED_PAD src0_sel:DWORD
	v_cvt_i32_f32_e32 v21, v21
	v_lshlrev_b32_e32 v14, 8, v14
	v_lshlrev_b32_e32 v16, 8, v16
	v_lshlrev_b32_e32 v18, 8, v18
	v_lshlrev_b32_e32 v20, 8, v20
	v_and_b32_e32 v29, 0xff0000, v29
	v_perm_b32 v15, v15, v28, s23
	v_and_b32_e32 v28, 0xff0000, v31
	v_perm_b32 v17, v17, v30, s23
	v_and_b32_e32 v30, 0xff0000, v33
	v_perm_b32 v19, v19, v32, s23
	v_and_b32_e32 v31, 0xff0000, v35
	v_perm_b32 v21, v21, v34, s23
	v_and_b32_e32 v14, 0xff00, v14
	v_and_b32_e32 v16, 0xff00, v16
	v_and_b32_e32 v18, 0xff00, v18
	v_and_b32_e32 v20, 0xff00, v20
	v_or3_b32 v14, v15, v14, v29
	v_or3_b32 v15, v17, v16, v28
	v_or3_b32 v16, v19, v18, v30
	v_or3_b32 v17, v21, v20, v31
	global_store_dwordx4 v[8:9], v[14:17], off
	global_load_dwordx4 v[14:17], v[22:23], off offset:2048
	s_nop 0
	global_load_dwordx4 v[18:21], v[24:25], off offset:16
	s_waitcnt vmcnt(1)
; #define GAS __attribute__((address_space(1)))
; __device__ __forceinline__ float bf_lo(unsigned w) { return __uint_as_float(w << 16); }
; __device__ __forceinline__ float bf_hi(unsigned w) { return __uint_as_float(w & 0xffff0000u); }
; __device__ __forceinline__ unsigned pack4_i8(int a, int b, int c, int d) { return (unsigned)(a & 0xff) | ((unsigned)(b & 0xff) << 8) | ((unsigned)(c & 0xff) << 16) | ((unsigned)d << 24); }
; __device__ __forceinline__ int quant_i8(float x, float inv) { return (int)fminf(fmaxf(__builtin_rintf(x * inv), -127.0f), 127.0f); }
; __device__ __forceinline__ void quant_row_i8(const bf16* hrow, unsigned char* qrow, float amax, int lane) {
;     ...
;     for (int it = 0; it < 4; ++it) { const GAS u32x4* src = (const GAS u32x4*)(hrow + it * 1024 + lane * 16); const u32x4 a = src[0], b = src[1];
;         u32x4 o;
;         o.x = pack4_i8(quant_i8(bf_lo(a.x), inv), quant_i8(bf_hi(a.x), inv), quant_i8(bf_lo(a.y), inv), quant_i8(bf_hi(a.y), inv));
;         o.y = pack4_i8(quant_i8(bf_lo(a.z), inv), quant_i8(bf_hi(a.z), inv), quant_i8(bf_lo(a.w), inv), quant_i8(bf_hi(a.w), inv));
;         o.z = pack4_i8(quant_i8(bf_lo(b.x), inv), quant_i8(bf_hi(b.x), inv), quant_i8(bf_lo(b.y), inv), quant_i8(bf_hi(b.y), inv));
;         o.w = pack4_i8(quant_i8(bf_lo(b.z), inv), quant_i8(bf_hi(b.z), inv), quant_i8(bf_lo(b.w), inv), quant_i8(bf_hi(b.w), inv));
;         *(GAS u32x4*)(qrow + it * 1024 + lane * 16) = o; }
	v_lshlrev_b32_e32 v22, 16, v14
	v_and_b32_e32 v14, 0xffff0000, v14
	v_lshlrev_b32_e32 v24, 16, v16
	v_and_b32_e32 v16, 0xffff0000, v16
	s_waitcnt vmcnt(0)
	v_lshlrev_b32_e32 v28, 16, v18
	v_and_b32_e32 v18, 0xffff0000, v18
	v_lshlrev_b32_e32 v30, 16, v20
	v_and_b32_e32 v20, 0xffff0000, v20
	v_lshlrev_b32_e32 v23, 16, v15
	v_and_b32_e32 v15, 0xffff0000, v15
	v_lshlrev_b32_e32 v25, 16, v17
	v_and_b32_e32 v17, 0xffff0000, v17
	v_lshlrev_b32_e32 v29, 16, v19
	v_and_b32_e32 v19, 0xffff0000, v19
	v_lshlrev_b32_e32 v31, 16, v21
	v_and_b32_e32 v21, 0xffff0000, v21
	v_mul_f32_e32 v14, v13, v14
	v_mul_f32_e32 v16, v13, v16
	v_mul_f32_e32 v18, v13, v18
	v_mul_f32_e32 v20, v13, v20
	v_mul_f32_e32 v22, v13, v22
	v_mul_f32_e32 v23, v13, v23
	v_mul_f32_e32 v15, v13, v15
	v_mul_f32_e32 v24, v13, v24
	v_mul_f32_e32 v25, v13, v25
	v_mul_f32_e32 v17, v13, v17
	v_mul_f32_e32 v28, v13, v28
	v_mul_f32_e32 v29, v13, v29
	v_mul_f32_e32 v19, v13, v19
	v_mul_f32_e32 v30, v13, v30
	v_mul_f32_e32 v31, v13, v31
	v_mul_f32_e32 v21, v13, v21
	v_rndne_f32_e32 v14, v14
	v_rndne_f32_e32 v16, v16
	v_rndne_f32_e32 v18, v18
	v_rndne_f32_e32 v20, v20
	v_rndne_f32_e32 v22, v22
	v_rndne_f32_e32 v23, v23
	v_rndne_f32_e32 v15, v15
	v_rndne_f32_e32 v24, v24
	v_rndne_f32_e32 v25, v25
	v_rndne_f32_e32 v17, v17
	v_rndne_f32_e32 v28, v28
	v_rndne_f32_e32 v29, v29
	v_rndne_f32_e32 v19, v19
	v_rndne_f32_e32 v30, v30
	v_rndne_f32_e32 v31, v31
	v_rndne_f32_e32 v21, v21
	v_med3_f32 v14, v14, s21, v12
	v_med3_f32 v16, v16, s21, v12
	v_med3_f32 v18, v18, s21, v12
	v_med3_f32 v20, v20, s21, v12
	v_med3_f32 v22, v22, s21, v12
	v_med3_f32 v23, v23, s21, v12
	v_med3_f32 v15, v15, s21, v12
	v_med3_f32 v24, v24, s21, v12
	v_med3_f32 v25, v25, s21, v12
	v_med3_f32 v17, v17, s21, v12
	v_med3_f32 v28, v28, s21, v12
	v_med3_f32 v29, v29, s21, v12
	v_med3_f32 v19, v19, s21, v12
	v_med3_f32 v30, v30, s21, v12
	v_med3_f32 v31, v31, s21, v12
	v_med3_f32 v21, v21, s21, v12
	v_cvt_i32_f32_e32 v14, v14
	v_cvt_i32_f32_e32 v16, v16
	v_cvt_i32_f32_e32 v18, v18
	v_cvt_i32_f32_e32 v20, v20
	v_cvt_i32_f32_e32 v22, v22
	v_cvt_i32_f32_sdwa v23, v23 dst_sel:WORD_1 dst_unused:UNUSED_PAD src0_sel:DWORD
	v_cvt_i32_f32_e32 v15, v15
	v_cvt_i32_f32_e32 v24, v24
	v_cvt_i32_f32_sdwa v25, v25 dst_sel:WORD_1 dst_unused:UNUSED_PAD src0_sel:DWORD
	v_cvt_i32_f32_e32 v17, v17
	v_cvt_i32_f32_e32 v28, v28
	v_cvt_i32_f32_sdwa v29, v29 dst_sel:WORD_1 dst_unused:UNUSED_PAD src0_sel:DWORD
	v_cvt_i32_f32_e32 v19, v19
	v_cvt_i32_f32_e32 v30, v30
	v_cvt_i32_f32_sdwa v31, v31 dst_sel:WORD_1 dst_unused:UNUSED_PAD src0_sel:DWORD
	v_cvt_i32_f32_e32 v21, v21
	v_lshlrev_b32_e32 v14, 8, v14
	v_lshlrev_b32_e32 v16, 8, v16
	v_lshlrev_b32_e32 v18, 8, v18
	v_lshlrev_b32_e32 v20, 8, v20
	v_and_b32_e32 v23, 0xff0000, v23
	v_perm_b32 v15, v15, v22, s23
	v_and_b32_e32 v22, 0xff0000, v25
	v_perm_b32 v17, v17, v24, s23
	v_and_b32_e32 v24, 0xff0000, v29
	v_perm_b32 v19, v19, v28, s23
	v_and_b32_e32 v25, 0xff0000, v31
	v_perm_b32 v21, v21, v30, s23
	v_and_b32_e32 v14, 0xff00, v14
	v_and_b32_e32 v16, 0xff00, v16
	v_and_b32_e32 v18, 0xff00, v18
	v_and_b32_e32 v20, 0xff00, v20
	v_or3_b32 v14, v15, v14, v23
	v_or3_b32 v15, v17, v16, v22
	v_or3_b32 v16, v19, v18, v24
	v_or3_b32 v17, v21, v20, v25
	global_store_dwordx4 v[8:9], v[14:17], off offset:1024
	global_load_dwordx4 v[14:17], v[10:11], off
	s_nop 0
	global_load_dwordx4 v[18:21], v[26:27], off offset:16
	s_waitcnt vmcnt(1)
	v_lshlrev_b32_e32 v22, 16, v14
	v_and_b32_e32 v14, 0xffff0000, v14
	v_lshlrev_b32_e32 v24, 16, v16
	v_and_b32_e32 v16, 0xffff0000, v16
	s_waitcnt vmcnt(0)
; #define GAS __attribute__((address_space(1)))
; __device__ __forceinline__ float bf_lo(unsigned w) { return __uint_as_float(w << 16); }
; __device__ __forceinline__ float bf_hi(unsigned w) { return __uint_as_float(w & 0xffff0000u); }
; __device__ __forceinline__ unsigned pack4_i8(int a, int b, int c, int d) { return (unsigned)(a & 0xff) | ((unsigned)(b & 0xff) << 8) | ((unsigned)(c & 0xff) << 16) | ((unsigned)d << 24); }
; __device__ __forceinline__ int quant_i8(float x, float inv) { return (int)fminf(fmaxf(__builtin_rintf(x * inv), -127.0f), 127.0f); }
; __device__ __forceinline__ void quant_row_i8(const bf16* hrow, unsigned char* qrow, float amax, int lane) {
;     ...
;     for (int it = 0; it < 4; ++it) { const GAS u32x4* src = (const GAS u32x4*)(hrow + it * 1024 + lane * 16); const u32x4 a = src[0], b = src[1];
;         u32x4 o;
;         o.x = pack4_i8(quant_i8(bf_lo(a.x), inv), quant_i8(bf_hi(a.x), inv), quant_i8(bf_lo(a.y), inv), quant_i8(bf_hi(a.y), inv));
;         o.y = pack4_i8(quant_i8(bf_lo(a.z), inv), quant_i8(bf_hi(a.z), inv), quant_i8(bf_lo(a.w), inv), quant_i8(bf_hi(a.w), inv));
;         o.z = pack4_i8(quant_i8(bf_lo(b.x), inv), quant_i8(bf_hi(b.x), inv), quant_i8(bf_lo(b.y), inv), quant_i8(bf_hi(b.y), inv));
;         o.w = pack4_i8(quant_i8(bf_lo(b.z), inv), quant_i8(bf_hi(b.z), inv), quant_i8(bf_lo(b.w), inv), quant_i8(bf_hi(b.w), inv));
;         *(GAS u32x4*)(qrow + it * 1024 + lane * 16) = o; }
	v_lshlrev_b32_e32 v26, 16, v18
	v_and_b32_e32 v18, 0xffff0000, v18
	v_lshlrev_b32_e32 v28, 16, v20
	v_and_b32_e32 v20, 0xffff0000, v20
	v_lshlrev_b32_e32 v23, 16, v15
	v_and_b32_e32 v15, 0xffff0000, v15
	v_lshlrev_b32_e32 v25, 16, v17
	v_and_b32_e32 v17, 0xffff0000, v17
	v_lshlrev_b32_e32 v27, 16, v19
	v_and_b32_e32 v19, 0xffff0000, v19
	v_lshlrev_b32_e32 v29, 16, v21
	v_and_b32_e32 v21, 0xffff0000, v21
	v_mul_f32_e32 v14, v13, v14
	v_mul_f32_e32 v16, v13, v16
	v_mul_f32_e32 v18, v13, v18
	v_mul_f32_e32 v20, v13, v20
	v_mul_f32_e32 v22, v13, v22
	v_mul_f32_e32 v23, v13, v23
	v_mul_f32_e32 v15, v13, v15
	v_mul_f32_e32 v24, v13, v24
	v_mul_f32_e32 v25, v13, v25
	v_mul_f32_e32 v17, v13, v17
	v_mul_f32_e32 v26, v13, v26
	v_mul_f32_e32 v27, v13, v27
	v_mul_f32_e32 v19, v13, v19
	v_mul_f32_e32 v28, v13, v28
	v_mul_f32_e32 v29, v13, v29
	v_mul_f32_e32 v21, v13, v21
	v_rndne_f32_e32 v14, v14
	v_rndne_f32_e32 v16, v16
	v_rndne_f32_e32 v18, v18
	v_rndne_f32_e32 v20, v20
	v_rndne_f32_e32 v22, v22
	v_rndne_f32_e32 v23, v23
	v_rndne_f32_e32 v15, v15
	v_rndne_f32_e32 v24, v24
	v_rndne_f32_e32 v25, v25
	v_rndne_f32_e32 v17, v17
	v_rndne_f32_e32 v26, v26
	v_rndne_f32_e32 v27, v27
	v_rndne_f32_e32 v19, v19
	v_rndne_f32_e32 v28, v28
	v_rndne_f32_e32 v29, v29
	v_rndne_f32_e32 v21, v21
	v_med3_f32 v14, v14, s21, v12
	v_med3_f32 v16, v16, s21, v12
	v_med3_f32 v18, v18, s21, v12
	v_med3_f32 v20, v20, s21, v12
	v_med3_f32 v22, v22, s21, v12
	v_med3_f32 v23, v23, s21, v12
	v_med3_f32 v15, v15, s21, v12
	v_med3_f32 v24, v24, s21, v12
	v_med3_f32 v25, v25, s21, v12
	v_med3_f32 v17, v17, s21, v12
	v_med3_f32 v26, v26, s21, v12
	v_med3_f32 v27, v27, s21, v12
	v_med3_f32 v19, v19, s21, v12
	v_med3_f32 v28, v28, s21, v12
	v_med3_f32 v29, v29, s21, v12
	v_med3_f32 v21, v21, s21, v12
	v_cvt_i32_f32_e32 v14, v14
	v_cvt_i32_f32_e32 v16, v16
	v_cvt_i32_f32_e32 v18, v18
	v_cvt_i32_f32_e32 v20, v20
	v_cvt_i32_f32_e32 v22, v22
	v_cvt_i32_f32_sdwa v23, v23 dst_sel:WORD_1 dst_unused:UNUSED_PAD src0_sel:DWORD
	v_cvt_i32_f32_e32 v15, v15
	v_cvt_i32_f32_e32 v24, v24
	v_cvt_i32_f32_sdwa v25, v25 dst_sel:WORD_1 dst_unused:UNUSED_PAD src0_sel:DWORD
	v_cvt_i32_f32_e32 v17, v17
	v_cvt_i32_f32_e32 v26, v26
	v_cvt_i32_f32_sdwa v27, v27 dst_sel:WORD_1 dst_unused:UNUSED_PAD src0_sel:DWORD
	v_cvt_i32_f32_e32 v19, v19
	v_cvt_i32_f32_e32 v28, v28
	v_cvt_i32_f32_sdwa v29, v29 dst_sel:WORD_1 dst_unused:UNUSED_PAD src0_sel:DWORD
	v_cvt_i32_f32_e32 v21, v21
	v_lshlrev_b32_e32 v14, 8, v14
	v_lshlrev_b32_e32 v16, 8, v16
	v_lshlrev_b32_e32 v18, 8, v18
	v_lshlrev_b32_e32 v20, 8, v20
	v_and_b32_e32 v23, 0xff0000, v23
	v_perm_b32 v15, v15, v22, s23
	v_and_b32_e32 v22, 0xff0000, v25
	v_perm_b32 v17, v17, v24, s23
	v_and_b32_e32 v24, 0xff0000, v27
	v_perm_b32 v19, v19, v26, s23
	v_and_b32_e32 v25, 0xff0000, v29
	v_perm_b32 v21, v21, v28, s23
	v_and_b32_e32 v14, 0xff00, v14
	v_and_b32_e32 v16, 0xff00, v16
	v_and_b32_e32 v18, 0xff00, v18
	v_and_b32_e32 v20, 0xff00, v20
	v_or3_b32 v14, v15, v14, v23
	v_or3_b32 v15, v17, v16, v22
	v_or3_b32 v16, v19, v18, v24
	v_or3_b32 v17, v21, v20, v25
	global_store_dwordx4 v[8:9], v[14:17], off offset:2048
	global_load_dwordx4 v[14:17], v[10:11], off offset:2048
	s_nop 0
	global_load_dwordx4 v[18:21], v[6:7], off offset:16
	s_waitcnt vmcnt(1)
	v_lshlrev_b32_e32 v6, 16, v14
	v_and_b32_e32 v7, 0xffff0000, v14
	v_lshlrev_b32_e32 v10, 16, v15
	v_and_b32_e32 v11, 0xffff0000, v15
	v_lshlrev_b32_e32 v14, 16, v16
	v_and_b32_e32 v15, 0xffff0000, v16
	v_lshlrev_b32_e32 v16, 16, v17
	v_and_b32_e32 v17, 0xffff0000, v17
	s_waitcnt vmcnt(0)
	v_lshlrev_b32_e32 v22, 16, v18
	v_and_b32_e32 v18, 0xffff0000, v18
	v_lshlrev_b32_e32 v23, 16, v19
	v_and_b32_e32 v19, 0xffff0000, v19
	v_lshlrev_b32_e32 v24, 16, v20
	v_and_b32_e32 v20, 0xffff0000, v20
	v_lshlrev_b32_e32 v25, 16, v21
	v_and_b32_e32 v21, 0xffff0000, v21
	v_mul_f32_e32 v6, v13, v6
	v_mul_f32_e32 v7, v13, v7
	v_mul_f32_e32 v11, v13, v11
	v_mul_f32_e32 v14, v13, v14
	v_mul_f32_e32 v15, v13, v15
	v_mul_f32_e32 v16, v13, v16
	v_mul_f32_e32 v17, v13, v17
	v_mul_f32_e32 v22, v13, v22
	v_mul_f32_e32 v18, v13, v18
	v_mul_f32_e32 v19, v13, v19
	v_mul_f32_e32 v20, v13, v20
	v_mul_f32_e32 v10, v13, v10
	v_mul_f32_e32 v23, v13, v23
	v_mul_f32_e32 v24, v13, v24
	v_mul_f32_e32 v25, v13, v25
	v_mul_f32_e32 v13, v13, v21
	v_rndne_f32_e32 v6, v6
	v_rndne_f32_e32 v7, v7
	v_rndne_f32_e32 v11, v11
	v_rndne_f32_e32 v14, v14
	v_rndne_f32_e32 v15, v15
	v_rndne_f32_e32 v16, v16
	v_rndne_f32_e32 v17, v17
	v_rndne_f32_e32 v21, v22
	v_rndne_f32_e32 v18, v18
	v_rndne_f32_e32 v19, v19
	v_rndne_f32_e32 v20, v20
	v_rndne_f32_e32 v10, v10
	v_rndne_f32_e32 v22, v23
	v_rndne_f32_e32 v23, v24
	v_rndne_f32_e32 v24, v25
	v_rndne_f32_e32 v13, v13
	v_med3_f32 v6, v6, s21, v12
	v_med3_f32 v7, v7, s21, v12
	v_med3_f32 v11, v11, s21, v12
	v_med3_f32 v14, v14, s21, v12
	v_med3_f32 v15, v15, s21, v12
	v_med3_f32 v16, v16, s21, v12
	v_med3_f32 v17, v17, s21, v12
	v_med3_f32 v21, v21, s21, v12
	v_med3_f32 v18, v18, s21, v12
	v_med3_f32 v19, v19, s21, v12
	v_med3_f32 v20, v20, s21, v12
	v_med3_f32 v10, v10, s21, v12
	v_med3_f32 v22, v22, s21, v12
	v_med3_f32 v23, v23, s21, v12
	v_med3_f32 v24, v24, s21, v12
	v_med3_f32 v13, v13, s21, v12
	v_cvt_i32_f32_e32 v6, v6
	v_cvt_i32_f32_e32 v7, v7
	v_cvt_i32_f32_e32 v11, v11
	v_cvt_i32_f32_e32 v14, v14
	v_cvt_i32_f32_e32 v15, v15
	v_cvt_i32_f32_sdwa v16, v16 dst_sel:WORD_1 dst_unused:UNUSED_PAD src0_sel:DWORD
	v_cvt_i32_f32_e32 v17, v17
	v_cvt_i32_f32_e32 v21, v21
	v_cvt_i32_f32_e32 v18, v18
	v_cvt_i32_f32_e32 v19, v19
	v_cvt_i32_f32_e32 v20, v20
	v_cvt_i32_f32_sdwa v10, v10 dst_sel:WORD_1 dst_unused:UNUSED_PAD src0_sel:DWORD
	v_cvt_i32_f32_sdwa v22, v22 dst_sel:WORD_1 dst_unused:UNUSED_PAD src0_sel:DWORD
	v_cvt_i32_f32_e32 v23, v23
	v_cvt_i32_f32_sdwa v24, v24 dst_sel:WORD_1 dst_unused:UNUSED_PAD src0_sel:DWORD
	v_cvt_i32_f32_e32 v13, v13
	v_lshlrev_b32_e32 v7, 8, v7
	v_perm_b32 v6, v11, v6, s23
	v_lshlrev_b32_e32 v11, 8, v15
	v_and_b32_e32 v15, 0xff0000, v16
	v_perm_b32 v16, v17, v14, s23
	v_lshlrev_b32_e32 v14, 8, v18
	v_perm_b32 v18, v19, v21, s23
	v_lshlrev_b32_e32 v19, 8, v20
	v_and_b32_e32 v10, 0xff0000, v10
	v_and_b32_e32 v17, 0xff0000, v22
	v_and_b32_e32 v20, 0xff0000, v24
	v_perm_b32 v13, v13, v23, s23
	v_and_b32_e32 v7, 0xff00, v7
	v_and_b32_e32 v11, 0xff00, v11
	v_and_b32_e32 v21, 0xff00, v14
	v_and_b32_e32 v19, 0xff00, v19
	v_or3_b32 v14, v6, v7, v10
	v_or3_b32 v15, v16, v11, v15
	v_or3_b32 v16, v18, v21, v17
	v_or3_b32 v17, v13, v19, v20
	global_store_dwordx4 v[8:9], v[14:17], off offset:3072
	s_cbranch_scc0 .LBB0_1122

;     const int tid = threadIdx.x, wid = __builtin_amdgcn_readfirstlane(tid >> 6), lane = tid & 63, wr = wid >> 2, wc = wid & 3, fr = lane & 15, fq = lane >> 4;
;     const int K = g.K, nt = K / BK;
;     unsigned voffA[2], voffB[2];
; #pragma unroll
;     for (int i = 0; i < 2; ++i) { int R, C; stage_rc(tid * 16 + i * 8192, R, C); const int Rb = Epi::PERM ? ((R & ~31) + perm32(R & 31)) : R;
;         voffA[i] = (unsigned)(R * g.lda + C) * 2u; voffB[i] = (unsigned)(Rb * g.ldb + C) * 2u; }
;     const size_t kstep = (size_t)(BK * 2);
;     const size_t hstepA = (size_t)HALF * g.lda * 2, hstepB = (size_t)HALF * g.ldb * 2;
;     const unsigned ldsw = (unsigned)wid * 1024u;
;     const unsigned ldsbase = (unsigned)__builtin_amdgcn_readfirstlane((int)((unsigned)(size_t)lds + ldsw)); (void)ldsw;
;     const int aoff = lds_byte(wr * 64 + fr, fq * 8), boff = lds_byte(wc * 32 + fr, fq * 8);
;     ...
;     Unit cur, nxt; int ui = 0;
;     if (!S.next(0, cur)) return;
;     f32x4 acc[2][2][4][2];
; #pragma unroll
;     for (int a = 0; a < 2; ++a)
; #pragma unroll
;         for (int b = 0; b < 2; ++b)
; #pragma unroll
;             for (int m = 0; m < 4; ++m)
; #pragma unroll
;                 for (int n = 0; n < 2; ++n) acc[a][b][m][n] = (f32x4){0.f, 0.f, 0.f, 0.f};
;     bf16x8 At[4][2], B0[2][2], B1[2][2];
;     if constexpr (VAR >= 2) {
; #pragma unroll
;         for (int m = 0; m < 4; ++m)
; #pragma unroll
;             for (int k = 0; k < 2; ++k) { const unsigned h_ = (unsigned)(tid * 2654435761u + (m * 2 + k) * 40503u); const u32x4 q_ = (u32x4){h_ & 0x3fff3fffu, (h_ * 3u) & 0x3fff3fffu, (h_ * 5u) & 0x3fff3fffu, (h_ * 7u) & 0x3fff3fffu}; At[m][k] = __builtin_bit_cast(bf16x8, q_);
;                 if (m < 2) { B0[m][k] = __builtin_bit_cast(bf16x8, q_ ^ 0x01010101u); B1[m][k] = __builtin_bit_cast(bf16x8, q_ ^ 0x02040204u); } }
;     }
;     const char* cA = unitA(g, cur); const char* cB = unitB(g, cur);
;     PG8_STAGE(PG8_SB(0, 0), cB, voffB); PG8_STAGE(PG8_SB(0, 1), cB + hstepB, voffB); PG8_STAGE(PG8_SA(0, 0), cA, voffA); PG8_STAGE(PG8_SA(0, 1), cA + hstepA, voffA);
;     if (wr == 1) PG8_BAR;
;     PG8_WAIT_V(2); PG8_BAR;
;     PG8_STAGE(PG8_SB(1, 0), cB + kstep, voffB); PG8_STAGE(PG8_SA(1, 0), cA + kstep, voffA); PG8_STAGE(PG8_SB(1, 1), cB + hstepB + kstep, voffB);
;     PG8_WAIT_V(6); PG8_BAR;
.LBB0_1182:
	s_andn2_b64 vcc, exec, s[0:1]
	v_and_b32_e32 v1, 15, v0
	s_cbranch_vccnz .LBB0_1221
	s_waitcnt vmcnt(47)
	v_lshlrev_b32_e32 v2, 4, v0
	v_and_b32_e32 v3, 32, v0
	v_bitop3_b32 v2, v2, v3, 48 bitop3:0x6c
	v_and_or_b32 v3, v0, 64, v2
	v_lshrrev_b32_e32 v2, 1, v0
	v_lshrrev_b32_e32 v5, 5, v0
	v_and_b32_e32 v2, 24, v2
	v_and_b32_e32 v5, 4, v5
	s_waitcnt vmcnt(46)
	v_bfe_u32 v6, v0, 2, 2
	v_bfe_u32 v4, v0, 2, 4
	v_or3_b32 v5, v5, v6, v2
	v_lshrrev_b32_e32 v6, 3, v0
	v_and_or_b32 v7, v6, 48, v4
	v_and_or_b32 v6, v6, 32, v5
	v_mul_u32_u24_e32 v209, 0x1080, v6
	v_add_u32_e32 v209, v209, v3
	v_bfe_u32 v6, v0, 3, 25
	v_writelane_b32 v244, s82, 53
	v_or_b32_e32 v6, 64, v6
	s_movk_i32 s0, 0x70
	v_writelane_b32 v244, s83, 54
	v_and_or_b32 v4, v6, s0, v4
	s_movk_i32 s0, 0x60
	v_and_or_b32 v5, v6, s0, v5
	s_lshl_b32 s0, s26, 10
	v_readlane_b32 s36, v244, 2
	s_lshr_b32 s25, s24, 8
	s_add_i32 s15, s0, 0
	v_readlane_b32 s50, v244, 16
	v_readlane_b32 s51, v244, 17
	v_readlane_b32 s17, v244, 14
	v_readlane_b32 s19, v244, 15
	s_ashr_i32 s11, s10, 31
	s_ashr_i32 s77, s76, 31
	s_mul_i32 s0, s10, 0x108000
	s_mov_b32 s1, 0
	v_readlane_b32 s2, v244, 49
	v_readlane_b32 s3, v244, 50
	s_add_u32 s78, s2, s0
	s_addc_u32 s79, s3, s1
	s_add_i32 s21, s15, 0x10000
	s_mov_b32 m0, s21
	s_nop 0
	global_load_lds_dwordx4 v209, s[78:79]
	s_add_i32 s23, s15, 0x12000
	v_mul_u32_u24_e32 v211, 0x1080, v5
	v_add_u32_e32 v211, v211, v3
	s_mov_b32 m0, s23
	s_nop 0
	global_load_lds_dwordx4 v211, s[78:79]
	s_add_u32 s0, s78, 0x84000
	s_addc_u32 s1, s79, 0
	s_add_i32 s28, s15, 0x14000
	s_mov_b32 m0, s28
	s_nop 0
	global_load_lds_dwordx4 v209, s[0:1]
	s_add_i32 s29, s15, 0x16000
	s_mov_b32 m0, s29
	s_nop 0
	global_load_lds_dwordx4 v211, s[0:1]
	s_mul_i32 s0, s76, 0x108000
	s_mov_b32 s1, 0
	s_add_u32 s80, s17, s0
	v_mul_u32_u24_e32 v208, 0x1080, v7
	v_add_u32_e32 v208, v208, v3
	s_addc_u32 s81, s19, s1
	s_mov_b32 m0, s15
	s_nop 0
	global_load_lds_dwordx4 v208, s[80:81]
	s_add_i32 s30, s15, 0x2000
	v_mul_u32_u24_e32 v210, 0x1080, v4
	v_add_u32_e32 v210, v210, v3
	s_mov_b32 m0, s30
	s_nop 0
	global_load_lds_dwordx4 v210, s[80:81]
	s_add_u32 s0, s80, 0x84000
	s_addc_u32 s1, s81, 0
	s_add_i32 s31, s15, 0x4000
	s_mov_b32 m0, s31
	s_nop 0
	global_load_lds_dwordx4 v208, s[0:1]
	s_add_i32 s33, s15, 0x6000
	s_mov_b32 m0, s33
	s_nop 0
	global_load_lds_dwordx4 v210, s[0:1]
	s_cmp_eq_u32 s25, 1
	s_mov_b32 s14, 0
	s_cselect_b64 s[62:63], -1, 0
	s_cmp_lg_u32 s25, 1
	v_readlane_b32 s37, v244, 3
	v_readlane_b32 s38, v244, 4
	v_readlane_b32 s39, v244, 5
	v_readlane_b32 s40, v244, 6
	v_readlane_b32 s41, v244, 7
	v_readlane_b32 s42, v244, 8
	v_readlane_b32 s43, v244, 9
	v_readlane_b32 s44, v244, 10
	v_readlane_b32 s45, v244, 11
	v_readlane_b32 s46, v244, 12
	v_readlane_b32 s47, v244, 13
	v_readlane_b32 s48, v244, 14
	v_readlane_b32 s49, v244, 15
	s_cbranch_scc1 .LBB0_1185
	s_barrier
.LBB0_1185:
	v_lshlrev_b32_e32 v5, 2, v0
	s_add_i32 s68, 0, 0x21000
	v_lshlrev_b32_e32 v3, 1, v2
	v_lshlrev_b32_e32 v4, 6, v0
	s_movk_i32 s11, 0x3c0
	v_and_b32_e32 v6, 32, v5
	v_add_u32_e32 v214, s68, v5
	v_lshlrev_b32_e32 v5, 2, v1
	v_lshlrev_b32_e32 v8, 6, v1
	v_and_or_b32 v4, v4, s11, v3
	v_and_or_b32 v3, v8, s11, v3
	s_lshl_b32 s11, s25, 13
	v_and_b32_e32 v8, 32, v5
	v_bitop3_b32 v3, v3, s11, v8 bitop3:0xde
	s_lshl_b32 s11, s26, 5
	s_and_b32 s11, s11, 0x60
	s_add_i32 s66, 0, 0x21600
	s_ashr_i32 s35, s22, 31
	s_ashr_i32 s77, s16, 31
	s_add_i32 s27, 0, 0x21200
	s_lshl_b32 s26, s11, 7
	v_and_b32_e32 v7, 0x7f, v0
	v_bitop3_b32 v4, s26, v4, v6 bitop3:0xf6
	s_add_u32 s26, s78, 0x80
	v_lshl_add_u32 v212, v7, 2, s66
	v_add_u32_e32 v7, s27, v5
	s_waitcnt vmcnt(2)
	s_barrier
	s_addc_u32 s27, s79, 0
	s_add_i32 s84, s15, 0x18000
	s_mov_b32 m0, s84
	s_nop 0
	global_load_lds_dwordx4 v209, s[26:27]
	s_add_i32 s85, s15, 0x1a000
	s_mov_b32 m0, s85
	s_nop 0
	global_load_lds_dwordx4 v211, s[26:27]
	s_add_u32 s26, s80, 0x80
	s_addc_u32 s27, s81, 0
	s_add_i32 s86, s15, 0x8000
	s_mov_b32 m0, s86
	s_nop 0
	global_load_lds_dwordx4 v208, s[26:27]
	s_add_i32 s87, s15, 0xa000
	s_mov_b32 m0, s87
	s_nop 0
	global_load_lds_dwordx4 v210, s[26:27]
	s_add_u32 s26, s78, 0x84080
	s_movk_i32 s0, 0x100
	s_addc_u32 s27, s79, 0
	s_add_i32 s88, s15, 0x1c000
	s_add_i32 s89, s15, 0x1e000
	s_add_i32 s90, s15, 0xc000
	v_cmp_gt_u32_e64 s[2:3], s0, v0
	s_movk_i32 s0, 0x80
	s_cmpk_lt_u32 s24, 0x100
	v_or_b32_e32 v216, s11, v2
	v_cmp_gt_u32_e64 s[4:5], s0, v0
	v_cmp_gt_u32_e64 s[0:1], 2, v1
	s_cselect_b64 s[64:65], -1, 0
	v_lshlrev_b32_e32 v2, 2, v216
	v_add_u32_e32 v217, s66, v2
	s_and_b64 s[66:67], s[64:65], s[0:1]
	s_add_i32 s0, 0, 0x20000
	s_lshl_b32 s1, s25, 10
	s_add_i32 s11, 0, 0x21800
	s_add_i32 s1, s0, s1
	v_add_u32_e32 v218, s11, v2
	s_add_i32 s11, 0, 0x21a00
	v_add_u32_e32 v222, s1, v2
	s_max_u32 s1, s25, 1
	s_mov_b32 m0, s88
	s_nop 0
	global_load_lds_dwordx4 v209, s[26:27]
	v_add_u32_e32 v219, s11, v2
	s_add_i32 s11, 0, 0x21c00
	s_lshl_b32 s1, s1, 10
	s_mov_b32 m0, s89
	s_nop 0
	global_load_lds_dwordx4 v211, s[26:27]
	v_add_u32_e32 v220, s11, v2
	s_add_i32 s11, 0, 0x21e00
	s_add_i32 s0, s0, s1
	s_waitcnt vmcnt(6)
	v_add_u32_e32 v221, s11, v2
	s_and_b32 s11, s24, 0xffffff00
	s_add_i32 s1, s0, 0xfffffc00
	s_addk_i32 s0, 0xfe00
	v_cmp_eq_u32_e32 vcc, 0, v1
	v_cmp_eq_u32_e64 s[8:9], 1, v1
	v_cndmask_b32_e64 v6, 1.0, 0, s[64:65]
	v_lshl_add_u32 v8, v1, 9, v222
	v_add_u32_e32 v228, s1, v2
	v_add_u32_e32 v229, s0, v2
	s_add_i32 s68, s68, s11
	v_add_u32_e32 v2, 0, v4
	v_cmp_lt_u32_e64 s[6:7], 13, v1
	v_cndmask_b32_e64 v213, 0, 1.0, vcc
	v_cndmask_b32_e64 v171, 0, 1.0, s[8:9]
	v_lshl_or_b32 v215, s25, 6, v1
	v_add_u32_e32 v223, 0xffffe400, v8
	v_add_u32_e32 v224, 0xffffe410, v8
	v_add_u32_e32 v225, 0xffffec00, v8
	v_add_u32_e32 v226, 0xffffec10, v8
	v_cndmask_b32_e32 v227, 0, v6, vcc
	v_cndmask_b32_e64 v173, 0, v6, s[8:9]
	s_add_i32 s91, s15, 0xe000
	v_add_u32_e32 v230, s68, v5
	v_mov_b64_e32 v[174:175], 0x1580
	v_mov_b64_e32 v[176:177], 0x157f
	v_add_u32_e32 v231, 0x10000, v2
	v_add_u32_e32 v232, 0x14000, v2
	v_add_u32_e32 v233, 0, v3
	v_add_u32_e32 v234, 0x18000, v2
	v_add_u32_e32 v235, 0x1c000, v2
	s_add_i32 s92, 0, 0x21400
	v_mov_b32_e32 v236, 0x358637bd
	v_mov_b32_e32 v237, 0x260
	s_add_i32 s93, 0, 0x22000
	v_add_u32_e32 v238, s11, v7
	s_mov_b32 s94, 0xac00
	s_movk_i32 s95, 0x5600
	s_mov_b64 s[72:73], s[80:81]
	s_barrier
	s_branch .LBB0_1188

; __device__ __forceinline__ const char* unitA(const Gemm& g, const Unit& u) { return (const char*)(g.A + (size_t)(u.z / g.zdiv) * g.sAhi + (size_t)(u.z % g.zdiv) * g.sAlo + (size_t)u.pm * BM * g.lda); }
; __device__ __forceinline__ const char* unitB(const Gemm& g, const Unit& u) { return (const char*)(g.Bt + (size_t)(u.z / g.zdiv) * g.sBhi + (size_t)(u.z % g.zdiv) * g.sBlo + (size_t)(u.pm / g.bdiv) * g.sBpm + (size_t)u.pn * BM * g.ldb); }
; #define PG8_STAGE(bufoff, gbase, voff) do { if constexpr (VAR != 1 && VAR != 3) { _Pragma("unroll") for (int _i = 0; _i < 2; ++_i) \
;         asm volatile("s_mov_b32 m0, %2\n\ts_nop 0\n\tglobal_load_lds_dwordx4 %0, %1" :: "v"((voff)[_i]), "s"((const char*)(gbase)), "s"(ldsbase + (unsigned)((bufoff) + _i * 8192)) : "memory", "m0"); } } while (0)
; #define PG8_LDA(dst, b, h) do { if constexpr (VAR < 2) _Pragma("unroll") for (int m = 0; m < 4; ++m) _Pragma("unroll") for (int k = 0; k < 2; ++k) dst[m][k] = *(const LAS bf16x8*)(lds + PG8_SA(b, h) + aoff + m * 2048 + k * 1024); } while (0)
; #define PG8_WAIT_V(n) asm volatile("s_waitcnt vmcnt(" #n ")" ::: "memory")
;     __device__ bool next(int i, Unit& u) const {
;         const long L = (long)i * G + c; if (L >= nwg) return false;
;         int wgid = (int)L; { const int q = nwg / NXCD, r = nwg % NXCD, xcd = wgid % NXCD, off = wgid / NXCD; wgid = (xcd < r ? xcd * (q + 1) : r * (q + 1) + (xcd - r) * q) + off; }
;         const int nig = wgm * nN, gid = wgid / nig, fm = gid * wgm, gsz = (nM - fm) < wgm ? (nM - fm) : wgm;
;         u.pm = fm + ((wgid % nig) % gsz); u.pn = (wgid % nig) / gsz; u.z = 0; return true;
;     }
;     ...
;         const bool has_next = S.next(ui + 1, nxt);
;         const char* nA = has_next ? unitA(g, nxt) : cA; const char* nB = has_next ? unitB(g, nxt) : cB;
;         for (int t = 0; t < nt; t += 2) {
;             const bool last = (t == nt - 2);
;             const char* a1 = cA + (size_t)(t + 1) * kstep;
;             const char* a2 = last ? nA : cA + (size_t)(t + 2) * kstep; const char* b2 = last ? nB : cB + (size_t)(t + 2) * kstep;
;             const char* a3 = a2 + kstep; const char* b3 = b2 + kstep;
;             PG8_LDB(B0, 0, 0); PG8_LDB(B1, 0, 1); PG8_SCHED; PG8_LDA(At, 0, 0); PG8_STAGE(PG8_SA(1, 1), a1 + hstepA, voffA);
;             PG8_WAIT_V(8); PG8_WAIT_L(0); PG8_BAR; PG8_MMA(0, 0, At, B0); PG8_MMA(0, 1, At, B1); PG8_BAR; PG8_SCHED;
.LBB0_1188:
	s_add_i32 s14, s14, 1
	s_mul_i32 s0, s14, s35
	s_mul_hi_u32 s1, s14, s22
	s_add_i32 s1, s1, s0
	s_mul_i32 s0, s14, s22
	s_add_u32 s0, s0, s16
	s_addc_u32 s1, s1, s77
	v_cmp_gt_i64_e32 vcc, s[0:1], v[176:177]
	v_cmp_lt_i64_e64 s[8:9], s[0:1], v[174:175]
	s_cbranch_vccnz .LBB0_1190
	s_ashr_i32 s1, s0, 31
	s_lshr_b32 s1, s1, 29
	s_add_i32 s1, s0, s1
	s_ashr_i32 s11, s1, 3
	s_and_b32 s1, s1, -8
	s_sub_i32 s0, s0, s1
	s_cmp_lt_i32 s0, 0
	s_movk_i32 s1, 0x2b1
	s_cselect_b32 s1, s1, 0x2b0
	s_mul_i32 s0, s0, s1
	s_add_i32 s0, s0, s11
	s_mul_hi_i32 s1, s0, 0x2fa0be83
	s_lshr_b32 s11, s1, 31
	s_ashr_i32 s1, s1, 7
	s_add_i32 s1, s1, s11
	s_lshl_b32 s11, s1, 3
	s_sub_i32 s24, 64, s11
	s_min_i32 s24, s24, 8
	s_abs_i32 s25, s24
	v_cvt_f32_u32_e32 v2, s25
	s_sub_i32 s27, 0, s25
	s_mulk_i32 s1, 0x2b0
	s_sub_i32 s0, s0, s1
	v_rcp_iflag_f32_e32 v2, v2
	s_abs_i32 s1, s0
	s_xor_b32 s26, s0, s24
	s_ashr_i32 s26, s26, 31
	v_mul_f32_e32 v2, 0x4f7ffffe, v2
	v_cvt_u32_f32_e32 v2, v2
	s_nop 0
	v_readfirstlane_b32 s68, v2
	s_mul_i32 s27, s27, s68
	s_mul_hi_u32 s27, s68, s27
	s_add_i32 s68, s68, s27
	s_mul_hi_u32 s27, s1, s68
	s_mul_i32 s68, s27, s25
	s_sub_i32 s1, s1, s68
	s_add_i32 s69, s27, 1
	s_sub_i32 s68, s1, s25
	s_cmp_ge_u32 s1, s25
	s_cselect_b32 s27, s69, s27
	s_cselect_b32 s1, s68, s1
	s_add_i32 s68, s27, 1
	s_cmp_ge_u32 s1, s25
	s_cselect_b32 s1, s68, s27
	s_xor_b32 s1, s1, s26
	s_sub_i32 s68, s1, s26
	s_mul_i32 s1, s68, s24
	s_sub_i32 s0, s0, s1
	s_add_i32 s70, s11, s0
	s_ashr_i32 s71, s70, 31
	s_mul_i32 s0, s70, 0x108000
	s_mov_b32 s1, 0
	s_add_u32 s72, s17, s0
	s_addc_u32 s73, s19, s1
.LBB0_1190:
	s_ashr_i32 s69, s68, 31
	s_mul_i32 s0, s68, 0x108000
	s_mov_b32 s1, 0
	v_readlane_b32 s24, v244, 49
	v_readlane_b32 s25, v244, 50
	s_add_u32 s74, s24, s0
	s_addc_u32 s75, s25, s1
	s_and_b64 s[0:1], s[8:9], exec
	s_cselect_b32 s11, s75, s79
	s_cselect_b32 s24, s74, s78
	s_add_u32 s25, s80, 0x100
	s_addc_u32 s26, s81, 0
	s_add_u32 s27, s78, 0x100
	s_addc_u32 s69, s79, 0
	s_add_u32 s0, s80, 0x84080
	s_waitcnt vmcnt(38)
	s_addc_u32 s1, s81, 0
	s_mov_b32 s71, -2
	s_waitcnt vmcnt(36)
	s_waitcnt vmcnt(34)
	s_waitcnt vmcnt(33)
	s_waitcnt vmcnt(32)
	ds_read_b128 v[2:5], v231
	ds_read_b128 v[6:9], v231 offset:1024
	ds_read_b128 v[10:13], v231 offset:2048
	ds_read_b128 v[14:17], v231 offset:3072
	ds_read_b128 v[18:21], v232
	ds_read_b128 v[26:29], v232 offset:1024
	ds_read_b128 v[154:157], v232 offset:2048
	ds_read_b128 v[158:161], v232 offset:3072
	s_cmp_eq_u32 s71, 28
	s_cselect_b32 s82, s72, s25
	s_cselect_b32 s83, s73, s26
	s_cselect_b32 s80, s24, s27
	s_cselect_b32 s81, s11, s69
	s_add_u32 s78, s82, 0x80
	s_addc_u32 s79, s83, 0
	ds_read_b128 v[162:165], v233
	ds_read_b128 v[166:169], v233 offset:1024
	ds_read_b128 v[178:181], v233 offset:2048
	ds_read_b128 v[182:185], v233 offset:3072
	ds_read_b128 v[186:189], v233 offset:4096
	ds_read_b128 v[190:193], v233 offset:5120
	ds_read_b128 v[194:197], v233 offset:6144
	ds_read_b128 v[198:201], v233 offset:7168
	s_mov_b32 m0, s90
	s_nop 0
	global_load_lds_dwordx4 v208, s[0:1]
	s_mov_b32 m0, s91
	s_nop 0
	global_load_lds_dwordx4 v210, s[0:1]
	s_waitcnt vmcnt(8) lgkmcnt(0)
	s_barrier
	v_mfma_i32_16x16x64_i8 v[150:153], v[2:5], v[162:165], 0
	v_mfma_i32_16x16x64_i8 v[142:145], v[10:13], v[162:165], 0
	v_mfma_i32_16x16x64_i8 v[126:129], v[2:5], v[178:181], 0
	v_mfma_i32_16x16x64_i8 v[122:125], v[10:13], v[178:181], 0
	v_mfma_i32_16x16x64_i8 v[114:117], v[2:5], v[186:189], 0
	v_mfma_i32_16x16x64_i8 v[106:109], v[10:13], v[186:189], 0
	v_mfma_i32_16x16x64_i8 v[146:149], v[2:5], v[194:197], 0
	v_mfma_i32_16x16x64_i8 v[138:141], v[10:13], v[194:197], 0
	v_mfma_i32_16x16x64_i8 v[150:153], v[6:9], v[166:169], v[150:153]
	v_mfma_i32_16x16x64_i8 v[142:145], v[14:17], v[166:169], v[142:145]
	v_mfma_i32_16x16x64_i8 v[126:129], v[6:9], v[182:185], v[126:129]
	v_mfma_i32_16x16x64_i8 v[122:125], v[14:17], v[182:185], v[122:125]
	v_mfma_i32_16x16x64_i8 v[114:117], v[6:9], v[190:193], v[114:117]
	v_mfma_i32_16x16x64_i8 v[106:109], v[14:17], v[190:193], v[106:109]
	v_mfma_i32_16x16x64_i8 v[146:149], v[6:9], v[198:201], v[146:149]
	v_mfma_i32_16x16x64_i8 v[138:141], v[14:17], v[198:201], v[138:141]
	v_mfma_i32_16x16x64_i8 v[134:137], v[18:21], v[162:165], 0
	v_mfma_i32_16x16x64_i8 v[130:133], v[154:157], v[162:165], 0
	v_mfma_i32_16x16x64_i8 v[118:121], v[18:21], v[178:181], 0
	v_mfma_i32_16x16x64_i8 v[110:113], v[154:157], v[178:181], 0
	v_mfma_i32_16x16x64_i8 v[102:105], v[18:21], v[186:189], 0
	v_mfma_i32_16x16x64_i8 v[98:101], v[154:157], v[186:189], 0
	v_mfma_i32_16x16x64_i8 v[94:97], v[18:21], v[194:197], 0
	v_mfma_i32_16x16x64_i8 v[90:93], v[154:157], v[194:197], 0
	v_mfma_i32_16x16x64_i8 v[134:137], v[26:29], v[166:169], v[134:137]
	v_mfma_i32_16x16x64_i8 v[130:133], v[158:161], v[166:169], v[130:133]
	v_mfma_i32_16x16x64_i8 v[118:121], v[26:29], v[182:185], v[118:121]
	v_mfma_i32_16x16x64_i8 v[110:113], v[158:161], v[182:185], v[110:113]
	v_mfma_i32_16x16x64_i8 v[102:105], v[26:29], v[190:193], v[102:105]
	v_mfma_i32_16x16x64_i8 v[98:101], v[158:161], v[190:193], v[98:101]
	v_mfma_i32_16x16x64_i8 v[94:97], v[26:29], v[198:201], v[94:97]
	v_mfma_i32_16x16x64_i8 v[90:93], v[158:161], v[198:201], v[90:93]
	s_barrier
; #define PG8_STAGE(bufoff, gbase, voff) do { if constexpr (VAR != 1 && VAR != 3) { _Pragma("unroll") for (int _i = 0; _i < 2; ++_i) \
;         asm volatile("s_mov_b32 m0, %2\n\ts_nop 0\n\tglobal_load_lds_dwordx4 %0, %1" :: "v"((voff)[_i]), "s"((const char*)(gbase)), "s"(ldsbase + (unsigned)((bufoff) + _i * 8192)) : "memory", "m0"); } } while (0)
; #define PG8_LDA(dst, b, h) do { if constexpr (VAR < 2) _Pragma("unroll") for (int m = 0; m < 4; ++m) _Pragma("unroll") for (int k = 0; k < 2; ++k) dst[m][k] = *(const LAS bf16x8*)(lds + PG8_SA(b, h) + aoff + m * 2048 + k * 1024); } while (0)
; #define PG8_LDB(dst, b, h) do { if constexpr (VAR < 2) _Pragma("unroll") for (int n = 0; n < 2; ++n) _Pragma("unroll") for (int k = 0; k < 2; ++k) dst[n][k] = *(const LAS bf16x8*)(lds + PG8_SB(b, h) + boff + n * 2048 + k * 1024); } while (0)
; #define PG8_WAIT_V(n) asm volatile("s_waitcnt vmcnt(" #n ")" ::: "memory")
; #define PG8_WAIT_L(n) asm volatile("s_waitcnt lgkmcnt(" #n ")" ::: "memory")
; #define PG8_BAR do { if constexpr (VAR != 3) __builtin_amdgcn_s_barrier(); } while (0)
; #define PG8_SCHED __builtin_amdgcn_sched_barrier(0)
;     ...
;             PG8_LDA(At, 0, 1); PG8_STAGE(PG8_SB(0, 0), b2, voffB); PG8_STAGE(PG8_SB(0, 1), b2 + hstepB, voffB); PG8_STAGE(PG8_SA(0, 0), a2, voffA);
;             PG8_WAIT_V(8); PG8_WAIT_L(0); PG8_BAR; PG8_MMA(1, 0, At, B0); PG8_MMA(1, 1, At, B1); PG8_BAR; PG8_SCHED;
;             PG8_LDB(B0, 1, 0); PG8_LDB(B1, 1, 1); PG8_SCHED; PG8_LDA(At, 1, 0); PG8_STAGE(PG8_SA(0, 1), a2 + hstepA, voffA);
;             PG8_WAIT_V(8); PG8_WAIT_L(0); PG8_BAR; PG8_MMA(0, 0, At, B0); PG8_MMA(0, 1, At, B1); PG8_BAR; PG8_SCHED;
	ds_read_b128 v[162:165], v233 offset:16384
	ds_read_b128 v[166:169], v233 offset:17408
	ds_read_b128 v[178:181], v233 offset:18432
	ds_read_b128 v[182:185], v233 offset:19456
	ds_read_b128 v[186:189], v233 offset:20480
	ds_read_b128 v[190:193], v233 offset:21504
	ds_read_b128 v[194:197], v233 offset:22528
	ds_read_b128 v[198:201], v233 offset:23552
	s_mov_b32 m0, s21
	s_nop 0
	global_load_lds_dwordx4 v209, s[80:81]
	s_add_u32 s96, s80, 0x84000
	s_mov_b32 m0, s23
	s_nop 0
	global_load_lds_dwordx4 v211, s[80:81]
	s_addc_u32 s97, s81, 0
	s_mov_b32 m0, s28
	s_nop 0
	global_load_lds_dwordx4 v209, s[96:97]
	s_mov_b32 m0, s29
	s_nop 0
	global_load_lds_dwordx4 v211, s[96:97]
	s_mov_b32 m0, s15
	s_nop 0
	global_load_lds_dwordx4 v208, s[82:83]
	s_mov_b32 m0, s30
	s_nop 0
	global_load_lds_dwordx4 v210, s[82:83]
	s_waitcnt vmcnt(8) lgkmcnt(0)
	s_barrier
	v_mfma_i32_16x16x64_i8 v[86:89], v[2:5], v[162:165], 0
	v_mfma_i32_16x16x64_i8 v[82:85], v[10:13], v[162:165], 0
	v_mfma_i32_16x16x64_i8 v[74:77], v[2:5], v[178:181], 0
	v_mfma_i32_16x16x64_i8 v[66:69], v[10:13], v[178:181], 0
	v_mfma_i32_16x16x64_i8 v[58:61], v[2:5], v[186:189], 0
	v_mfma_i32_16x16x64_i8 v[50:53], v[10:13], v[186:189], 0
	v_mfma_i32_16x16x64_i8 v[2:5], v[2:5], v[194:197], 0
	v_mfma_i32_16x16x64_i8 v[86:89], v[6:9], v[166:169], v[86:89]
	v_mfma_i32_16x16x64_i8 v[82:85], v[14:17], v[166:169], v[82:85]
	v_mfma_i32_16x16x64_i8 v[74:77], v[6:9], v[182:185], v[74:77]
	v_mfma_i32_16x16x64_i8 v[66:69], v[14:17], v[182:185], v[66:69]
	v_mfma_i32_16x16x64_i8 v[58:61], v[6:9], v[190:193], v[58:61]
	v_mfma_i32_16x16x64_i8 v[50:53], v[14:17], v[190:193], v[50:53]
	v_mfma_i32_16x16x64_i8 v[2:5], v[6:9], v[198:201], v[2:5]
	v_mfma_i32_16x16x64_i8 v[6:9], v[10:13], v[194:197], 0
	v_mfma_i32_16x16x64_i8 v[6:9], v[14:17], v[198:201], v[6:9]
	v_mfma_i32_16x16x64_i8 v[22:25], v[18:21], v[178:181], 0
	v_mfma_i32_16x16x64_i8 v[62:65], v[26:29], v[182:185], v[22:25]
	v_mfma_i32_16x16x64_i8 v[22:25], v[154:157], v[178:181], 0
	v_mfma_i32_16x16x64_i8 v[54:57], v[158:161], v[182:185], v[22:25]
	v_mfma_i32_16x16x64_i8 v[22:25], v[18:21], v[186:189], 0
	v_mfma_i32_16x16x64_i8 v[46:49], v[26:29], v[190:193], v[22:25]
	v_mfma_i32_16x16x64_i8 v[22:25], v[154:157], v[186:189], 0
	v_mfma_i32_16x16x64_i8 v[10:13], v[18:21], v[162:165], 0
	v_mfma_i32_16x16x64_i8 v[14:17], v[154:157], v[162:165], 0
	v_mfma_i32_16x16x64_i8 v[42:45], v[158:161], v[190:193], v[22:25]
	v_mfma_i32_16x16x64_i8 v[18:21], v[18:21], v[194:197], 0
	v_mfma_i32_16x16x64_i8 v[22:25], v[154:157], v[194:197], 0
	v_mfma_i32_16x16x64_i8 v[10:13], v[26:29], v[166:169], v[10:13]
	v_mfma_i32_16x16x64_i8 v[14:17], v[158:161], v[166:169], v[14:17]
	v_mfma_i32_16x16x64_i8 v[18:21], v[26:29], v[198:201], v[18:21]
	v_mfma_i32_16x16x64_i8 v[26:29], v[158:161], v[198:201], v[22:25]
	s_barrier
	s_nop 1
	ds_read_b128 v[22:25], v234
	ds_read_b128 v[30:33], v234 offset:1024
	ds_read_b128 v[34:37], v234 offset:2048
	ds_read_b128 v[38:41], v234 offset:3072
	ds_read_b128 v[154:157], v235
	ds_read_b128 v[158:161], v235 offset:1024
	ds_read_b128 v[162:165], v235 offset:2048
	ds_read_b128 v[166:169], v235 offset:3072
	ds_read_b128 v[70:73], v233 offset:32768
	ds_read_b128 v[78:81], v233 offset:33792
	ds_read_b128 v[178:181], v233 offset:34816
	ds_read_b128 v[182:185], v233 offset:35840
	ds_read_b128 v[186:189], v233 offset:36864
	ds_read_b128 v[190:193], v233 offset:37888
	ds_read_b128 v[194:197], v233 offset:38912
	ds_read_b128 v[198:201], v233 offset:39936
	s_add_u32 s82, s82, 0x84000
	s_addc_u32 s83, s83, 0
	s_mov_b32 m0, s31
	s_nop 0
	global_load_lds_dwordx4 v208, s[82:83]
	s_mov_b32 m0, s33
	s_nop 0
	global_load_lds_dwordx4 v210, s[82:83]
	s_waitcnt vmcnt(8) lgkmcnt(0)
	s_barrier
	v_mfma_i32_16x16x64_i8 v[150:153], v[22:25], v[70:73], v[150:153]
	v_mfma_i32_16x16x64_i8 v[142:145], v[34:37], v[70:73], v[142:145]
	v_mfma_i32_16x16x64_i8 v[126:129], v[22:25], v[178:181], v[126:129]
	v_mfma_i32_16x16x64_i8 v[122:125], v[34:37], v[178:181], v[122:125]
	v_mfma_i32_16x16x64_i8 v[114:117], v[22:25], v[186:189], v[114:117]
	v_mfma_i32_16x16x64_i8 v[106:109], v[34:37], v[186:189], v[106:109]
	v_mfma_i32_16x16x64_i8 v[146:149], v[22:25], v[194:197], v[146:149]
	v_mfma_i32_16x16x64_i8 v[138:141], v[34:37], v[194:197], v[138:141]
	v_mfma_i32_16x16x64_i8 v[150:153], v[30:33], v[78:81], v[150:153]
	v_mfma_i32_16x16x64_i8 v[142:145], v[38:41], v[78:81], v[142:145]
	v_mfma_i32_16x16x64_i8 v[126:129], v[30:33], v[182:185], v[126:129]
	v_mfma_i32_16x16x64_i8 v[122:125], v[38:41], v[182:185], v[122:125]
	v_mfma_i32_16x16x64_i8 v[114:117], v[30:33], v[190:193], v[114:117]
	v_mfma_i32_16x16x64_i8 v[106:109], v[38:41], v[190:193], v[106:109]
	v_mfma_i32_16x16x64_i8 v[146:149], v[30:33], v[198:201], v[146:149]
	v_mfma_i32_16x16x64_i8 v[138:141], v[38:41], v[198:201], v[138:141]
	v_mfma_i32_16x16x64_i8 v[134:137], v[154:157], v[70:73], v[134:137]
	v_mfma_i32_16x16x64_i8 v[70:73], v[162:165], v[70:73], v[130:133]
	v_mfma_i32_16x16x64_i8 v[130:133], v[166:169], v[78:81], v[70:73]
	v_mfma_i32_16x16x64_i8 v[70:73], v[154:157], v[178:181], v[118:121]
	v_mfma_i32_16x16x64_i8 v[118:121], v[158:161], v[182:185], v[70:73]
	v_mfma_i32_16x16x64_i8 v[70:73], v[162:165], v[178:181], v[110:113]
	v_mfma_i32_16x16x64_i8 v[110:113], v[166:169], v[182:185], v[70:73]
	v_mfma_i32_16x16x64_i8 v[70:73], v[154:157], v[186:189], v[102:105]
	v_mfma_i32_16x16x64_i8 v[102:105], v[158:161], v[190:193], v[70:73]
	v_mfma_i32_16x16x64_i8 v[70:73], v[162:165], v[186:189], v[98:101]
	v_mfma_i32_16x16x64_i8 v[98:101], v[166:169], v[190:193], v[70:73]
	v_mfma_i32_16x16x64_i8 v[70:73], v[154:157], v[194:197], v[94:97]
	v_mfma_i32_16x16x64_i8 v[94:97], v[158:161], v[198:201], v[70:73]
	v_mfma_i32_16x16x64_i8 v[70:73], v[162:165], v[194:197], v[90:93]
	v_mfma_i32_16x16x64_i8 v[134:137], v[158:161], v[78:81], v[134:137]
	v_mfma_i32_16x16x64_i8 v[90:93], v[166:169], v[198:201], v[70:73]
	s_barrier
; #define PG8_STAGE(bufoff, gbase, voff) do { if constexpr (VAR != 1 && VAR != 3) { _Pragma("unroll") for (int _i = 0; _i < 2; ++_i) \
;         asm volatile("s_mov_b32 m0, %2\n\ts_nop 0\n\tglobal_load_lds_dwordx4 %0, %1" :: "v"((voff)[_i]), "s"((const char*)(gbase)), "s"(ldsbase + (unsigned)((bufoff) + _i * 8192)) : "memory", "m0"); } } while (0)
; #define PG8_LDA(dst, b, h) do { if constexpr (VAR < 2) _Pragma("unroll") for (int m = 0; m < 4; ++m) _Pragma("unroll") for (int k = 0; k < 2; ++k) dst[m][k] = *(const LAS bf16x8*)(lds + PG8_SA(b, h) + aoff + m * 2048 + k * 1024); } while (0)
; #define PG8_LDB(dst, b, h) do { if constexpr (VAR < 2) _Pragma("unroll") for (int n = 0; n < 2; ++n) _Pragma("unroll") for (int k = 0; k < 2; ++k) dst[n][k] = *(const LAS bf16x8*)(lds + PG8_SB(b, h) + boff + n * 2048 + k * 1024); } while (0)
; #define PG8_WAIT_V(n) asm volatile("s_waitcnt vmcnt(" #n ")" ::: "memory")
; #define PG8_WAIT_L(n) asm volatile("s_waitcnt lgkmcnt(" #n ")" ::: "memory")
;     ...
;         for (int t = 0; t < nt; t += 2) {
;             const bool last = (t == nt - 2);
;             const char* a1 = cA + (size_t)(t + 1) * kstep;
;             const char* a2 = last ? nA : cA + (size_t)(t + 2) * kstep; const char* b2 = last ? nB : cB + (size_t)(t + 2) * kstep;
;             const char* a3 = a2 + kstep; const char* b3 = b2 + kstep;
;             PG8_LDB(B0, 0, 0); PG8_LDB(B1, 0, 1); PG8_SCHED; PG8_LDA(At, 0, 0); PG8_STAGE(PG8_SA(1, 1), a1 + hstepA, voffA);
;             PG8_WAIT_V(8); PG8_WAIT_L(0); PG8_BAR; PG8_MMA(0, 0, At, B0); PG8_MMA(0, 1, At, B1); PG8_BAR; PG8_SCHED;
;             PG8_LDA(At, 0, 1); PG8_STAGE(PG8_SB(0, 0), b2, voffB); PG8_STAGE(PG8_SB(0, 1), b2 + hstepB, voffB); PG8_STAGE(PG8_SA(0, 0), a2, voffA);
;             PG8_WAIT_V(8); PG8_WAIT_L(0); PG8_BAR; PG8_MMA(1, 0, At, B0); PG8_MMA(1, 1, At, B1); PG8_BAR; PG8_SCHED;
;             PG8_LDB(B0, 1, 0); PG8_LDB(B1, 1, 1); PG8_SCHED; PG8_LDA(At, 1, 0); PG8_STAGE(PG8_SA(0, 1), a2 + hstepA, voffA);
;             PG8_WAIT_V(8); PG8_WAIT_L(0); PG8_BAR; PG8_MMA(0, 0, At, B0); PG8_MMA(0, 1, At, B1); PG8_BAR; PG8_SCHED;
;             PG8_LDA(At, 1, 1); PG8_STAGE(PG8_SB(1, 0), b3, voffB); PG8_STAGE(PG8_SB(1, 1), b3 + hstepB, voffB); PG8_STAGE(PG8_SA(1, 0), a3, voffA);
;             PG8_WAIT_V(8); PG8_WAIT_L(0); PG8_BAR; PG8_MMA(1, 0, At, B0); PG8_MMA(1, 1, At, B1); PG8_BAR; PG8_SCHED;
	s_nop 3
	ds_read_b128 v[70:73], v233 offset:49152
	ds_read_b128 v[178:181], v233 offset:50176
	ds_read_b128 v[182:185], v233 offset:51200
	ds_read_b128 v[186:189], v233 offset:52224
	ds_read_b128 v[190:193], v233 offset:53248
	ds_read_b128 v[194:197], v233 offset:54272
	ds_read_b128 v[198:201], v233 offset:55296
	ds_read_b128 v[202:205], v233 offset:56320
	s_add_u32 s82, s80, 0x80
	s_addc_u32 s83, s81, 0
	s_mov_b32 m0, s84
	s_nop 0
	global_load_lds_dwordx4 v209, s[82:83]
	s_add_u32 s80, s80, 0x84080
	s_mov_b32 m0, s85
	s_nop 0
	global_load_lds_dwordx4 v211, s[82:83]
	s_addc_u32 s81, s81, 0
	s_mov_b32 m0, s88
	s_nop 0
	global_load_lds_dwordx4 v209, s[80:81]
	s_mov_b32 m0, s89
	s_nop 0
	global_load_lds_dwordx4 v211, s[80:81]
	s_mov_b32 m0, s86
	s_nop 0
	global_load_lds_dwordx4 v208, s[78:79]
	s_mov_b32 m0, s87
	s_nop 0
	global_load_lds_dwordx4 v210, s[78:79]
	s_waitcnt vmcnt(8) lgkmcnt(0)
	s_barrier
	v_mfma_i32_16x16x64_i8 v[78:81], v[22:25], v[70:73], v[86:89]
	v_mfma_i32_16x16x64_i8 v[74:77], v[22:25], v[182:185], v[74:77]
	v_mfma_i32_16x16x64_i8 v[58:61], v[22:25], v[190:193], v[58:61]
	v_mfma_i32_16x16x64_i8 v[2:5], v[22:25], v[198:201], v[2:5]
	v_mfma_i32_16x16x64_i8 v[86:89], v[30:33], v[178:181], v[78:81]
	v_mfma_i32_16x16x64_i8 v[78:81], v[34:37], v[70:73], v[82:85]
	v_mfma_i32_16x16x64_i8 v[74:77], v[30:33], v[186:189], v[74:77]
	v_mfma_i32_16x16x64_i8 v[66:69], v[34:37], v[182:185], v[66:69]
	v_mfma_i32_16x16x64_i8 v[58:61], v[30:33], v[194:197], v[58:61]
	v_mfma_i32_16x16x64_i8 v[50:53], v[34:37], v[190:193], v[50:53]
	v_mfma_i32_16x16x64_i8 v[30:33], v[30:33], v[202:205], v[2:5]
	v_mfma_i32_16x16x64_i8 v[2:5], v[34:37], v[198:201], v[6:9]
	v_mfma_i32_16x16x64_i8 v[82:85], v[38:41], v[178:181], v[78:81]
	v_mfma_i32_16x16x64_i8 v[66:69], v[38:41], v[186:189], v[66:69]
	v_mfma_i32_16x16x64_i8 v[50:53], v[38:41], v[194:197], v[50:53]
	v_mfma_i32_16x16x64_i8 v[22:25], v[38:41], v[202:205], v[2:5]
	v_mfma_i32_16x16x64_i8 v[2:5], v[154:157], v[70:73], v[10:13]
	v_mfma_i32_16x16x64_i8 v[78:81], v[158:161], v[178:181], v[2:5]
	v_mfma_i32_16x16x64_i8 v[2:5], v[162:165], v[70:73], v[14:17]
	v_mfma_i32_16x16x64_i8 v[70:73], v[166:169], v[178:181], v[2:5]
	v_mfma_i32_16x16x64_i8 v[2:5], v[154:157], v[182:185], v[62:65]
	v_mfma_i32_16x16x64_i8 v[62:65], v[158:161], v[186:189], v[2:5]
	v_mfma_i32_16x16x64_i8 v[2:5], v[162:165], v[182:185], v[54:57]
	v_mfma_i32_16x16x64_i8 v[54:57], v[166:169], v[186:189], v[2:5]
	v_mfma_i32_16x16x64_i8 v[2:5], v[154:157], v[190:193], v[46:49]
	v_mfma_i32_16x16x64_i8 v[46:49], v[158:161], v[194:197], v[2:5]
	v_mfma_i32_16x16x64_i8 v[2:5], v[162:165], v[190:193], v[42:45]
	v_mfma_i32_16x16x64_i8 v[42:45], v[166:169], v[194:197], v[2:5]
	v_mfma_i32_16x16x64_i8 v[2:5], v[154:157], v[198:201], v[18:21]
	v_mfma_i32_16x16x64_i8 v[38:41], v[158:161], v[202:205], v[2:5]
	v_mfma_i32_16x16x64_i8 v[2:5], v[162:165], v[198:201], v[26:29]
	v_mfma_i32_16x16x64_i8 v[34:37], v[166:169], v[202:205], v[2:5]
	s_barrier
	s_add_i32 s71, s71, 2
	s_add_u32 s25, s25, 0x100
	s_addc_u32 s26, s26, 0
	s_add_u32 s27, s27, 0x100
	s_addc_u32 s69, s69, 0
	s_add_u32 s0, s0, 0x100
	s_addc_u32 s1, s1, 0
	s_cmp_gt_u32 s71, 29
	s_cbranch_scc0 .LBB0_1191
	s_branch .Lmy_kexit_8
.LBB0_1191:
	ds_read_b128 v[2:5], v231
	ds_read_b128 v[6:9], v231 offset:1024
	ds_read_b128 v[10:13], v231 offset:2048
	ds_read_b128 v[14:17], v231 offset:3072
	ds_read_b128 v[18:21], v232
	ds_read_b128 v[26:29], v232 offset:1024
	ds_read_b128 v[154:157], v232 offset:2048
	ds_read_b128 v[158:161], v232 offset:3072
	s_cmp_eq_u32 s71, 28
	s_cselect_b32 s82, s72, s25
	s_cselect_b32 s83, s73, s26
	s_cselect_b32 s80, s24, s27
	s_cselect_b32 s81, s11, s69
	s_add_u32 s78, s82, 0x80
	s_addc_u32 s79, s83, 0
	ds_read_b128 v[162:165], v233
	ds_read_b128 v[166:169], v233 offset:1024
	ds_read_b128 v[178:181], v233 offset:2048
	ds_read_b128 v[182:185], v233 offset:3072
	ds_read_b128 v[186:189], v233 offset:4096
	ds_read_b128 v[190:193], v233 offset:5120
	ds_read_b128 v[194:197], v233 offset:6144
	ds_read_b128 v[198:201], v233 offset:7168
	s_mov_b32 m0, s90
	s_nop 0
	global_load_lds_dwordx4 v208, s[0:1]
	s_mov_b32 m0, s91
	s_nop 0
	global_load_lds_dwordx4 v210, s[0:1]
	s_waitcnt vmcnt(8) lgkmcnt(0)
	s_barrier
	v_mfma_i32_16x16x64_i8 v[150:153], v[2:5], v[162:165], v[150:153]
	v_mfma_i32_16x16x64_i8 v[142:145], v[10:13], v[162:165], v[142:145]
	v_mfma_i32_16x16x64_i8 v[126:129], v[2:5], v[178:181], v[126:129]
	v_mfma_i32_16x16x64_i8 v[122:125], v[10:13], v[178:181], v[122:125]
	v_mfma_i32_16x16x64_i8 v[114:117], v[2:5], v[186:189], v[114:117]
	v_mfma_i32_16x16x64_i8 v[106:109], v[10:13], v[186:189], v[106:109]
	v_mfma_i32_16x16x64_i8 v[146:149], v[2:5], v[194:197], v[146:149]
	v_mfma_i32_16x16x64_i8 v[138:141], v[10:13], v[194:197], v[138:141]
	v_mfma_i32_16x16x64_i8 v[150:153], v[6:9], v[166:169], v[150:153]
	v_mfma_i32_16x16x64_i8 v[142:145], v[14:17], v[166:169], v[142:145]
	v_mfma_i32_16x16x64_i8 v[126:129], v[6:9], v[182:185], v[126:129]
	v_mfma_i32_16x16x64_i8 v[122:125], v[14:17], v[182:185], v[122:125]
	v_mfma_i32_16x16x64_i8 v[114:117], v[6:9], v[190:193], v[114:117]
	v_mfma_i32_16x16x64_i8 v[106:109], v[14:17], v[190:193], v[106:109]
	v_mfma_i32_16x16x64_i8 v[146:149], v[6:9], v[198:201], v[146:149]
	v_mfma_i32_16x16x64_i8 v[138:141], v[14:17], v[198:201], v[138:141]
	v_mfma_i32_16x16x64_i8 v[134:137], v[18:21], v[162:165], v[134:137]
	v_mfma_i32_16x16x64_i8 v[130:133], v[154:157], v[162:165], v[130:133]
	v_mfma_i32_16x16x64_i8 v[118:121], v[18:21], v[178:181], v[118:121]
	v_mfma_i32_16x16x64_i8 v[110:113], v[154:157], v[178:181], v[110:113]
	v_mfma_i32_16x16x64_i8 v[102:105], v[18:21], v[186:189], v[102:105]
	v_mfma_i32_16x16x64_i8 v[98:101], v[154:157], v[186:189], v[98:101]
	v_mfma_i32_16x16x64_i8 v[94:97], v[18:21], v[194:197], v[94:97]
	v_mfma_i32_16x16x64_i8 v[90:93], v[154:157], v[194:197], v[90:93]
	v_mfma_i32_16x16x64_i8 v[134:137], v[26:29], v[166:169], v[134:137]
	v_mfma_i32_16x16x64_i8 v[130:133], v[158:161], v[166:169], v[130:133]
	v_mfma_i32_16x16x64_i8 v[118:121], v[26:29], v[182:185], v[118:121]
	v_mfma_i32_16x16x64_i8 v[110:113], v[158:161], v[182:185], v[110:113]
	v_mfma_i32_16x16x64_i8 v[102:105], v[26:29], v[190:193], v[102:105]
	v_mfma_i32_16x16x64_i8 v[98:101], v[158:161], v[190:193], v[98:101]
	v_mfma_i32_16x16x64_i8 v[94:97], v[26:29], v[198:201], v[94:97]
	v_mfma_i32_16x16x64_i8 v[90:93], v[158:161], v[198:201], v[90:93]
	s_barrier
; #define PG8_STAGE(bufoff, gbase, voff) do { if constexpr (VAR != 1 && VAR != 3) { _Pragma("unroll") for (int _i = 0; _i < 2; ++_i) \
;         asm volatile("s_mov_b32 m0, %2\n\ts_nop 0\n\tglobal_load_lds_dwordx4 %0, %1" :: "v"((voff)[_i]), "s"((const char*)(gbase)), "s"(ldsbase + (unsigned)((bufoff) + _i * 8192)) : "memory", "m0"); } } while (0)
; #define PG8_LDA(dst, b, h) do { if constexpr (VAR < 2) _Pragma("unroll") for (int m = 0; m < 4; ++m) _Pragma("unroll") for (int k = 0; k < 2; ++k) dst[m][k] = *(const LAS bf16x8*)(lds + PG8_SA(b, h) + aoff + m * 2048 + k * 1024); } while (0)
; #define PG8_LDB(dst, b, h) do { if constexpr (VAR < 2) _Pragma("unroll") for (int n = 0; n < 2; ++n) _Pragma("unroll") for (int k = 0; k < 2; ++k) dst[n][k] = *(const LAS bf16x8*)(lds + PG8_SB(b, h) + boff + n * 2048 + k * 1024); } while (0)
; #define PG8_WAIT_V(n) asm volatile("s_waitcnt vmcnt(" #n ")" ::: "memory")
; #define PG8_WAIT_L(n) asm volatile("s_waitcnt lgkmcnt(" #n ")" ::: "memory")
; #define PG8_BAR do { if constexpr (VAR != 3) __builtin_amdgcn_s_barrier(); } while (0)
; #define PG8_SCHED __builtin_amdgcn_sched_barrier(0)
;     ...
;             PG8_LDA(At, 0, 1); PG8_STAGE(PG8_SB(0, 0), b2, voffB); PG8_STAGE(PG8_SB(0, 1), b2 + hstepB, voffB); PG8_STAGE(PG8_SA(0, 0), a2, voffA);
;             PG8_WAIT_V(8); PG8_WAIT_L(0); PG8_BAR; PG8_MMA(1, 0, At, B0); PG8_MMA(1, 1, At, B1); PG8_BAR; PG8_SCHED;
;             PG8_LDB(B0, 1, 0); PG8_LDB(B1, 1, 1); PG8_SCHED; PG8_LDA(At, 1, 0); PG8_STAGE(PG8_SA(0, 1), a2 + hstepA, voffA);
;             PG8_WAIT_V(8); PG8_WAIT_L(0); PG8_BAR; PG8_MMA(0, 0, At, B0); PG8_MMA(0, 1, At, B1); PG8_BAR; PG8_SCHED;
	ds_read_b128 v[162:165], v233 offset:16384
	ds_read_b128 v[166:169], v233 offset:17408
	ds_read_b128 v[178:181], v233 offset:18432
	ds_read_b128 v[182:185], v233 offset:19456
	ds_read_b128 v[186:189], v233 offset:20480
	ds_read_b128 v[190:193], v233 offset:21504
	ds_read_b128 v[194:197], v233 offset:22528
	ds_read_b128 v[198:201], v233 offset:23552
	s_mov_b32 m0, s21
	s_nop 0
	global_load_lds_dwordx4 v209, s[80:81]
	s_add_u32 s96, s80, 0x84000
	s_mov_b32 m0, s23
	s_nop 0
	global_load_lds_dwordx4 v211, s[80:81]
	s_addc_u32 s97, s81, 0
	s_mov_b32 m0, s28
	s_nop 0
	global_load_lds_dwordx4 v209, s[96:97]
	s_mov_b32 m0, s29
	s_nop 0
	global_load_lds_dwordx4 v211, s[96:97]
	s_mov_b32 m0, s15
	s_nop 0
	global_load_lds_dwordx4 v208, s[82:83]
	s_mov_b32 m0, s30
	s_nop 0
	global_load_lds_dwordx4 v210, s[82:83]
	s_waitcnt vmcnt(8) lgkmcnt(0)
	s_barrier
	v_mfma_i32_16x16x64_i8 v[86:89], v[2:5], v[162:165], v[86:89]
	v_mfma_i32_16x16x64_i8 v[82:85], v[10:13], v[162:165], v[82:85]
	v_mfma_i32_16x16x64_i8 v[74:77], v[2:5], v[178:181], v[74:77]
	v_mfma_i32_16x16x64_i8 v[66:69], v[10:13], v[178:181], v[66:69]
	v_mfma_i32_16x16x64_i8 v[58:61], v[2:5], v[186:189], v[58:61]
	v_mfma_i32_16x16x64_i8 v[50:53], v[10:13], v[186:189], v[50:53]
	v_mfma_i32_16x16x64_i8 v[2:5], v[2:5], v[194:197], v[30:33]
	v_mfma_i32_16x16x64_i8 v[86:89], v[6:9], v[166:169], v[86:89]
	v_mfma_i32_16x16x64_i8 v[82:85], v[14:17], v[166:169], v[82:85]
	v_mfma_i32_16x16x64_i8 v[74:77], v[6:9], v[182:185], v[74:77]
	v_mfma_i32_16x16x64_i8 v[66:69], v[14:17], v[182:185], v[66:69]
	v_mfma_i32_16x16x64_i8 v[58:61], v[6:9], v[190:193], v[58:61]
	v_mfma_i32_16x16x64_i8 v[50:53], v[14:17], v[190:193], v[50:53]
	v_mfma_i32_16x16x64_i8 v[2:5], v[6:9], v[198:201], v[2:5]
	v_mfma_i32_16x16x64_i8 v[6:9], v[10:13], v[194:197], v[22:25]
	v_mfma_i32_16x16x64_i8 v[6:9], v[14:17], v[198:201], v[6:9]
	v_mfma_i32_16x16x64_i8 v[22:25], v[18:21], v[178:181], v[62:65]
	v_mfma_i32_16x16x64_i8 v[62:65], v[26:29], v[182:185], v[22:25]
	v_mfma_i32_16x16x64_i8 v[22:25], v[154:157], v[178:181], v[54:57]
	v_mfma_i32_16x16x64_i8 v[54:57], v[158:161], v[182:185], v[22:25]
	v_mfma_i32_16x16x64_i8 v[22:25], v[18:21], v[186:189], v[46:49]
	v_mfma_i32_16x16x64_i8 v[46:49], v[26:29], v[190:193], v[22:25]
	v_mfma_i32_16x16x64_i8 v[22:25], v[154:157], v[186:189], v[42:45]
	v_mfma_i32_16x16x64_i8 v[10:13], v[18:21], v[162:165], v[78:81]
	v_mfma_i32_16x16x64_i8 v[14:17], v[154:157], v[162:165], v[70:73]
	v_mfma_i32_16x16x64_i8 v[42:45], v[158:161], v[190:193], v[22:25]
	v_mfma_i32_16x16x64_i8 v[18:21], v[18:21], v[194:197], v[38:41]
	v_mfma_i32_16x16x64_i8 v[22:25], v[154:157], v[194:197], v[34:37]
	v_mfma_i32_16x16x64_i8 v[10:13], v[26:29], v[166:169], v[10:13]
	v_mfma_i32_16x16x64_i8 v[14:17], v[158:161], v[166:169], v[14:17]
	v_mfma_i32_16x16x64_i8 v[18:21], v[26:29], v[198:201], v[18:21]
	v_mfma_i32_16x16x64_i8 v[26:29], v[158:161], v[198:201], v[22:25]
	s_barrier
	s_nop 1
	ds_read_b128 v[22:25], v234
	ds_read_b128 v[30:33], v234 offset:1024
	ds_read_b128 v[34:37], v234 offset:2048
	ds_read_b128 v[38:41], v234 offset:3072
	ds_read_b128 v[154:157], v235
	ds_read_b128 v[158:161], v235 offset:1024
	ds_read_b128 v[162:165], v235 offset:2048
	ds_read_b128 v[166:169], v235 offset:3072
	ds_read_b128 v[70:73], v233 offset:32768
	ds_read_b128 v[78:81], v233 offset:33792
	ds_read_b128 v[178:181], v233 offset:34816
	ds_read_b128 v[182:185], v233 offset:35840
	ds_read_b128 v[186:189], v233 offset:36864
	ds_read_b128 v[190:193], v233 offset:37888
	ds_read_b128 v[194:197], v233 offset:38912
	ds_read_b128 v[198:201], v233 offset:39936
	s_add_u32 s82, s82, 0x84000
	s_addc_u32 s83, s83, 0
	s_mov_b32 m0, s31
	s_nop 0
	global_load_lds_dwordx4 v208, s[82:83]
	s_mov_b32 m0, s33
	s_nop 0
	global_load_lds_dwordx4 v210, s[82:83]
	s_waitcnt vmcnt(8) lgkmcnt(0)
	s_barrier
; #define PG8_STAGE(bufoff, gbase, voff) do { if constexpr (VAR != 1 && VAR != 3) { _Pragma("unroll") for (int _i = 0; _i < 2; ++_i) \
;         asm volatile("s_mov_b32 m0, %2\n\ts_nop 0\n\tglobal_load_lds_dwordx4 %0, %1" :: "v"((voff)[_i]), "s"((const char*)(gbase)), "s"(ldsbase + (unsigned)((bufoff) + _i * 8192)) : "memory", "m0"); } } while (0)
; #define PG8_LDA(dst, b, h) do { if constexpr (VAR < 2) _Pragma("unroll") for (int m = 0; m < 4; ++m) _Pragma("unroll") for (int k = 0; k < 2; ++k) dst[m][k] = *(const LAS bf16x8*)(lds + PG8_SA(b, h) + aoff + m * 2048 + k * 1024); } while (0)
; #define PG8_WAIT_V(n) asm volatile("s_waitcnt vmcnt(" #n ")" ::: "memory")
; #define PG8_WAIT_L(n) asm volatile("s_waitcnt lgkmcnt(" #n ")" ::: "memory")
; #define PG8_BAR do { if constexpr (VAR != 3) __builtin_amdgcn_s_barrier(); } while (0)
; #define PG8_SCHED __builtin_amdgcn_sched_barrier(0)
;     ...
;             PG8_WAIT_V(8); PG8_WAIT_L(0); PG8_BAR; PG8_MMA(0, 0, At, B0); PG8_MMA(0, 1, At, B1); PG8_BAR; PG8_SCHED;
;             PG8_LDA(At, 1, 1); PG8_STAGE(PG8_SB(1, 0), b3, voffB); PG8_STAGE(PG8_SB(1, 1), b3 + hstepB, voffB); PG8_STAGE(PG8_SA(1, 0), a3, voffA);
;             PG8_WAIT_V(8); PG8_WAIT_L(0); PG8_BAR; PG8_MMA(1, 0, At, B0); PG8_MMA(1, 1, At, B1); PG8_BAR; PG8_SCHED;
	v_mfma_i32_16x16x64_i8 v[150:153], v[22:25], v[70:73], v[150:153]
	v_mfma_i32_16x16x64_i8 v[142:145], v[34:37], v[70:73], v[142:145]
	v_mfma_i32_16x16x64_i8 v[126:129], v[22:25], v[178:181], v[126:129]
	v_mfma_i32_16x16x64_i8 v[122:125], v[34:37], v[178:181], v[122:125]
	v_mfma_i32_16x16x64_i8 v[114:117], v[22:25], v[186:189], v[114:117]
	v_mfma_i32_16x16x64_i8 v[106:109], v[34:37], v[186:189], v[106:109]
	v_mfma_i32_16x16x64_i8 v[146:149], v[22:25], v[194:197], v[146:149]
	v_mfma_i32_16x16x64_i8 v[138:141], v[34:37], v[194:197], v[138:141]
	v_mfma_i32_16x16x64_i8 v[150:153], v[30:33], v[78:81], v[150:153]
	v_mfma_i32_16x16x64_i8 v[142:145], v[38:41], v[78:81], v[142:145]
	v_mfma_i32_16x16x64_i8 v[126:129], v[30:33], v[182:185], v[126:129]
	v_mfma_i32_16x16x64_i8 v[122:125], v[38:41], v[182:185], v[122:125]
	v_mfma_i32_16x16x64_i8 v[114:117], v[30:33], v[190:193], v[114:117]
	v_mfma_i32_16x16x64_i8 v[106:109], v[38:41], v[190:193], v[106:109]
	v_mfma_i32_16x16x64_i8 v[146:149], v[30:33], v[198:201], v[146:149]
	v_mfma_i32_16x16x64_i8 v[138:141], v[38:41], v[198:201], v[138:141]
	v_mfma_i32_16x16x64_i8 v[134:137], v[154:157], v[70:73], v[134:137]
	v_mfma_i32_16x16x64_i8 v[70:73], v[162:165], v[70:73], v[130:133]
	v_mfma_i32_16x16x64_i8 v[130:133], v[166:169], v[78:81], v[70:73]
	v_mfma_i32_16x16x64_i8 v[70:73], v[154:157], v[178:181], v[118:121]
	v_mfma_i32_16x16x64_i8 v[118:121], v[158:161], v[182:185], v[70:73]
	v_mfma_i32_16x16x64_i8 v[70:73], v[162:165], v[178:181], v[110:113]
	v_mfma_i32_16x16x64_i8 v[110:113], v[166:169], v[182:185], v[70:73]
	v_mfma_i32_16x16x64_i8 v[70:73], v[154:157], v[186:189], v[102:105]
	v_mfma_i32_16x16x64_i8 v[102:105], v[158:161], v[190:193], v[70:73]
	v_mfma_i32_16x16x64_i8 v[70:73], v[162:165], v[186:189], v[98:101]
	v_mfma_i32_16x16x64_i8 v[98:101], v[166:169], v[190:193], v[70:73]
	v_mfma_i32_16x16x64_i8 v[70:73], v[154:157], v[194:197], v[94:97]
	v_mfma_i32_16x16x64_i8 v[94:97], v[158:161], v[198:201], v[70:73]
	v_mfma_i32_16x16x64_i8 v[70:73], v[162:165], v[194:197], v[90:93]
	v_mfma_i32_16x16x64_i8 v[134:137], v[158:161], v[78:81], v[134:137]
	v_mfma_i32_16x16x64_i8 v[90:93], v[166:169], v[198:201], v[70:73]
	s_barrier
	s_nop 3
	ds_read_b128 v[70:73], v233 offset:49152
	ds_read_b128 v[178:181], v233 offset:50176
	ds_read_b128 v[182:185], v233 offset:51200
	ds_read_b128 v[186:189], v233 offset:52224
	ds_read_b128 v[190:193], v233 offset:53248
	ds_read_b128 v[194:197], v233 offset:54272
	ds_read_b128 v[198:201], v233 offset:55296
	ds_read_b128 v[202:205], v233 offset:56320
	s_add_u32 s82, s80, 0x80
	s_addc_u32 s83, s81, 0
	s_mov_b32 m0, s84
	s_nop 0
	global_load_lds_dwordx4 v209, s[82:83]
	s_add_u32 s80, s80, 0x84080
	s_mov_b32 m0, s85
	s_nop 0
	global_load_lds_dwordx4 v211, s[82:83]
	s_addc_u32 s81, s81, 0
	s_mov_b32 m0, s88
	s_nop 0
	global_load_lds_dwordx4 v209, s[80:81]
	s_mov_b32 m0, s89
	s_nop 0
	global_load_lds_dwordx4 v211, s[80:81]
	s_mov_b32 m0, s86
	s_nop 0
	global_load_lds_dwordx4 v208, s[78:79]
	s_mov_b32 m0, s87
	s_nop 0
	global_load_lds_dwordx4 v210, s[78:79]
	s_waitcnt vmcnt(8) lgkmcnt(0)
	s_barrier
	v_mfma_i32_16x16x64_i8 v[78:81], v[22:25], v[70:73], v[86:89]
	v_mfma_i32_16x16x64_i8 v[74:77], v[22:25], v[182:185], v[74:77]
	v_mfma_i32_16x16x64_i8 v[58:61], v[22:25], v[190:193], v[58:61]
	v_mfma_i32_16x16x64_i8 v[2:5], v[22:25], v[198:201], v[2:5]
	v_mfma_i32_16x16x64_i8 v[86:89], v[30:33], v[178:181], v[78:81]
	v_mfma_i32_16x16x64_i8 v[78:81], v[34:37], v[70:73], v[82:85]
	v_mfma_i32_16x16x64_i8 v[74:77], v[30:33], v[186:189], v[74:77]
	v_mfma_i32_16x16x64_i8 v[66:69], v[34:37], v[182:185], v[66:69]
	v_mfma_i32_16x16x64_i8 v[58:61], v[30:33], v[194:197], v[58:61]
	v_mfma_i32_16x16x64_i8 v[50:53], v[34:37], v[190:193], v[50:53]
	v_mfma_i32_16x16x64_i8 v[30:33], v[30:33], v[202:205], v[2:5]
	v_mfma_i32_16x16x64_i8 v[2:5], v[34:37], v[198:201], v[6:9]
	v_mfma_i32_16x16x64_i8 v[82:85], v[38:41], v[178:181], v[78:81]
	v_mfma_i32_16x16x64_i8 v[66:69], v[38:41], v[186:189], v[66:69]
	v_mfma_i32_16x16x64_i8 v[50:53], v[38:41], v[194:197], v[50:53]
	v_mfma_i32_16x16x64_i8 v[22:25], v[38:41], v[202:205], v[2:5]
	v_mfma_i32_16x16x64_i8 v[2:5], v[154:157], v[70:73], v[10:13]
	v_mfma_i32_16x16x64_i8 v[78:81], v[158:161], v[178:181], v[2:5]
	v_mfma_i32_16x16x64_i8 v[2:5], v[162:165], v[70:73], v[14:17]
	v_mfma_i32_16x16x64_i8 v[70:73], v[166:169], v[178:181], v[2:5]
	v_mfma_i32_16x16x64_i8 v[2:5], v[154:157], v[182:185], v[62:65]
	v_mfma_i32_16x16x64_i8 v[62:65], v[158:161], v[186:189], v[2:5]
	v_mfma_i32_16x16x64_i8 v[2:5], v[162:165], v[182:185], v[54:57]
	v_mfma_i32_16x16x64_i8 v[54:57], v[166:169], v[186:189], v[2:5]
	v_mfma_i32_16x16x64_i8 v[2:5], v[154:157], v[190:193], v[46:49]
	v_mfma_i32_16x16x64_i8 v[46:49], v[158:161], v[194:197], v[2:5]
	v_mfma_i32_16x16x64_i8 v[2:5], v[162:165], v[190:193], v[42:45]
	v_mfma_i32_16x16x64_i8 v[42:45], v[166:169], v[194:197], v[2:5]
	v_mfma_i32_16x16x64_i8 v[2:5], v[154:157], v[198:201], v[18:21]
	v_mfma_i32_16x16x64_i8 v[38:41], v[158:161], v[202:205], v[2:5]
	v_mfma_i32_16x16x64_i8 v[2:5], v[162:165], v[198:201], v[26:29]
	v_mfma_i32_16x16x64_i8 v[34:37], v[166:169], v[202:205], v[2:5]
	s_barrier
	s_add_i32 s71, s71, 2
	s_add_u32 s25, s25, 0x100
	s_addc_u32 s26, s26, 0
	s_add_u32 s27, s27, 0x100
	s_addc_u32 s69, s69, 0
	s_add_u32 s0, s0, 0x100
	s_addc_u32 s1, s1, 0
	s_cmp_gt_u32 s71, 29
	s_cbranch_scc0 .LBB0_1191
